# v19 with the conservative wait-state placeholders kept (no hazard-model-based nop removal)
# speedup vs baseline: 1.0025x; 1.0025x over previous
.LBB0_529:
	s_or_b64 exec, exec, s[4:5]
	s_and_b32 s1, s51, 0x300
	v_or_b32_sdwa v24, v25, s1 dst_sel:DWORD dst_unused:UNUSED_PAD src0_sel:BYTE_0 src1_sel:DWORD
	v_readlane_b32 s4, v252, 49
	v_lshlrev_b32_e32 v2, 2, v24
	v_mov_b32_e32 v3, v34
	v_readlane_b32 s5, v252, 50
	s_ashr_i32 s1, s0, 31
	s_lshl_b64 s[48:49], s[0:1], 11
	v_lshl_add_u64 v[20:21], s[4:5], 0, v[2:3]
	v_add_co_u32_e32 v6, vcc, 0x1000, v20
	s_nop 0
	global_load_dword v4, v2, s[4:5]
	v_addc_co_u32_e32 v7, vcc, 0, v21, vcc
	v_add_co_u32_e32 v8, vcc, 0x2000, v20
	global_load_dword v6, v[6:7], off
	s_nop 0
	v_addc_co_u32_e32 v9, vcc, 0, v21, vcc
	v_add_co_u32_e32 v10, vcc, 0x3000, v20
	global_load_dword v8, v[8:9], off
	s_nop 0
	v_addc_co_u32_e32 v11, vcc, 0, v21, vcc
	v_add_co_u32_e32 v12, vcc, 0x4000, v20
	global_load_dword v10, v[10:11], off
	s_nop 0
	v_addc_co_u32_e32 v13, vcc, 0, v21, vcc
	global_load_dword v5, v[12:13], off
	v_add_co_u32_e32 v12, vcc, 0x5000, v20
	v_readlane_b32 s4, v252, 51
	s_nop 0
	v_addc_co_u32_e32 v13, vcc, 0, v21, vcc
	global_load_dword v7, v[12:13], off
	v_add_co_u32_e32 v12, vcc, 0x6000, v20
	v_readlane_b32 s0, v252, 35
	s_nop 0
	v_addc_co_u32_e32 v13, vcc, 0, v21, vcc
	global_load_dword v9, v[12:13], off
	v_add_co_u32_e32 v12, vcc, 0x7000, v20
	v_readlane_b32 s5, v252, 52
	s_nop 0
	v_addc_co_u32_e32 v13, vcc, 0, v21, vcc
	global_load_dword v11, v[12:13], off
	v_add_co_u32_e32 v12, vcc, 0x8000, v20
	s_add_u32 s0, s0, s48
	s_nop 0
	v_addc_co_u32_e32 v13, vcc, 0, v21, vcc
	v_add_co_u32_e32 v14, vcc, 0x9000, v20
	global_load_dword v12, v[12:13], off
	s_nop 0
	v_addc_co_u32_e32 v15, vcc, 0, v21, vcc
	v_add_co_u32_e32 v16, vcc, 0xa000, v20
	global_load_dword v14, v[14:15], off
	s_nop 0
	v_addc_co_u32_e32 v17, vcc, 0, v21, vcc
	v_add_co_u32_e32 v18, vcc, 0xb000, v20
	global_load_dword v16, v[16:17], off
	s_nop 0
	v_addc_co_u32_e32 v19, vcc, 0, v21, vcc
	v_add_co_u32_e32 v22, vcc, 0xc000, v20
	global_load_dword v18, v[18:19], off
	s_nop 0
	v_addc_co_u32_e32 v23, vcc, 0, v21, vcc
	global_load_dword v13, v[22:23], off
	v_add_co_u32_e32 v22, vcc, 0xd000, v20
	v_readlane_b32 s1, v252, 36
	s_nop 0
	v_addc_co_u32_e32 v23, vcc, 0, v21, vcc
	global_load_dword v15, v[22:23], off
	v_add_co_u32_e32 v22, vcc, 0xe000, v20
	global_load_dword v26, v2, s[4:5]
	s_nop 0
	v_addc_co_u32_e32 v23, vcc, 0, v21, vcc
	v_add_co_u32_e32 v20, vcc, 0xf000, v20
	s_addc_u32 s1, s1, s49
	s_nop 0
	v_addc_co_u32_e32 v21, vcc, 0, v21, vcc
	v_lshlrev_b32_e32 v2, 1, v24
	global_load_dword v17, v[22:23], off
	global_load_dword v19, v[20:21], off
	v_lshl_add_u64 v[20:21], s[0:1], 0, v[2:3]
	v_readlane_b32 s0, v252, 39
	s_add_u32 s0, s0, s48
	v_readlane_b32 s1, v252, 41
	s_addc_u32 s1, s1, s49
	s_nop 0
	v_lshl_add_u64 v[22:23], s[0:1], 0, v[2:3]
	s_ashr_i32 s0, s55, 3
	s_and_b32 s38, s0, 0xffffffe0
	s_cmp_lt_i32 s38, s73
	s_cselect_b64 s[2:3], -1, 0
	v_writelane_b32 v255, s2, 45
	s_and_b64 s[4:5], s[2:3], exec
	s_cselect_b32 s4, s38, 0
	s_ashr_i32 s5, s4, 31
	v_writelane_b32 v255, s3, 46
	s_lshl_b64 s[2:3], s[4:5], 11
	s_or_b32 s72, s38, 1
	v_writelane_b32 v255, s2, 49
	s_cmp_lt_i32 s72, s73
	s_nop 0
	v_writelane_b32 v255, s3, 50
	s_cselect_b64 s[2:3], -1, 0
	v_writelane_b32 v255, s2, 3
	s_and_b64 s[4:5], s[2:3], exec
	s_cselect_b32 s4, s72, 0
	s_ashr_i32 s5, s4, 31
	v_writelane_b32 v255, s3, 4
	s_lshl_b64 s[2:3], s[4:5], 11
	s_or_b32 s40, s38, 2
	v_writelane_b32 v252, s2, 55
	s_cmp_lt_i32 s40, s73
	s_mov_b32 s58, s40
	v_writelane_b32 v252, s3, 56
	s_cselect_b64 s[2:3], -1, 0
	v_writelane_b32 v254, s2, 21
	s_and_b64 s[4:5], s[2:3], exec
	s_cselect_b32 s4, s40, 0
	s_ashr_i32 s5, s4, 31
	v_writelane_b32 v254, s3, 22
	s_lshl_b64 s[2:3], s[4:5], 11
	s_or_b32 s18, s38, 3
	s_cmp_lt_i32 s18, s73
	s_cselect_b64 s[14:15], -1, 0
	s_and_b64 s[4:5], s[14:15], exec
	s_cselect_b32 s4, s18, 0
	v_writelane_b32 v252, s2, 53
	s_ashr_i32 s5, s4, 31
	s_or_b32 s52, s38, 4
	v_writelane_b32 v252, s3, 54
	s_lshl_b64 s[2:3], s[4:5], 11
	v_writelane_b32 v252, s2, 57
	s_cmp_lt_i32 s52, s73
	s_nop 0
	v_writelane_b32 v252, s3, 58
	s_cselect_b64 s[2:3], -1, 0
	v_writelane_b32 v254, s2, 15
	s_and_b64 s[4:5], s[2:3], exec
	s_cselect_b32 s4, s52, 0
	s_ashr_i32 s5, s4, 31
	v_writelane_b32 v254, s3, 16
	s_lshl_b64 s[2:3], s[4:5], 11
	s_or_b32 s56, s38, 5
	s_cmp_lt_i32 s56, s73
	s_cselect_b64 s[10:11], -1, 0
	s_and_b64 s[4:5], s[10:11], exec
	s_cselect_b32 s4, s56, 0
	v_writelane_b32 v252, s2, 59
	s_ashr_i32 s5, s4, 31
	s_or_b32 s20, s38, 6
	v_writelane_b32 v252, s3, 60
	s_lshl_b64 s[2:3], s[4:5], 11
	s_cmp_lt_i32 s20, s73
	s_cselect_b64 s[12:13], -1, 0
	s_and_b64 s[4:5], s[12:13], exec
	s_cselect_b32 s4, s20, 0
	v_writelane_b32 v252, s2, 61
	s_ashr_i32 s5, s4, 31
	s_or_b32 s60, s38, 7
	v_writelane_b32 v252, s3, 62
	s_lshl_b64 s[2:3], s[4:5], 11
	s_cmp_lt_i32 s60, s73
	s_cselect_b64 s[22:23], -1, 0
	s_and_b64 s[4:5], s[22:23], exec
	s_cselect_b32 s4, s60, 0
	v_writelane_b32 v252, s2, 63
	s_ashr_i32 s5, s4, 31
	s_or_b32 s62, s38, 8
	v_writelane_b32 v255, s3, 0
	s_lshl_b64 s[2:3], s[4:5], 11
	v_writelane_b32 v255, s2, 5
	s_cmp_lt_i32 s62, s73
	v_writelane_b32 v252, s58, 33
	v_writelane_b32 v255, s3, 6
	s_cselect_b64 s[2:3], -1, 0
	v_writelane_b32 v255, s2, 23
	s_and_b64 s[4:5], s[2:3], exec
	s_cselect_b32 s4, s62, 0
	s_ashr_i32 s5, s4, 31
	v_writelane_b32 v255, s3, 24
	s_lshl_b64 s[2:3], s[4:5], 11
	s_or_b32 s64, s38, 9
	v_writelane_b32 v255, s2, 7
	s_cmp_lt_i32 s64, s73
	v_writelane_b32 v252, s59, 34
	v_writelane_b32 v255, s3, 8
	s_cselect_b64 s[2:3], -1, 0
	v_writelane_b32 v255, s2, 17
	s_and_b64 s[4:5], s[2:3], exec
	s_cselect_b32 s4, s64, 0
	s_ashr_i32 s5, s4, 31
	v_writelane_b32 v255, s3, 18
	s_lshl_b64 s[2:3], s[4:5], 11
	s_or_b32 s66, s38, 10
	v_writelane_b32 v255, s2, 11
	s_cmp_lt_i32 s66, s73
	s_mov_b32 s58, s18
	v_writelane_b32 v255, s3, 12
	s_cselect_b64 s[2:3], -1, 0
	v_writelane_b32 v255, s2, 27
	s_and_b64 s[4:5], s[2:3], exec
	s_cselect_b32 s4, s66, 0
	s_ashr_i32 s5, s4, 31
	v_writelane_b32 v255, s3, 28
	s_lshl_b64 s[2:3], s[4:5], 11
	s_or_b32 s68, s38, 11
	v_writelane_b32 v255, s2, 15
	s_cmp_lt_i32 s68, s73
	v_writelane_b32 v252, s58, 31
	v_writelane_b32 v255, s3, 16
	s_cselect_b64 s[2:3], -1, 0
	v_writelane_b32 v253, s2, 32
	s_and_b64 s[4:5], s[2:3], exec
	s_cselect_b32 s4, s68, 0
	s_ashr_i32 s5, s4, 31
	v_writelane_b32 v253, s3, 33
	s_lshl_b64 s[2:3], s[4:5], 11
	s_or_b32 s70, s38, 12
	s_cmp_lt_i32 s70, s73
	s_cselect_b64 s[28:29], -1, 0
	s_and_b64 s[4:5], s[28:29], exec
	s_cselect_b32 s4, s70, 0
	v_writelane_b32 v255, s2, 19
	s_ashr_i32 s5, s4, 31
	s_or_b32 s24, s38, 13
	v_writelane_b32 v255, s3, 20
	s_lshl_b64 s[2:3], s[4:5], 11
	v_writelane_b32 v255, s2, 21
	s_cmp_lt_i32 s24, s73
	v_writelane_b32 v252, s59, 32
	v_writelane_b32 v255, s3, 22
	s_cselect_b64 s[2:3], -1, 0
	v_writelane_b32 v255, s2, 1
	s_and_b64 s[4:5], s[2:3], exec
	s_cselect_b32 s4, s24, 0
	s_ashr_i32 s5, s4, 31
	v_writelane_b32 v255, s3, 2
	s_lshl_b64 s[2:3], s[4:5], 11
	s_or_b32 s44, s38, 14
	s_cmp_lt_i32 s44, s73
	s_cselect_b64 s[26:27], -1, 0
	s_and_b64 s[4:5], s[26:27], exec
	s_cselect_b32 s4, s44, 0
	v_writelane_b32 v255, s2, 25
	s_ashr_i32 s5, s4, 31
	s_or_b32 s74, s38, 15
	v_writelane_b32 v255, s3, 26
	s_lshl_b64 s[2:3], s[4:5], 11
	s_cmp_lt_i32 s74, s73
	s_cselect_b64 s[46:47], -1, 0
	s_and_b64 s[4:5], s[46:47], exec
	s_cselect_b32 s4, s74, 0
	v_writelane_b32 v255, s2, 29
	s_ashr_i32 s5, s4, 31
	s_or_b32 s76, s38, 16
	v_writelane_b32 v255, s3, 30
	s_lshl_b64 s[2:3], s[4:5], 11
	s_cmp_lt_i32 s76, s73
	s_cselect_b64 s[42:43], -1, 0
	s_and_b64 s[4:5], s[42:43], exec
	s_cselect_b32 s4, s76, 0
	v_writelane_b32 v255, s2, 31
	s_ashr_i32 s5, s4, 31
	s_or_b32 s78, s38, 17
	v_writelane_b32 v255, s3, 32
	s_lshl_b64 s[2:3], s[4:5], 11
	v_writelane_b32 v255, s2, 33
	s_cmp_lt_i32 s78, s73
	s_mov_b32 s58, s52
	v_writelane_b32 v255, s3, 34
	s_cselect_b64 s[2:3], -1, 0
	v_writelane_b32 v253, s2, 28
	s_and_b64 s[4:5], s[2:3], exec
	s_cselect_b32 s4, s78, 0
	s_ashr_i32 s5, s4, 31
	v_writelane_b32 v253, s3, 29
	s_lshl_b64 s[2:3], s[4:5], 11
	s_or_b32 s80, s38, 18
	s_cmp_lt_i32 s80, s73
	s_cselect_b64 vcc, -1, 0
	s_and_b64 s[4:5], vcc, exec
	s_cselect_b32 s4, s80, 0
	v_writelane_b32 v255, s2, 35
	s_ashr_i32 s5, s4, 31
	s_or_b32 s82, s38, 19
	v_writelane_b32 v255, s3, 36
	s_lshl_b64 s[2:3], s[4:5], 11
	s_cmp_lt_i32 s82, s73
	s_cselect_b64 s[36:37], -1, 0
	s_and_b64 s[4:5], s[36:37], exec
	s_cselect_b32 s4, s82, 0
	v_writelane_b32 v255, s2, 39
	s_ashr_i32 s5, s4, 31
	s_or_b32 s94, s38, 20
	v_writelane_b32 v255, s3, 40
	s_lshl_b64 s[2:3], s[4:5], 11
	s_cmp_lt_i32 s94, s73
	s_cselect_b64 s[34:35], -1, 0
	s_and_b64 s[4:5], s[34:35], exec
	s_cselect_b32 s4, s94, 0
	v_writelane_b32 v255, s2, 43
	s_ashr_i32 s5, s4, 31
	s_or_b32 s92, s38, 21
	v_writelane_b32 v255, s3, 44
	s_lshl_b64 s[2:3], s[4:5], 11
	s_cmp_lt_i32 s92, s73
	s_cselect_b64 s[30:31], -1, 0
	s_and_b64 s[4:5], s[30:31], exec
	s_cselect_b32 s4, s92, 0
	v_writelane_b32 v255, s2, 47
	s_ashr_i32 s5, s4, 31
	s_or_b32 s90, s38, 22
	v_writelane_b32 v255, s3, 48
	s_lshl_b64 s[2:3], s[4:5], 11
	v_writelane_b32 v255, s2, 51
	s_cmp_lt_i32 s90, s73
	s_nop 0
	v_writelane_b32 v255, s3, 52
	s_cselect_b64 s[2:3], -1, 0
	v_writelane_b32 v255, s2, 53
	s_and_b64 s[4:5], s[2:3], exec
	s_cselect_b32 s4, s90, 0
	s_ashr_i32 s5, s4, 31
	v_writelane_b32 v255, s3, 54
	s_lshl_b64 s[2:3], s[4:5], 11
	s_or_b32 s88, s38, 23
	v_writelane_b32 v255, s2, 55
	s_cmp_lt_i32 s88, s73
	s_nop 0
	v_writelane_b32 v255, s3, 56
	s_cselect_b64 s[2:3], -1, 0
	v_writelane_b32 v254, s2, 5
	s_and_b64 s[4:5], s[2:3], exec
	s_cselect_b32 s4, s88, 0
	s_ashr_i32 s5, s4, 31
	v_writelane_b32 v254, s3, 6
	s_lshl_b64 s[2:3], s[4:5], 11
	s_or_b32 s86, s38, 24
	v_writelane_b32 v255, s2, 59
	s_cmp_lt_i32 s86, s73
	s_nop 0
	v_writelane_b32 v255, s3, 60
	s_cselect_b64 s[2:3], -1, 0
	v_writelane_b32 v255, s2, 41
	s_and_b64 s[4:5], s[2:3], exec
	s_cselect_b32 s4, s86, 0
	s_ashr_i32 s5, s4, 31
	v_writelane_b32 v255, s3, 42
	s_lshl_b64 s[2:3], s[4:5], 11
	s_or_b32 s84, s38, 25
	v_writelane_b32 v254, s2, 9
	s_cmp_lt_i32 s84, s73
	s_nop 0
	v_writelane_b32 v254, s3, 10
	s_cselect_b64 s[2:3], -1, 0
	v_writelane_b32 v255, s2, 57
	s_and_b64 s[4:5], s[2:3], exec
	s_cselect_b32 s4, s84, 0
	s_ashr_i32 s5, s4, 31
	v_writelane_b32 v255, s3, 58
	s_lshl_b64 s[2:3], s[4:5], 11
	s_or_b32 s96, s38, 26
	v_writelane_b32 v255, s2, 63
	s_cmp_lt_i32 s96, s73
	s_nop 0
	v_writelane_b32 v254, s3, 0
	s_cselect_b64 s[2:3], -1, 0
	v_writelane_b32 v255, s2, 37
	s_and_b64 s[4:5], s[2:3], exec
	s_cselect_b32 s4, s96, 0
	s_ashr_i32 s5, s4, 31
	v_writelane_b32 v255, s3, 38
	s_lshl_b64 s[2:3], s[4:5], 11
	s_or_b32 s54, s38, 27
	v_writelane_b32 v254, s2, 1
	s_cmp_lt_i32 s54, s73
	s_nop 0
	v_writelane_b32 v254, s3, 2
	s_cselect_b64 s[2:3], -1, 0
	v_writelane_b32 v255, s2, 61
	s_and_b64 s[4:5], s[2:3], exec
	s_cselect_b32 s4, s54, 0
	s_ashr_i32 s5, s4, 31
	v_writelane_b32 v255, s3, 62
	s_lshl_b64 s[2:3], s[4:5], 11
	s_or_b32 s8, s38, 28
	v_writelane_b32 v254, s2, 3
	s_cmp_lt_i32 s8, s73
	s_nop 0
	v_writelane_b32 v254, s3, 4
	s_cselect_b64 s[2:3], -1, 0
	v_writelane_b32 v253, s2, 30
	s_and_b64 s[4:5], s[2:3], exec
	s_cselect_b32 s4, s8, 0
	s_ashr_i32 s5, s4, 31
	v_writelane_b32 v253, s3, 31
	s_lshl_b64 s[2:3], s[4:5], 11
	s_or_b32 s6, s38, 29
	v_writelane_b32 v254, s2, 7
	s_cmp_lt_i32 s6, s73
	s_nop 0
	v_writelane_b32 v254, s3, 8
	s_cselect_b64 s[2:3], -1, 0
	v_writelane_b32 v254, s2, 13
	s_and_b64 s[4:5], s[2:3], exec
	s_cselect_b32 s4, s6, 0
	s_ashr_i32 s5, s4, 31
	v_writelane_b32 v254, s3, 14
	s_lshl_b64 s[2:3], s[4:5], 11
	s_or_b32 s50, s38, 30
	v_writelane_b32 v254, s2, 11
	s_cmp_lt_i32 s50, s73
	s_nop 0
	v_writelane_b32 v254, s3, 12
	s_cselect_b64 s[2:3], -1, 0
	v_writelane_b32 v254, s2, 17
	s_and_b64 s[4:5], s[2:3], exec
	s_cselect_b32 s4, s50, 0
	v_writelane_b32 v254, s3, 18
	s_ashr_i32 s5, s4, 31
	s_lshl_b64 s[4:5], s[4:5], 11
	s_or_b32 s2, s0, 31
	v_writelane_b32 v254, s58, 25
	s_cmp_lt_i32 s2, s73
	s_cselect_b64 s[0:1], -1, 0
	v_writelane_b32 v254, s59, 26
	s_mov_b32 s58, s56
	v_writelane_b32 v254, s58, 27
	v_writelane_b32 v253, s0, 10
	s_nop 0
	v_writelane_b32 v254, s59, 28
	s_mov_b32 s58, s20
	v_writelane_b32 v253, s1, 11
	s_and_b64 s[0:1], s[0:1], exec
	v_writelane_b32 v254, s58, 31
	s_cselect_b32 s0, s2, 0
	s_lshl_b32 s71, s70, 6
	v_writelane_b32 v254, s59, 32
	s_lshl_b32 s59, s20, 6
	s_add_i32 s59, s59, 0
	s_mov_b32 s58, s60
	v_writelane_b32 v254, s58, 29
	s_add_i32 s9, s71, 0
	s_lshl_b32 s71, s24, 6
	v_writelane_b32 v254, s59, 30
	s_mov_b32 s58, s62
	v_writelane_b32 v254, s58, 33
	v_writelane_b32 v255, s9, 13
	s_add_i32 s9, s71, 0
	v_writelane_b32 v254, s59, 34
	s_mov_b32 s58, s64
	v_writelane_b32 v254, s58, 35
	s_lshl_b32 s71, s44, 6
	v_writelane_b32 v255, s9, 9
	v_writelane_b32 v254, s59, 36
	s_mov_b32 s58, s66
	v_writelane_b32 v254, s58, 37
	s_add_i32 s9, s71, 0
	s_lshl_b32 s71, s74, 6
	v_writelane_b32 v254, s59, 38
	s_mov_b32 s58, s68
	v_writelane_b32 v254, s58, 39
	s_ashr_i32 s1, s0, 31
	s_lshl_b64 s[0:1], s[0:1], 11
	v_writelane_b32 v254, s59, 40
	s_mov_b32 s58, s70
	v_writelane_b32 v254, s58, 41
	s_lshl_b32 s17, s38, 6
	s_add_i32 s7, s17, 0
	v_writelane_b32 v254, s59, 42
	s_mov_b32 s58, s24
	v_writelane_b32 v254, s58, 43
	s_lshl_b32 s17, s72, 6
	s_add_i32 s79, s17, 0
	v_writelane_b32 v254, s59, 44
	s_mov_b32 s58, s44
	v_writelane_b32 v254, s58, 45
	s_lshl_b32 s17, s40, 6
	s_add_i32 s3, s17, 0
	v_writelane_b32 v254, s59, 46
	v_writelane_b32 v254, s9, 49
	s_mov_b32 s58, s74
	v_writelane_b32 v254, s58, 47
	s_add_i32 s9, s71, 0
	s_lshl_b32 s71, s76, 6
	v_writelane_b32 v254, s59, 48
	v_writelane_b32 v254, s9, 52
	s_mov_b32 s58, s76
	v_writelane_b32 v254, s58, 50
	s_add_i32 s9, s71, 0
	s_lshl_b32 s71, s78, 6
	v_writelane_b32 v254, s59, 51
	v_writelane_b32 v254, s9, 55
	s_mov_b32 s58, s78
	v_writelane_b32 v254, s58, 53
	s_add_i32 s9, s71, 0
	s_lshl_b32 s71, s80, 6
	v_writelane_b32 v254, s59, 54
	v_writelane_b32 v254, s9, 58
	s_mov_b32 s58, s80
	v_writelane_b32 v254, s58, 56
	s_add_i32 s9, s71, 0
	s_lshl_b32 s71, s82, 6
	v_writelane_b32 v254, s59, 57
	v_writelane_b32 v254, s9, 61
	s_mov_b32 s58, s82
	v_writelane_b32 v254, s58, 59
	s_add_i32 s9, s71, 0
	s_lshl_b32 s71, s94, 6
	v_writelane_b32 v254, s59, 60
	s_mov_b32 s58, s94
	v_writelane_b32 v253, s9, 0
	v_writelane_b32 v254, s58, 62
	s_add_i32 s9, s71, 0
	v_writelane_b32 v253, s9, 3
	v_writelane_b32 v254, s59, 63
	s_mov_b32 s58, s92
	v_writelane_b32 v253, s58, 1
	s_lshl_b32 s71, s92, 6
	s_add_i32 s9, s71, 0
	v_writelane_b32 v253, s59, 2
	v_writelane_b32 v253, s9, 6
	s_mov_b32 s58, s90
	v_writelane_b32 v253, s58, 4
	s_lshl_b32 s71, s90, 6
	s_add_i32 s97, s71, 0
	v_writelane_b32 v253, s59, 5
	s_mov_b32 s58, s88
	v_writelane_b32 v253, s58, 8
	s_lshl_b32 s71, s88, 6
	s_add_i32 s95, s71, 0
	v_writelane_b32 v253, s59, 9
	s_mov_b32 s58, s86
	v_writelane_b32 v253, s58, 12
	s_lshl_b32 s71, s86, 6
	s_add_i32 s94, s71, 0
	v_writelane_b32 v253, s59, 13
	s_mov_b32 s58, s84
	v_writelane_b32 v253, s58, 14
	s_lshl_b32 s71, s84, 6
	s_add_i32 s93, s71, 0
	v_writelane_b32 v253, s59, 15
	s_mov_b32 s58, s96
	v_writelane_b32 v253, s58, 16
	s_lshl_b32 s71, s96, 6
	s_add_i32 s92, s71, 0
	v_writelane_b32 v253, s59, 17
	s_mov_b32 s58, s54
	s_lshl_b32 s71, s54, 6
	v_writelane_b32 v253, s58, 18
	s_add_i32 s9, s71, 0
	v_writelane_b32 v254, s9, 19
	v_writelane_b32 v253, s59, 19
	s_mov_b32 s58, s8
	s_lshl_b32 s71, s8, 6
	v_readlane_b32 s8, v255, 49
	v_readlane_b32 s9, v255, 50
	v_readlane_b32 s90, v255, 45
	v_readlane_b32 s91, v255, 46
	v_lshl_add_u64 v[28:29], v[20:21], 0, s[8:9]
	global_load_ushort v86, v[28:29], off
	v_lshl_add_u64 v[28:29], v[22:23], 0, s[8:9]
	v_readlane_b32 s8, v252, 55
	v_readlane_b32 s9, v252, 56
	global_load_ushort v1, v[28:29], off
	v_writelane_b32 v253, s58, 20
	v_lshl_add_u64 v[28:29], v[20:21], 0, s[8:9]
	global_load_ushort v84, v[28:29], off
	v_lshl_add_u64 v[28:29], v[22:23], 0, s[8:9]
	v_readlane_b32 s8, v252, 53
	v_readlane_b32 s9, v252, 54
	s_waitcnt vmcnt(0)
	global_load_ushort v88, v[28:29], off
	v_writelane_b32 v253, s59, 21
	v_lshl_add_u64 v[28:29], v[20:21], 0, s[8:9]
	global_load_ushort v82, v[28:29], off
	v_lshl_add_u64 v[28:29], v[22:23], 0, s[8:9]
	v_readlane_b32 s8, v252, 57
	v_readlane_b32 s9, v252, 58
	global_load_ushort v87, v[28:29], off
	s_add_i32 s96, s71, 0
	v_lshl_add_u64 v[28:29], v[20:21], 0, s[8:9]
	global_load_ushort v80, v[28:29], off
	v_lshl_add_u64 v[28:29], v[22:23], 0, s[8:9]
	v_readlane_b32 s8, v252, 59
	v_readlane_b32 s9, v252, 60
	global_load_ushort v85, v[28:29], off
	s_mov_b32 s58, s6
	v_lshl_add_u64 v[28:29], v[20:21], 0, s[8:9]
	global_load_ushort v79, v[28:29], off
	v_lshl_add_u64 v[28:29], v[22:23], 0, s[8:9]
	v_readlane_b32 s8, v252, 61
	v_readlane_b32 s9, v252, 62
	global_load_ushort v83, v[28:29], off
	s_lshl_b32 s71, s6, 6
	v_lshl_add_u64 v[28:29], v[20:21], 0, s[8:9]
	global_load_ushort v77, v[28:29], off
	v_lshl_add_u64 v[28:29], v[22:23], 0, s[8:9]
	v_readlane_b32 s8, v252, 63
	v_readlane_b32 s9, v255, 0
	global_load_ushort v81, v[28:29], off
	s_mov_b32 s6, 0xbfb8aa3b
	v_lshl_add_u64 v[28:29], v[20:21], 0, s[8:9]
	global_load_ushort v75, v[28:29], off
	v_lshl_add_u64 v[28:29], v[22:23], 0, s[8:9]
	v_readlane_b32 s8, v255, 5
	v_readlane_b32 s9, v255, 6
	global_load_ushort v78, v[28:29], off
	s_lshl_b32 s17, s18, 6
	v_lshl_add_u64 v[28:29], v[20:21], 0, s[8:9]
	global_load_ushort v73, v[28:29], off
	v_lshl_add_u64 v[28:29], v[22:23], 0, s[8:9]
	v_readlane_b32 s8, v255, 7
	v_readlane_b32 s9, v255, 8
	global_load_ushort v76, v[28:29], off
	s_add_i32 s17, s17, 0
	v_lshl_add_u64 v[28:29], v[20:21], 0, s[8:9]
	global_load_ushort v69, v[28:29], off
	v_lshl_add_u64 v[28:29], v[22:23], 0, s[8:9]
	v_readlane_b32 s8, v255, 11
	v_readlane_b32 s9, v255, 12
	global_load_ushort v74, v[28:29], off
	s_lshl_b32 s53, s52, 6
	v_lshl_add_u64 v[28:29], v[20:21], 0, s[8:9]
	global_load_ushort v70, v[28:29], off
	v_lshl_add_u64 v[28:29], v[22:23], 0, s[8:9]
	v_readlane_b32 s8, v255, 15
	v_readlane_b32 s9, v255, 16
	global_load_ushort v72, v[28:29], off
	s_add_i32 s53, s53, 0
	v_lshl_add_u64 v[28:29], v[20:21], 0, s[8:9]
	global_load_ushort v67, v[28:29], off
	v_lshl_add_u64 v[28:29], v[22:23], 0, s[8:9]
	v_readlane_b32 s8, v255, 19
	v_readlane_b32 s9, v255, 20
	global_load_ushort v71, v[28:29], off
	s_lshl_b32 s57, s56, 6
	v_lshl_add_u64 v[28:29], v[20:21], 0, s[8:9]
	global_load_ushort v65, v[28:29], off
	v_lshl_add_u64 v[28:29], v[22:23], 0, s[8:9]
	v_readlane_b32 s8, v255, 21
	v_readlane_b32 s9, v255, 22
	global_load_ushort v68, v[28:29], off
	s_add_i32 s57, s57, 0
	v_lshl_add_u64 v[28:29], v[20:21], 0, s[8:9]
	global_load_ushort v63, v[28:29], off
	v_lshl_add_u64 v[28:29], v[22:23], 0, s[8:9]
	v_readlane_b32 s8, v255, 25
	v_readlane_b32 s9, v255, 26
	global_load_ushort v66, v[28:29], off
	s_waitcnt vmcnt(0) lgkmcnt(0)
	v_lshlrev_b32_e32 v1, 16, v1
	v_lshl_add_u64 v[28:29], v[20:21], 0, s[8:9]
	global_load_ushort v61, v[28:29], off
	v_lshl_add_u64 v[28:29], v[22:23], 0, s[8:9]
	v_readlane_b32 s8, v255, 29
	v_readlane_b32 s9, v255, 30
	global_load_ushort v64, v[28:29], off
	v_cndmask_b32_e64 v89, 0, v1, s[90:91]
	v_lshl_add_u64 v[28:29], v[20:21], 0, s[8:9]
	global_load_ushort v59, v[28:29], off
	v_lshl_add_u64 v[28:29], v[22:23], 0, s[8:9]
	v_readlane_b32 s8, v255, 31
	v_readlane_b32 s9, v255, 32
	global_load_ushort v62, v[28:29], off
	v_mov_b32_e32 v1, s7
	v_lshl_add_u64 v[28:29], v[20:21], 0, s[8:9]
	global_load_ushort v57, v[28:29], off
	v_lshl_add_u64 v[28:29], v[22:23], 0, s[8:9]
	v_readlane_b32 s8, v255, 33
	v_readlane_b32 s9, v255, 34
	global_load_ushort v60, v[28:29], off
	s_mov_b32 s7, 0x800000
	v_lshl_add_u64 v[28:29], v[20:21], 0, s[8:9]
	global_load_ushort v43, v[28:29], off
	v_lshl_add_u64 v[28:29], v[22:23], 0, s[8:9]
	v_readlane_b32 s8, v255, 35
	v_readlane_b32 s9, v255, 36
	global_load_ushort v58, v[28:29], off
	v_writelane_b32 v253, s58, 22
	v_lshl_add_u64 v[28:29], v[20:21], 0, s[8:9]
	global_load_ushort v35, v[28:29], off
	v_lshl_add_u64 v[28:29], v[22:23], 0, s[8:9]
	v_readlane_b32 s8, v255, 39
	v_readlane_b32 s9, v255, 40
	global_load_ushort v50, v[28:29], off
	v_writelane_b32 v253, s59, 23
	v_lshl_add_u64 v[28:29], v[20:21], 0, s[8:9]
	global_load_ushort v36, v[28:29], off
	v_lshl_add_u64 v[28:29], v[22:23], 0, s[8:9]
	v_readlane_b32 s8, v255, 43
	v_readlane_b32 s9, v255, 44
	global_load_ushort v51, v[28:29], off
	s_mov_b32 s58, s50
	v_lshl_add_u64 v[28:29], v[20:21], 0, s[8:9]
	global_load_ushort v37, v[28:29], off
	v_lshl_add_u64 v[28:29], v[22:23], 0, s[8:9]
	v_readlane_b32 s8, v255, 47
	v_readlane_b32 s9, v255, 48
	global_load_ushort v52, v[28:29], off
	v_writelane_b32 v253, s58, 24
	v_lshl_add_u64 v[28:29], v[20:21], 0, s[8:9]
	global_load_ushort v38, v[28:29], off
	v_lshl_add_u64 v[28:29], v[22:23], 0, s[8:9]
	v_readlane_b32 s8, v255, 51
	v_readlane_b32 s9, v255, 52
	global_load_ushort v53, v[28:29], off
	v_writelane_b32 v253, s59, 25
	v_lshl_add_u64 v[28:29], v[20:21], 0, s[8:9]
	global_load_ushort v39, v[28:29], off
	v_lshl_add_u64 v[28:29], v[22:23], 0, s[8:9]
	v_readlane_b32 s8, v255, 55
	v_readlane_b32 s9, v255, 56
	global_load_ushort v54, v[28:29], off
	s_mov_b32 s58, s2
	v_lshl_add_u64 v[28:29], v[20:21], 0, s[8:9]
	global_load_ushort v40, v[28:29], off
	v_lshl_add_u64 v[28:29], v[22:23], 0, s[8:9]
	v_readlane_b32 s8, v255, 59
	v_readlane_b32 s9, v255, 60
	global_load_ushort v55, v[28:29], off
	v_writelane_b32 v253, s58, 26
	v_lshl_add_u64 v[28:29], v[20:21], 0, s[8:9]
	global_load_ushort v41, v[28:29], off
	v_lshl_add_u64 v[28:29], v[22:23], 0, s[8:9]
	v_readlane_b32 s8, v254, 9
	v_readlane_b32 s9, v254, 10
	global_load_ushort v56, v[28:29], off
	s_lshl_b32 s61, s60, 6
	v_lshl_add_u64 v[30:31], v[22:23], 0, s[8:9]
	global_load_ushort v49, v[30:31], off
	v_lshl_add_u64 v[28:29], v[20:21], 0, s[8:9]
	v_readlane_b32 s8, v255, 63
	v_readlane_b32 s9, v254, 0
	global_load_ushort v28, v[28:29], off
	s_add_i32 s61, s61, 0
	v_lshl_add_u64 v[30:31], v[20:21], 0, s[8:9]
	global_load_ushort v29, v[30:31], off
	v_lshl_add_u64 v[30:31], v[22:23], 0, s[8:9]
	v_readlane_b32 s8, v254, 1
	v_readlane_b32 s9, v254, 2
	global_load_ushort v44, v[30:31], off
	s_lshl_b32 s63, s62, 6
	v_lshl_add_u64 v[32:33], v[22:23], 0, s[8:9]
	global_load_ushort v45, v[32:33], off
	v_lshl_add_u64 v[30:31], v[20:21], 0, s[8:9]
	v_readlane_b32 s8, v254, 3
	v_readlane_b32 s9, v254, 4
	global_load_ushort v30, v[30:31], off
	s_add_i32 s63, s63, 0
	v_lshl_add_u64 v[32:33], v[20:21], 0, s[8:9]
	global_load_ushort v31, v[32:33], off
	v_lshl_add_u64 v[32:33], v[22:23], 0, s[8:9]
	v_readlane_b32 s8, v254, 7
	v_readlane_b32 s9, v254, 8
	global_load_ushort v46, v[32:33], off
	s_lshl_b32 s65, s64, 6
	v_lshl_add_u64 v[90:91], v[22:23], 0, s[8:9]
	global_load_ushort v47, v[90:91], off
	v_lshl_add_u64 v[32:33], v[20:21], 0, s[8:9]
	v_readlane_b32 s8, v254, 11
	v_readlane_b32 s9, v254, 12
	global_load_ushort v32, v[32:33], off
	s_add_i32 s65, s65, 0
	v_lshl_add_u64 v[90:91], v[20:21], 0, s[8:9]
	global_load_ushort v33, v[90:91], off
	v_lshl_add_u64 v[90:91], v[22:23], 0, s[8:9]
	global_load_ushort v48, v[90:91], off
	v_lshl_add_u64 v[90:91], v[20:21], 0, s[4:5]
	v_lshl_add_u64 v[20:21], v[20:21], 0, s[0:1]
	global_load_ushort v27, v[90:91], off
	s_mov_b32 s8, 0x3f317217
	global_load_ushort v20, v[20:21], off
	v_lshl_add_u64 v[90:91], v[22:23], 0, s[4:5]
	v_lshl_add_u64 v[22:23], v[22:23], 0, s[0:1]
	global_load_ushort v42, v[90:91], off
	global_load_ushort v21, v[22:23], off
	s_waitcnt lgkmcnt(0)
	s_barrier
	ds_read_b128 v[184:187], v1 offset:4096
	ds_read_b128 v[188:191], v1 offset:4112
	ds_read_b128 v[192:195], v1 offset:4128
	ds_read_b128 v[196:199], v1 offset:4144
	s_nop 0
	s_mov_b32 s9, 0x7f800000
	s_lshl_b32 s67, s66, 6
	s_add_i32 s67, s67, 0
	s_lshl_b32 s69, s68, 6
	s_waitcnt lgkmcnt(4)
	s_waitcnt lgkmcnt(3)
	v_mul_f32_e32 v22, v6, v185
	v_fmac_f32_e32 v22, v4, v184
	v_fmac_f32_e32 v22, v8, v186
	v_fmac_f32_e32 v22, v10, v187
	s_nop 0
	v_add_f32_e32 v22, v26, v22
	s_add_i32 s69, s69, 0
	v_writelane_b32 v253, s59, 27
	s_add_i32 s68, s71, 0
	s_waitcnt lgkmcnt(2)
	v_mul_f32_e32 v23, v7, v189
	v_fmac_f32_e32 v23, v5, v188
	v_fmac_f32_e32 v23, v9, v190
	v_fmac_f32_e32 v23, v11, v191
	s_nop 0
	v_add_f32_e32 v22, v22, v23
	s_lshl_b32 s71, s50, 6
	s_add_i32 s66, s71, 0
	s_lshl_b32 s71, s2, 6
	s_waitcnt lgkmcnt(1)
	v_mul_f32_e32 v23, v14, v193
	v_fmac_f32_e32 v23, v12, v192
	v_fmac_f32_e32 v23, v16, v194
	v_fmac_f32_e32 v23, v18, v195
	s_nop 0
	v_add_f32_e32 v22, v22, v23
	s_add_i32 s60, s71, 0
	v_readlane_b32 s82, v255, 3
	v_readlane_b32 s83, v255, 4
	s_waitcnt lgkmcnt(0)
	v_mul_f32_e32 v1, v15, v197
	v_fmac_f32_e32 v1, v13, v196
	v_fmac_f32_e32 v1, v17, v198
	v_fmac_f32_e32 v1, v19, v199
	v_add_f32_e32 v1, v22, v1
	v_max_f32_e64 v22, -v1, 0
	v_mul_f32_e64 v1, |v1|, s6
	v_exp_f32_e32 v1, v1
	s_mov_b64 s[80:81], s[14:15]
	s_mov_b64 s[76:77], s[10:11]
	s_and_b32 s71, s55, 0x3fffff00
	v_add_f32_e32 v1, 1.0, v1
	v_cmp_gt_f32_e64 s[0:1], s7, v1
	s_mov_b64 s[74:75], s[12:13]
	s_lshl_b32 s71, s71, 2
	v_cndmask_b32_e64 v23, 0, 32, s[0:1]
	v_ldexp_f32 v1, v1, v23
	v_log_f32_e32 v1, v1
	s_add_i32 s50, s71, 0
	s_mov_b64 s[70:71], s[22:23]
	s_cmpk_lt_u32 s55, 0x100
	v_mul_f32_e32 v23, 0x3f317217, v1
	v_fma_f32 v23, v1, s8, -v23
	v_fmac_f32_e32 v23, 0x3377d1cf, v1
	v_fmac_f32_e32 v23, 0x3f317217, v1
	v_cmp_lt_f32_e64 s[4:5], |v1|, s9
	v_readlane_b32 s55, v252, 43
	s_cselect_b64 s[88:89], -1, 0
	v_cndmask_b32_e64 v1, v1, v23, s[4:5]
	v_cndmask_b32_e64 v23, 0, v226, s[0:1]
	v_sub_f32_e32 v1, v1, v23
	v_mov_b32_e32 v23, s79
	ds_read_b128 v[184:187], v23 offset:4096
	ds_read_b128 v[188:191], v23 offset:4112
	ds_read_b128 v[192:195], v23 offset:4128
	ds_read_b128 v[196:199], v23 offset:4144
	s_nop 0
	v_add_f32_e32 v1, v22, v1
	v_mul_f32_e32 v1, 0xbd800000, v1
	v_cndmask_b32_e64 v22, 0, v1, s[90:91]
	v_add_f32_e32 v1, 0, v22
	s_waitcnt lgkmcnt(3)
	v_mul_f32_e32 v91, v6, v185
	v_fmac_f32_e32 v91, v4, v184
	v_fmac_f32_e32 v91, v8, v186
	v_fmac_f32_e32 v91, v10, v187
	v_add_f32_e32 v94, v26, v91
	s_nop 0
	v_readlane_b32 s78, v254, 15
	v_readlane_b32 s79, v254, 16
	s_add_u32 s84, s55, s48
	v_readlane_b32 s55, v252, 44
	s_waitcnt lgkmcnt(2)
	v_mul_f32_e32 v91, v7, v189
	v_fmac_f32_e32 v91, v5, v188
	v_fmac_f32_e32 v91, v9, v190
	v_fmac_f32_e32 v91, v11, v191
	v_add_f32_e32 v94, v94, v91
	s_nop 0
	s_addc_u32 s85, s55, s49
	v_readlane_b32 s55, v252, 45
	s_add_u32 s86, s55, s48
	s_mov_b64 s[54:55], s[28:29]
	s_waitcnt lgkmcnt(1)
	v_mul_f32_e32 v91, v14, v193
	v_fmac_f32_e32 v91, v12, v192
	v_fmac_f32_e32 v91, v16, v194
	v_fmac_f32_e32 v91, v18, v195
	v_add_f32_e32 v94, v94, v91
	s_nop 0
	v_readlane_b32 s48, v252, 46
	s_addc_u32 s87, s48, s49
	s_mov_b64 s[48:49], s[26:27]
	v_readlane_b32 s14, v253, 28
	s_waitcnt lgkmcnt(0)
	v_mul_f32_e32 v23, v15, v197
	v_fmac_f32_e32 v23, v13, v196
	v_fmac_f32_e32 v23, v17, v198
	v_fmac_f32_e32 v23, v19, v199
	v_add_f32_e32 v23, v94, v23
	v_max_f32_e64 v90, -v23, 0
	v_mul_f32_e64 v23, |v23|, s6
	v_exp_f32_e32 v23, v23
	v_mov_b32_e32 v94, s3
	ds_read_b128 v[184:187], v94 offset:4096
	ds_read_b128 v[188:191], v94 offset:4112
	ds_read_b128 v[192:195], v94 offset:4128
	ds_read_b128 v[196:199], v94 offset:4144
	v_readlane_b32 s2, v254, 21
	v_readlane_b32 s3, v254, 22
	v_add_f32_e32 v23, 1.0, v23
	v_cmp_gt_f32_e64 s[0:1], s7, v23
	v_readlane_b32 s15, v253, 29
	s_mov_b64 s[40:41], vcc
	v_cndmask_b32_e64 v91, 0, 32, s[0:1]
	v_ldexp_f32 v23, v23, v91
	v_log_f32_e32 v23, v23
	v_readlane_b32 s24, v255, 53
	v_readlane_b32 s25, v255, 54
	v_readlane_b32 s44, v254, 5
	v_mul_f32_e32 v91, 0x3f317217, v23
	v_fma_f32 v91, v23, s8, -v91
	v_fmac_f32_e32 v91, 0x3377d1cf, v23
	v_fmac_f32_e32 v91, 0x3f317217, v23
	v_cmp_lt_f32_e64 s[4:5], |v23|, s9
	v_readlane_b32 s45, v254, 6
	v_readlane_b32 s26, v255, 41
	v_cndmask_b32_e64 v23, v23, v91, s[4:5]
	v_cndmask_b32_e64 v91, 0, v226, s[0:1]
	v_sub_f32_e32 v23, v23, v91
	v_add_f32_e32 v23, v90, v23
	s_nop 0
	v_mul_f32_e32 v23, 0xbd800000, v23
	v_cndmask_b32_e64 v23, 0, v23, s[82:83]
	v_add_f32_e32 v1, v1, v23
	v_readlane_b32 s27, v255, 42
	s_waitcnt lgkmcnt(3)
	v_mul_f32_e32 v91, v6, v185
	v_fmac_f32_e32 v91, v4, v184
	v_fmac_f32_e32 v91, v8, v186
	v_fmac_f32_e32 v91, v10, v187
	v_add_f32_e32 v95, v26, v91
	s_nop 0
	v_readlane_b32 s28, v255, 57
	v_readlane_b32 s29, v255, 58
	v_readlane_b32 s22, v255, 37
	v_readlane_b32 s23, v255, 38
	s_waitcnt lgkmcnt(2)
	v_mul_f32_e32 v91, v7, v189
	v_fmac_f32_e32 v91, v5, v188
	v_fmac_f32_e32 v91, v9, v190
	v_fmac_f32_e32 v91, v11, v191
	v_add_f32_e32 v95, v95, v91
	s_nop 0
	v_readlane_b32 s10, v255, 61
	v_readlane_b32 s11, v255, 62
	v_readlane_b32 s18, v253, 30
	v_readlane_b32 s19, v253, 31
	s_waitcnt lgkmcnt(1)
	v_mul_f32_e32 v91, v14, v193
	v_fmac_f32_e32 v91, v12, v192
	v_fmac_f32_e32 v91, v16, v194
	v_fmac_f32_e32 v91, v18, v195
	v_add_f32_e32 v95, v95, v91
	s_nop 0
	v_readlane_b32 s20, v254, 13
	v_readlane_b32 s21, v254, 14
	v_readlane_b32 s12, v254, 17
	v_readlane_b32 s13, v254, 18
	s_waitcnt lgkmcnt(0)
	v_mul_f32_e32 v91, v15, v197
	v_fmac_f32_e32 v91, v13, v196
	v_fmac_f32_e32 v91, v17, v198
	v_fmac_f32_e32 v91, v19, v199
	v_add_f32_e32 v90, v95, v91
	v_max_f32_e64 v91, -v90, 0
	v_mul_f32_e64 v90, |v90|, s6
	v_exp_f32_e32 v90, v90
	s_ashr_i32 s39, s38, 31
	s_cmp_ge_i32 s38, s73
	v_add_f32_e32 v90, 1.0, v90
	v_cmp_gt_f32_e64 s[0:1], s7, v90
	s_nop 1
	v_cndmask_b32_e64 v92, 0, 32, s[0:1]
	v_ldexp_f32 v90, v90, v92
	v_log_f32_e32 v90, v90
	s_nop 0
	v_mul_f32_e32 v92, 0x3f317217, v90
	v_fma_f32 v92, v90, s8, -v92
	v_fmac_f32_e32 v92, 0x3377d1cf, v90
	v_fmac_f32_e32 v92, 0x3f317217, v90
	v_cmp_lt_f32_e64 s[4:5], |v90|, s9
	s_nop 1
	v_cndmask_b32_e64 v90, v90, v92, s[4:5]
	v_cndmask_b32_e64 v92, 0, v226, s[0:1]
	v_sub_f32_e32 v90, v90, v92
	v_add_f32_e32 v90, v91, v90
	v_mov_b32_e32 v91, s17
	ds_read_b128 v[184:187], v91 offset:4096
	ds_read_b128 v[188:191], v91 offset:4112
	ds_read_b128 v[192:195], v91 offset:4128
	ds_read_b128 v[196:199], v91 offset:4144
	s_nop 0
	v_mul_f32_e32 v90, 0xbd800000, v90
	v_cndmask_b32_e64 v90, 0, v90, s[2:3]
	v_add_f32_e32 v1, v1, v90
	s_waitcnt lgkmcnt(3)
	v_mul_f32_e32 v93, v6, v185
	v_fmac_f32_e32 v93, v4, v184
	v_fmac_f32_e32 v93, v8, v186
	v_fmac_f32_e32 v93, v10, v187
	v_add_f32_e32 v96, v26, v93
	s_nop 0
	s_waitcnt lgkmcnt(2)
	v_mul_f32_e32 v93, v7, v189
	v_fmac_f32_e32 v93, v5, v188
	v_fmac_f32_e32 v93, v9, v190
	v_fmac_f32_e32 v93, v11, v191
	v_add_f32_e32 v96, v96, v93
	s_nop 0
	s_waitcnt lgkmcnt(1)
	v_mul_f32_e32 v93, v14, v193
	v_fmac_f32_e32 v93, v12, v192
	v_fmac_f32_e32 v93, v16, v194
	v_fmac_f32_e32 v93, v18, v195
	v_add_f32_e32 v96, v96, v93
	s_nop 0
	s_waitcnt lgkmcnt(0)
	v_mul_f32_e32 v91, v15, v197
	v_fmac_f32_e32 v91, v13, v196
	v_fmac_f32_e32 v91, v17, v198
	v_fmac_f32_e32 v91, v19, v199
	v_add_f32_e32 v91, v96, v91
	v_max_f32_e64 v92, -v91, 0
	v_mul_f32_e64 v91, |v91|, s6
	v_exp_f32_e32 v91, v91
	v_mov_b32_e32 v96, s53
	ds_read_b128 v[184:187], v96 offset:4096
	ds_read_b128 v[188:191], v96 offset:4112
	ds_read_b128 v[192:195], v96 offset:4128
	ds_read_b128 v[196:199], v96 offset:4144
	v_readlane_b32 s52, v255, 1
	v_readlane_b32 s53, v255, 2
	v_add_f32_e32 v91, 1.0, v91
	v_cmp_gt_f32_e64 s[0:1], s7, v91
	s_nop 1
	v_cndmask_b32_e64 v93, 0, 32, s[0:1]
	v_ldexp_f32 v91, v91, v93
	v_log_f32_e32 v91, v91
	s_nop 0
	v_mul_f32_e32 v93, 0x3f317217, v91
	v_fma_f32 v93, v91, s8, -v93
	v_fmac_f32_e32 v93, 0x3377d1cf, v91
	v_fmac_f32_e32 v93, 0x3f317217, v91
	v_cmp_lt_f32_e64 s[4:5], |v91|, s9
	s_nop 1
	v_cndmask_b32_e64 v91, v91, v93, s[4:5]
	v_cndmask_b32_e64 v93, 0, v226, s[0:1]
	v_sub_f32_e32 v91, v91, v93
	v_add_f32_e32 v91, v92, v91
	s_nop 0
	v_mul_f32_e32 v91, 0xbd800000, v91
	v_cndmask_b32_e64 v91, 0, v91, s[80:81]
	v_add_f32_e32 v1, v1, v91
	s_waitcnt lgkmcnt(3)
	v_mul_f32_e32 v93, v6, v185
	v_fmac_f32_e32 v93, v4, v184
	v_fmac_f32_e32 v93, v8, v186
	v_fmac_f32_e32 v93, v10, v187
	v_add_f32_e32 v97, v26, v93
	s_nop 0
	s_waitcnt lgkmcnt(2)
	v_mul_f32_e32 v93, v7, v189
	v_fmac_f32_e32 v93, v5, v188
	v_fmac_f32_e32 v93, v9, v190
	v_fmac_f32_e32 v93, v11, v191
	v_add_f32_e32 v97, v97, v93
	s_nop 0
	s_waitcnt lgkmcnt(1)
	v_mul_f32_e32 v93, v14, v193
	v_fmac_f32_e32 v93, v12, v192
	v_fmac_f32_e32 v93, v16, v194
	v_fmac_f32_e32 v93, v18, v195
	v_add_f32_e32 v97, v97, v93
	s_nop 0
	s_waitcnt lgkmcnt(0)
	v_mul_f32_e32 v93, v15, v197
	v_fmac_f32_e32 v93, v13, v196
	v_fmac_f32_e32 v93, v17, v198
	v_fmac_f32_e32 v93, v19, v199
	v_add_f32_e32 v92, v97, v93
	v_max_f32_e64 v93, -v92, 0
	v_mul_f32_e64 v92, |v92|, s6
	v_exp_f32_e32 v92, v92
	s_nop 0
	v_add_f32_e32 v92, 1.0, v92
	v_cmp_gt_f32_e64 s[0:1], s7, v92
	s_nop 1
	v_cndmask_b32_e64 v94, 0, 32, s[0:1]
	v_ldexp_f32 v92, v92, v94
	v_log_f32_e32 v92, v92
	s_nop 0
	v_mul_f32_e32 v94, 0x3f317217, v92
	v_fma_f32 v94, v92, s8, -v94
	v_fmac_f32_e32 v94, 0x3377d1cf, v92
	v_fmac_f32_e32 v94, 0x3f317217, v92
	v_cmp_lt_f32_e64 s[4:5], |v92|, s9
	s_nop 1
	v_cndmask_b32_e64 v92, v92, v94, s[4:5]
	v_cndmask_b32_e64 v94, 0, v226, s[0:1]
	v_sub_f32_e32 v92, v92, v94
	v_add_f32_e32 v92, v93, v92
	v_mov_b32_e32 v93, s57
	ds_read_b128 v[184:187], v93 offset:4096
	ds_read_b128 v[188:191], v93 offset:4112
	ds_read_b128 v[192:195], v93 offset:4128
	ds_read_b128 v[196:199], v93 offset:4144
	s_nop 0
	v_mul_f32_e32 v92, 0xbd800000, v92
	v_cndmask_b32_e64 v92, 0, v92, s[78:79]
	v_add_f32_e32 v1, v1, v92
	v_readlane_b32 s56, v253, 32
	s_waitcnt lgkmcnt(3)
	v_mul_f32_e32 v95, v6, v185
	v_fmac_f32_e32 v95, v4, v184
	v_fmac_f32_e32 v95, v8, v186
	v_fmac_f32_e32 v95, v10, v187
	v_add_f32_e32 v98, v26, v95
	s_nop 0
	v_readlane_b32 s57, v253, 33
	s_waitcnt lgkmcnt(2)
	v_mul_f32_e32 v95, v7, v189
	v_fmac_f32_e32 v95, v5, v188
	v_fmac_f32_e32 v95, v9, v190
	v_fmac_f32_e32 v95, v11, v191
	v_add_f32_e32 v98, v98, v95
	s_nop 0
	s_waitcnt lgkmcnt(1)
	v_mul_f32_e32 v95, v14, v193
	v_fmac_f32_e32 v95, v12, v192
	v_fmac_f32_e32 v95, v16, v194
	v_fmac_f32_e32 v95, v18, v195
	v_add_f32_e32 v98, v98, v95
	s_nop 0
	s_waitcnt lgkmcnt(0)
	v_mul_f32_e32 v93, v15, v197
	v_fmac_f32_e32 v93, v13, v196
	v_fmac_f32_e32 v93, v17, v198
	v_fmac_f32_e32 v93, v19, v199
	v_add_f32_e32 v93, v98, v93
	v_max_f32_e64 v94, -v93, 0
	v_mul_f32_e64 v93, |v93|, s6
	v_exp_f32_e32 v93, v93
	v_mov_b32_e32 v98, s59
	ds_read_b128 v[184:187], v98 offset:4096
	ds_read_b128 v[188:191], v98 offset:4112
	ds_read_b128 v[192:195], v98 offset:4128
	ds_read_b128 v[196:199], v98 offset:4144
	v_readlane_b32 s58, v255, 27
	v_readlane_b32 s59, v255, 28
	v_add_f32_e32 v93, 1.0, v93
	v_cmp_gt_f32_e64 s[0:1], s7, v93
	s_nop 1
	v_cndmask_b32_e64 v95, 0, 32, s[0:1]
	v_ldexp_f32 v93, v93, v95
	v_log_f32_e32 v93, v93
	s_nop 0
	v_mul_f32_e32 v95, 0x3f317217, v93
	v_fma_f32 v95, v93, s8, -v95
	v_fmac_f32_e32 v95, 0x3377d1cf, v93
	v_fmac_f32_e32 v95, 0x3f317217, v93
	v_cmp_lt_f32_e64 s[4:5], |v93|, s9
	s_nop 1
	v_cndmask_b32_e64 v93, v93, v95, s[4:5]
	v_cndmask_b32_e64 v95, 0, v226, s[0:1]
	v_sub_f32_e32 v93, v93, v95
	v_add_f32_e32 v93, v94, v93
	s_nop 0
	v_mul_f32_e32 v93, 0xbd800000, v93
	v_cndmask_b32_e64 v93, 0, v93, s[76:77]
	v_add_f32_e32 v1, v1, v93
	s_waitcnt lgkmcnt(3)
	v_mul_f32_e32 v95, v6, v185
	v_fmac_f32_e32 v95, v4, v184
	v_fmac_f32_e32 v95, v8, v186
	v_fmac_f32_e32 v95, v10, v187
	v_add_f32_e32 v99, v26, v95
	s_nop 0
	s_waitcnt lgkmcnt(2)
	v_mul_f32_e32 v95, v7, v189
	v_fmac_f32_e32 v95, v5, v188
	v_fmac_f32_e32 v95, v9, v190
	v_fmac_f32_e32 v95, v11, v191
	v_add_f32_e32 v99, v99, v95
	s_nop 0
	s_waitcnt lgkmcnt(1)
	v_mul_f32_e32 v95, v14, v193
	v_fmac_f32_e32 v95, v12, v192
	v_fmac_f32_e32 v95, v16, v194
	v_fmac_f32_e32 v95, v18, v195
	v_add_f32_e32 v99, v99, v95
	s_nop 0
	s_waitcnt lgkmcnt(0)
	v_mul_f32_e32 v95, v15, v197
	v_fmac_f32_e32 v95, v13, v196
	v_fmac_f32_e32 v95, v17, v198
	v_fmac_f32_e32 v95, v19, v199
	v_add_f32_e32 v94, v99, v95
	v_max_f32_e64 v95, -v94, 0
	v_mul_f32_e64 v94, |v94|, s6
	v_exp_f32_e32 v94, v94
	s_nop 0
	v_add_f32_e32 v94, 1.0, v94
	v_cmp_gt_f32_e64 s[0:1], s7, v94
	s_nop 1
	v_cndmask_b32_e64 v96, 0, 32, s[0:1]
	v_ldexp_f32 v94, v94, v96
	v_log_f32_e32 v94, v94
	s_nop 0
	v_mul_f32_e32 v96, 0x3f317217, v94
	v_fma_f32 v96, v94, s8, -v96
	v_fmac_f32_e32 v96, 0x3377d1cf, v94
	v_fmac_f32_e32 v96, 0x3f317217, v94
	v_cmp_lt_f32_e64 s[4:5], |v94|, s9
	s_nop 1
	v_cndmask_b32_e64 v94, v94, v96, s[4:5]
	v_cndmask_b32_e64 v96, 0, v226, s[0:1]
	v_sub_f32_e32 v94, v94, v96
	v_add_f32_e32 v94, v95, v94
	v_mov_b32_e32 v95, s61
	ds_read_b128 v[184:187], v95 offset:4096
	ds_read_b128 v[188:191], v95 offset:4112
	ds_read_b128 v[192:195], v95 offset:4128
	ds_read_b128 v[196:199], v95 offset:4144
	s_nop 0
	s_nop 0
	s_nop 0
	s_nop 0
	v_mul_f32_e32 v94, 0xbd800000, v94
	s_waitcnt lgkmcnt(3)
	v_mul_f32_e32 v95, v6, v185
	v_fmac_f32_e32 v95, v4, v184
	s_waitcnt lgkmcnt(2)
	v_mul_f32_e32 v96, v7, v189
	v_fmac_f32_e32 v95, v8, v186
	v_fmac_f32_e32 v96, v5, v188
	v_fmac_f32_e32 v95, v10, v187
	v_fmac_f32_e32 v96, v9, v190
	v_add_f32_e32 v95, v26, v95
	v_fmac_f32_e32 v96, v11, v191
	v_add_f32_e32 v95, v95, v96
	s_waitcnt lgkmcnt(1)
	v_mul_f32_e32 v96, v14, v193
	v_fmac_f32_e32 v96, v12, v192
	v_fmac_f32_e32 v96, v16, v194
	v_fmac_f32_e32 v96, v18, v195
	v_add_f32_e32 v95, v95, v96
	s_waitcnt lgkmcnt(0)
	v_mul_f32_e32 v96, v15, v197
	v_fmac_f32_e32 v96, v13, v196
	v_fmac_f32_e32 v96, v17, v198
	v_fmac_f32_e32 v96, v19, v199
	v_add_f32_e32 v95, v95, v96
	v_max_f32_e64 v96, -v95, 0
	v_mul_f32_e64 v95, |v95|, s6
	v_exp_f32_e32 v95, v95
	v_mov_b32_e32 v108, s63
	ds_read_b128 v[184:187], v108 offset:4096
	ds_read_b128 v[188:191], v108 offset:4112
	ds_read_b128 v[192:195], v108 offset:4128
	ds_read_b128 v[196:199], v108 offset:4144
	v_cndmask_b32_e64 v94, 0, v94, s[74:75]
	v_readlane_b32 s62, v255, 23
	v_add_f32_e32 v95, 1.0, v95
	v_cmp_gt_f32_e64 s[0:1], s7, v95
	v_add_f32_e32 v1, v1, v94
	v_readlane_b32 s63, v255, 24
	v_cndmask_b32_e64 v97, 0, 32, s[0:1]
	v_ldexp_f32 v95, v95, v97
	v_log_f32_e32 v95, v95
	s_nop 0
	v_mul_f32_e32 v97, 0x3f317217, v95
	v_fma_f32 v97, v95, s8, -v97
	v_fmac_f32_e32 v97, 0x3377d1cf, v95
	v_fmac_f32_e32 v97, 0x3f317217, v95
	v_cmp_lt_f32_e64 s[4:5], |v95|, s9
	s_nop 1
	v_cndmask_b32_e64 v95, v95, v97, s[4:5]
	v_cndmask_b32_e64 v97, 0, v226, s[0:1]
	v_sub_f32_e32 v95, v95, v97
	v_add_f32_e32 v95, v96, v95
	s_nop 0
	s_nop 0
	s_nop 0
	s_nop 0
	v_mul_f32_e32 v95, 0xbd800000, v95
	s_waitcnt lgkmcnt(3)
	v_mul_f32_e32 v97, v6, v185
	v_fmac_f32_e32 v97, v4, v184
	v_fmac_f32_e32 v97, v8, v186
	v_fmac_f32_e32 v97, v10, v187
	v_add_f32_e32 v96, v26, v97
	s_waitcnt lgkmcnt(2)
	v_mul_f32_e32 v97, v7, v189
	v_fmac_f32_e32 v97, v5, v188
	v_fmac_f32_e32 v97, v9, v190
	v_fmac_f32_e32 v97, v11, v191
	v_add_f32_e32 v96, v96, v97
	s_waitcnt lgkmcnt(1)
	v_mul_f32_e32 v97, v14, v193
	v_fmac_f32_e32 v97, v12, v192
	v_fmac_f32_e32 v97, v16, v194
	v_fmac_f32_e32 v97, v18, v195
	v_add_f32_e32 v96, v96, v97
	s_waitcnt lgkmcnt(0)
	v_mul_f32_e32 v97, v15, v197
	v_fmac_f32_e32 v97, v13, v196
	v_fmac_f32_e32 v97, v17, v198
	v_fmac_f32_e32 v97, v19, v199
	v_add_f32_e32 v96, v96, v97
	v_max_f32_e64 v97, -v96, 0
	v_mul_f32_e64 v96, |v96|, s6
	v_exp_f32_e32 v96, v96
	v_cndmask_b32_e64 v95, 0, v95, s[70:71]
	v_add_f32_e32 v1, v1, v95
	v_add_f32_e32 v96, 1.0, v96
	v_cmp_gt_f32_e64 s[0:1], s7, v96
	s_nop 1
	v_cndmask_b32_e64 v98, 0, 32, s[0:1]
	v_ldexp_f32 v96, v96, v98
	v_log_f32_e32 v96, v96
	s_nop 0
	v_mul_f32_e32 v98, 0x3f317217, v96
	v_fma_f32 v98, v96, s8, -v98
	v_fmac_f32_e32 v98, 0x3377d1cf, v96
	v_fmac_f32_e32 v98, 0x3f317217, v96
	v_cmp_lt_f32_e64 s[4:5], |v96|, s9
	s_nop 1
	v_cndmask_b32_e64 v96, v96, v98, s[4:5]
	v_cndmask_b32_e64 v98, 0, v226, s[0:1]
	v_sub_f32_e32 v96, v96, v98
	v_add_f32_e32 v96, v97, v96
	v_mov_b32_e32 v97, s65
	ds_read_b128 v[184:187], v97 offset:4096
	ds_read_b128 v[188:191], v97 offset:4112
	ds_read_b128 v[192:195], v97 offset:4128
	ds_read_b128 v[196:199], v97 offset:4144
	s_nop 0
	s_nop 0
	s_nop 0
	s_nop 0
	v_mul_f32_e32 v96, 0xbd800000, v96
	s_waitcnt lgkmcnt(3)
	v_mul_f32_e32 v97, v6, v185
	v_fmac_f32_e32 v97, v4, v184
	s_waitcnt lgkmcnt(2)
	v_mul_f32_e32 v98, v7, v189
	v_fmac_f32_e32 v97, v8, v186
	v_fmac_f32_e32 v98, v5, v188
	v_fmac_f32_e32 v97, v10, v187
	v_fmac_f32_e32 v98, v9, v190
	v_add_f32_e32 v97, v26, v97
	v_fmac_f32_e32 v98, v11, v191
	v_add_f32_e32 v97, v97, v98
	s_waitcnt lgkmcnt(1)
	v_mul_f32_e32 v98, v14, v193
	v_fmac_f32_e32 v98, v12, v192
	v_fmac_f32_e32 v98, v16, v194
	v_fmac_f32_e32 v98, v18, v195
	v_add_f32_e32 v97, v97, v98
	s_waitcnt lgkmcnt(0)
	v_mul_f32_e32 v98, v15, v197
	v_fmac_f32_e32 v98, v13, v196
	v_fmac_f32_e32 v98, v17, v198
	v_fmac_f32_e32 v98, v19, v199
	v_add_f32_e32 v97, v97, v98
	v_max_f32_e64 v98, -v97, 0
	v_mul_f32_e64 v97, |v97|, s6
	v_exp_f32_e32 v97, v97
	v_mov_b32_e32 v110, s67
	ds_read_b128 v[184:187], v110 offset:4096
	ds_read_b128 v[188:191], v110 offset:4112
	ds_read_b128 v[192:195], v110 offset:4128
	ds_read_b128 v[196:199], v110 offset:4144
	v_readlane_b32 s64, v255, 17
	v_cndmask_b32_e64 v96, 0, v96, s[62:63]
	v_add_f32_e32 v97, 1.0, v97
	v_cmp_gt_f32_e64 s[0:1], s7, v97
	v_readlane_b32 s65, v255, 18
	v_add_f32_e32 v1, v1, v96
	v_cndmask_b32_e64 v99, 0, 32, s[0:1]
	v_ldexp_f32 v97, v97, v99
	v_log_f32_e32 v97, v97
	s_nop 0
	v_mul_f32_e32 v99, 0x3f317217, v97
	v_fma_f32 v99, v97, s8, -v99
	v_fmac_f32_e32 v99, 0x3377d1cf, v97
	v_fmac_f32_e32 v99, 0x3f317217, v97
	v_cmp_lt_f32_e64 s[4:5], |v97|, s9
	s_nop 1
	v_cndmask_b32_e64 v97, v97, v99, s[4:5]
	v_cndmask_b32_e64 v99, 0, v226, s[0:1]
	v_sub_f32_e32 v97, v97, v99
	v_add_f32_e32 v97, v98, v97
	s_nop 0
	s_nop 0
	s_nop 0
	s_nop 0
	v_mul_f32_e32 v97, 0xbd800000, v97
	s_waitcnt lgkmcnt(3)
	v_mul_f32_e32 v99, v6, v185
	v_fmac_f32_e32 v99, v4, v184
	v_fmac_f32_e32 v99, v8, v186
	v_fmac_f32_e32 v99, v10, v187
	v_add_f32_e32 v98, v26, v99
	s_waitcnt lgkmcnt(2)
	v_mul_f32_e32 v99, v7, v189
	v_fmac_f32_e32 v99, v5, v188
	v_fmac_f32_e32 v99, v9, v190
	v_fmac_f32_e32 v99, v11, v191
	v_add_f32_e32 v98, v98, v99
	s_waitcnt lgkmcnt(1)
	v_mul_f32_e32 v99, v14, v193
	v_fmac_f32_e32 v99, v12, v192
	v_fmac_f32_e32 v99, v16, v194
	v_fmac_f32_e32 v99, v18, v195
	v_add_f32_e32 v98, v98, v99
	s_waitcnt lgkmcnt(0)
	v_mul_f32_e32 v99, v15, v197
	v_fmac_f32_e32 v99, v13, v196
	v_fmac_f32_e32 v99, v17, v198
	v_fmac_f32_e32 v99, v19, v199
	v_add_f32_e32 v98, v98, v99
	v_max_f32_e64 v99, -v98, 0
	v_mul_f32_e64 v98, |v98|, s6
	v_exp_f32_e32 v98, v98
	v_cndmask_b32_e64 v97, 0, v97, s[64:65]
	v_add_f32_e32 v1, v1, v97
	v_add_f32_e32 v98, 1.0, v98
	v_cmp_gt_f32_e64 s[0:1], s7, v98
	s_nop 1
	v_cndmask_b32_e64 v100, 0, 32, s[0:1]
	v_ldexp_f32 v98, v98, v100
	v_log_f32_e32 v98, v98
	s_nop 0
	v_mul_f32_e32 v100, 0x3f317217, v98
	v_fma_f32 v100, v98, s8, -v100
	v_fmac_f32_e32 v100, 0x3377d1cf, v98
	v_fmac_f32_e32 v100, 0x3f317217, v98
	v_cmp_lt_f32_e64 s[4:5], |v98|, s9
	s_nop 1
	v_cndmask_b32_e64 v98, v98, v100, s[4:5]
	v_cndmask_b32_e64 v100, 0, v226, s[0:1]
	v_sub_f32_e32 v98, v98, v100
	v_add_f32_e32 v98, v99, v98
	v_mov_b32_e32 v99, s69
	ds_read_b128 v[184:187], v99 offset:4096
	ds_read_b128 v[188:191], v99 offset:4112
	ds_read_b128 v[192:195], v99 offset:4128
	ds_read_b128 v[196:199], v99 offset:4144
	s_nop 0
	s_nop 0
	s_nop 0
	s_nop 0
	v_mul_f32_e32 v98, 0xbd800000, v98
	s_waitcnt lgkmcnt(3)
	v_mul_f32_e32 v99, v6, v185
	v_fmac_f32_e32 v99, v4, v184
	s_waitcnt lgkmcnt(2)
	v_mul_f32_e32 v100, v7, v189
	v_fmac_f32_e32 v99, v8, v186
	v_fmac_f32_e32 v100, v5, v188
	v_fmac_f32_e32 v99, v10, v187
	v_fmac_f32_e32 v100, v9, v190
	v_add_f32_e32 v99, v26, v99
	v_fmac_f32_e32 v100, v11, v191
	v_add_f32_e32 v99, v99, v100
	s_waitcnt lgkmcnt(1)
	v_mul_f32_e32 v100, v14, v193
	v_fmac_f32_e32 v100, v12, v192
	v_fmac_f32_e32 v100, v16, v194
	v_fmac_f32_e32 v100, v18, v195
	v_add_f32_e32 v99, v99, v100
	s_waitcnt lgkmcnt(0)
	v_mul_f32_e32 v100, v15, v197
	v_fmac_f32_e32 v100, v13, v196
	v_fmac_f32_e32 v100, v17, v198
	v_fmac_f32_e32 v100, v19, v199
	v_add_f32_e32 v99, v99, v100
	v_max_f32_e64 v100, -v99, 0
	v_mul_f32_e64 v99, |v99|, s6
	v_exp_f32_e32 v99, v99
	v_cndmask_b32_e64 v98, 0, v98, s[58:59]
	v_add_f32_e32 v1, v1, v98
	v_add_f32_e32 v99, 1.0, v99
	v_cmp_gt_f32_e64 s[0:1], s7, v99
	s_nop 1
	v_cndmask_b32_e64 v101, 0, 32, s[0:1]
	v_ldexp_f32 v99, v99, v101
	v_log_f32_e32 v99, v99
	s_nop 0
	v_mul_f32_e32 v101, 0x3f317217, v99
	v_fma_f32 v101, v99, s8, -v101
	v_fmac_f32_e32 v101, 0x3377d1cf, v99
	v_fmac_f32_e32 v101, 0x3f317217, v99
	v_cmp_lt_f32_e64 s[4:5], |v99|, s9
	s_nop 1
	v_cndmask_b32_e64 v99, v99, v101, s[4:5]
	v_cndmask_b32_e64 v101, 0, v226, s[0:1]
	v_readlane_b32 s0, v255, 13
	v_sub_f32_e32 v99, v99, v101
	v_add_f32_e32 v99, v100, v99
	v_mov_b32_e32 v112, s0
	ds_read_b128 v[184:187], v112 offset:4096
	ds_read_b128 v[188:191], v112 offset:4112
	ds_read_b128 v[192:195], v112 offset:4128
	ds_read_b128 v[196:199], v112 offset:4144
	s_nop 0
	s_nop 0
	s_nop 0
	s_nop 0
	v_mul_f32_e32 v99, 0xbd800000, v99
	s_waitcnt lgkmcnt(3)
	v_mul_f32_e32 v101, v6, v185
	v_fmac_f32_e32 v101, v4, v184
	v_fmac_f32_e32 v101, v8, v186
	v_fmac_f32_e32 v101, v10, v187
	v_add_f32_e32 v100, v26, v101
	s_waitcnt lgkmcnt(2)
	v_mul_f32_e32 v101, v7, v189
	v_fmac_f32_e32 v101, v5, v188
	v_fmac_f32_e32 v101, v9, v190
	v_fmac_f32_e32 v101, v11, v191
	v_add_f32_e32 v100, v100, v101
	s_waitcnt lgkmcnt(1)
	v_mul_f32_e32 v101, v14, v193
	v_fmac_f32_e32 v101, v12, v192
	v_fmac_f32_e32 v101, v16, v194
	v_fmac_f32_e32 v101, v18, v195
	v_add_f32_e32 v100, v100, v101
	s_waitcnt lgkmcnt(0)
	v_mul_f32_e32 v101, v15, v197
	v_fmac_f32_e32 v101, v13, v196
	v_fmac_f32_e32 v101, v17, v198
	v_fmac_f32_e32 v101, v19, v199
	v_add_f32_e32 v100, v100, v101
	v_max_f32_e64 v101, -v100, 0
	v_mul_f32_e64 v100, |v100|, s6
	v_exp_f32_e32 v100, v100
	v_cndmask_b32_e64 v99, 0, v99, s[56:57]
	v_add_f32_e32 v1, v1, v99
	v_add_f32_e32 v100, 1.0, v100
	v_cmp_gt_f32_e64 s[0:1], s7, v100
	s_nop 1
	v_cndmask_b32_e64 v102, 0, 32, s[0:1]
	v_ldexp_f32 v100, v100, v102
	v_log_f32_e32 v100, v100
	s_nop 0
	v_mul_f32_e32 v102, 0x3f317217, v100
	v_fma_f32 v102, v100, s8, -v102
	v_fmac_f32_e32 v102, 0x3377d1cf, v100
	v_fmac_f32_e32 v102, 0x3f317217, v100
	v_cmp_lt_f32_e64 s[4:5], |v100|, s9
	s_nop 1
	v_cndmask_b32_e64 v100, v100, v102, s[4:5]
	v_cndmask_b32_e64 v102, 0, v226, s[0:1]
	v_sub_f32_e32 v100, v100, v102
	v_readlane_b32 s0, v255, 9
	v_add_f32_e32 v100, v101, v100
	v_mul_f32_e32 v100, 0xbd800000, v100
	v_mov_b32_e32 v101, s0
	ds_read_b128 v[184:187], v101 offset:4096
	ds_read_b128 v[188:191], v101 offset:4112
	ds_read_b128 v[192:195], v101 offset:4128
	ds_read_b128 v[196:199], v101 offset:4144
	s_nop 0
	s_nop 0
	s_nop 0
	s_nop 0
	v_cndmask_b32_e64 v100, 0, v100, s[54:55]
	s_waitcnt lgkmcnt(3)
	v_mul_f32_e32 v101, v6, v185
	v_fmac_f32_e32 v101, v4, v184
	s_waitcnt lgkmcnt(2)
	v_mul_f32_e32 v102, v7, v189
	v_fmac_f32_e32 v101, v8, v186
	v_fmac_f32_e32 v102, v5, v188
	v_fmac_f32_e32 v101, v10, v187
	v_fmac_f32_e32 v102, v9, v190
	v_add_f32_e32 v101, v26, v101
	v_fmac_f32_e32 v102, v11, v191
	v_add_f32_e32 v101, v101, v102
	s_waitcnt lgkmcnt(1)
	v_mul_f32_e32 v102, v14, v193
	v_fmac_f32_e32 v102, v12, v192
	v_fmac_f32_e32 v102, v16, v194
	v_fmac_f32_e32 v102, v18, v195
	v_add_f32_e32 v101, v101, v102
	s_waitcnt lgkmcnt(0)
	v_mul_f32_e32 v102, v15, v197
	v_fmac_f32_e32 v102, v13, v196
	v_fmac_f32_e32 v102, v17, v198
	v_fmac_f32_e32 v102, v19, v199
	v_add_f32_e32 v101, v101, v102
	v_max_f32_e64 v102, -v101, 0
	v_mul_f32_e64 v101, |v101|, s6
	v_exp_f32_e32 v101, v101
	v_add_f32_e32 v1, v1, v100
	v_add_f32_e32 v101, 1.0, v101
	v_cmp_gt_f32_e64 s[0:1], s7, v101
	s_nop 1
	v_cndmask_b32_e64 v103, 0, 32, s[0:1]
	v_ldexp_f32 v101, v101, v103
	v_log_f32_e32 v101, v101
	s_nop 0
	v_mul_f32_e32 v103, 0x3f317217, v101
	v_fma_f32 v103, v101, s8, -v103
	v_fmac_f32_e32 v103, 0x3377d1cf, v101
	v_fmac_f32_e32 v103, 0x3f317217, v101
	v_cmp_lt_f32_e64 s[4:5], |v101|, s9
	s_nop 1
	v_cndmask_b32_e64 v101, v101, v103, s[4:5]
	v_cndmask_b32_e64 v103, 0, v226, s[0:1]
	v_readlane_b32 s0, v254, 49
	v_sub_f32_e32 v101, v101, v103
	v_add_f32_e32 v101, v102, v101
	v_mov_b32_e32 v114, s0
	ds_read_b128 v[184:187], v114 offset:4096
	ds_read_b128 v[188:191], v114 offset:4112
	ds_read_b128 v[192:195], v114 offset:4128
	ds_read_b128 v[196:199], v114 offset:4144
	s_nop 0
	s_nop 0
	s_nop 0
	s_nop 0
	v_mul_f32_e32 v101, 0xbd800000, v101
	s_waitcnt lgkmcnt(3)
	v_mul_f32_e32 v103, v6, v185
	v_fmac_f32_e32 v103, v4, v184
	v_fmac_f32_e32 v103, v8, v186
	v_fmac_f32_e32 v103, v10, v187
	v_add_f32_e32 v102, v26, v103
	s_waitcnt lgkmcnt(2)
	v_mul_f32_e32 v103, v7, v189
	v_fmac_f32_e32 v103, v5, v188
	v_fmac_f32_e32 v103, v9, v190
	v_fmac_f32_e32 v103, v11, v191
	v_add_f32_e32 v102, v102, v103
	s_waitcnt lgkmcnt(1)
	v_mul_f32_e32 v103, v14, v193
	v_fmac_f32_e32 v103, v12, v192
	v_fmac_f32_e32 v103, v16, v194
	v_fmac_f32_e32 v103, v18, v195
	v_add_f32_e32 v102, v102, v103
	s_waitcnt lgkmcnt(0)
	v_mul_f32_e32 v103, v15, v197
	v_fmac_f32_e32 v103, v13, v196
	v_fmac_f32_e32 v103, v17, v198
	v_fmac_f32_e32 v103, v19, v199
	v_add_f32_e32 v102, v102, v103
	v_max_f32_e64 v103, -v102, 0
	v_mul_f32_e64 v102, |v102|, s6
	v_exp_f32_e32 v102, v102
	v_cndmask_b32_e64 v101, 0, v101, s[52:53]
	v_add_f32_e32 v1, v1, v101
	v_add_f32_e32 v102, 1.0, v102
	v_cmp_gt_f32_e64 s[0:1], s7, v102
	s_nop 1
	v_cndmask_b32_e64 v104, 0, 32, s[0:1]
	v_ldexp_f32 v102, v102, v104
	v_log_f32_e32 v102, v102
	s_nop 0
	v_mul_f32_e32 v104, 0x3f317217, v102
	v_fma_f32 v104, v102, s8, -v104
	v_fmac_f32_e32 v104, 0x3377d1cf, v102
	v_fmac_f32_e32 v104, 0x3f317217, v102
	v_cmp_lt_f32_e64 s[4:5], |v102|, s9
	s_nop 1
	v_cndmask_b32_e64 v102, v102, v104, s[4:5]
	v_cndmask_b32_e64 v104, 0, v226, s[0:1]
	v_sub_f32_e32 v102, v102, v104
	v_readlane_b32 s0, v254, 52
	v_add_f32_e32 v102, v103, v102
	v_mul_f32_e32 v102, 0xbd800000, v102
	v_mov_b32_e32 v103, s0
	ds_read_b128 v[184:187], v103 offset:4096
	ds_read_b128 v[188:191], v103 offset:4112
	ds_read_b128 v[192:195], v103 offset:4128
	ds_read_b128 v[196:199], v103 offset:4144
	s_nop 0
	s_nop 0
	s_nop 0
	s_nop 0
	v_cndmask_b32_e64 v102, 0, v102, s[48:49]
	s_waitcnt lgkmcnt(3)
	v_mul_f32_e32 v103, v6, v185
	v_fmac_f32_e32 v103, v4, v184
	s_waitcnt lgkmcnt(2)
	v_mul_f32_e32 v104, v7, v189
	v_fmac_f32_e32 v103, v8, v186
	v_fmac_f32_e32 v104, v5, v188
	v_fmac_f32_e32 v103, v10, v187
	v_fmac_f32_e32 v104, v9, v190
	v_add_f32_e32 v103, v26, v103
	v_fmac_f32_e32 v104, v11, v191
	v_add_f32_e32 v103, v103, v104
	s_waitcnt lgkmcnt(1)
	v_mul_f32_e32 v104, v14, v193
	v_fmac_f32_e32 v104, v12, v192
	v_fmac_f32_e32 v104, v16, v194
	v_fmac_f32_e32 v104, v18, v195
	v_add_f32_e32 v103, v103, v104
	s_waitcnt lgkmcnt(0)
	v_mul_f32_e32 v104, v15, v197
	v_fmac_f32_e32 v104, v13, v196
	v_fmac_f32_e32 v104, v17, v198
	v_fmac_f32_e32 v104, v19, v199
	v_add_f32_e32 v103, v103, v104
	v_max_f32_e64 v104, -v103, 0
	v_mul_f32_e64 v103, |v103|, s6
	v_exp_f32_e32 v103, v103
	v_add_f32_e32 v1, v1, v102
	v_add_f32_e32 v103, 1.0, v103
	v_cmp_gt_f32_e64 s[0:1], s7, v103
	s_nop 1
	v_cndmask_b32_e64 v105, 0, 32, s[0:1]
	v_ldexp_f32 v103, v103, v105
	v_log_f32_e32 v103, v103
	s_nop 0
	v_mul_f32_e32 v105, 0x3f317217, v103
	v_fma_f32 v105, v103, s8, -v105
	v_fmac_f32_e32 v105, 0x3377d1cf, v103
	v_fmac_f32_e32 v105, 0x3f317217, v103
	v_cmp_lt_f32_e64 s[4:5], |v103|, s9
	s_nop 1
	v_cndmask_b32_e64 v103, v103, v105, s[4:5]
	v_cndmask_b32_e64 v105, 0, v226, s[0:1]
	v_readlane_b32 s0, v254, 55
	v_sub_f32_e32 v103, v103, v105
	v_add_f32_e32 v103, v104, v103
	v_mov_b32_e32 v116, s0
	ds_read_b128 v[184:187], v116 offset:4096
	ds_read_b128 v[188:191], v116 offset:4112
	ds_read_b128 v[192:195], v116 offset:4128
	ds_read_b128 v[196:199], v116 offset:4144
	s_nop 0
	s_nop 0
	s_nop 0
	s_nop 0
	v_mul_f32_e32 v103, 0xbd800000, v103
	s_waitcnt lgkmcnt(3)
	v_mul_f32_e32 v105, v6, v185
	v_fmac_f32_e32 v105, v4, v184
	v_fmac_f32_e32 v105, v8, v186
	v_fmac_f32_e32 v105, v10, v187
	v_add_f32_e32 v104, v26, v105
	s_waitcnt lgkmcnt(2)
	v_mul_f32_e32 v105, v7, v189
	v_fmac_f32_e32 v105, v5, v188
	v_fmac_f32_e32 v105, v9, v190
	v_fmac_f32_e32 v105, v11, v191
	v_add_f32_e32 v104, v104, v105
	s_waitcnt lgkmcnt(1)
	v_mul_f32_e32 v105, v14, v193
	v_fmac_f32_e32 v105, v12, v192
	v_fmac_f32_e32 v105, v16, v194
	v_fmac_f32_e32 v105, v18, v195
	v_add_f32_e32 v104, v104, v105
	s_waitcnt lgkmcnt(0)
	v_mul_f32_e32 v105, v15, v197
	v_fmac_f32_e32 v105, v13, v196
	v_fmac_f32_e32 v105, v17, v198
	v_fmac_f32_e32 v105, v19, v199
	v_add_f32_e32 v104, v104, v105
	v_max_f32_e64 v105, -v104, 0
	v_mul_f32_e64 v104, |v104|, s6
	v_exp_f32_e32 v104, v104
	v_cndmask_b32_e64 v103, 0, v103, s[46:47]
	v_add_f32_e32 v1, v1, v103
	v_add_f32_e32 v104, 1.0, v104
	v_cmp_gt_f32_e64 s[0:1], s7, v104
	s_nop 1
	v_cndmask_b32_e64 v106, 0, 32, s[0:1]
	v_ldexp_f32 v104, v104, v106
	v_log_f32_e32 v104, v104
	s_nop 0
	v_mul_f32_e32 v106, 0x3f317217, v104
	v_fma_f32 v106, v104, s8, -v106
	v_fmac_f32_e32 v106, 0x3377d1cf, v104
	v_fmac_f32_e32 v106, 0x3f317217, v104
	v_cmp_lt_f32_e64 s[4:5], |v104|, s9
	s_nop 1
	v_cndmask_b32_e64 v104, v104, v106, s[4:5]
	v_cndmask_b32_e64 v106, 0, v226, s[0:1]
	v_sub_f32_e32 v104, v104, v106
	v_readlane_b32 s0, v254, 58
	v_add_f32_e32 v104, v105, v104
	v_mul_f32_e32 v104, 0xbd800000, v104
	v_mov_b32_e32 v105, s0
	ds_read_b128 v[184:187], v105 offset:4096
	ds_read_b128 v[188:191], v105 offset:4112
	ds_read_b128 v[192:195], v105 offset:4128
	ds_read_b128 v[196:199], v105 offset:4144
	s_nop 0
	s_nop 0
	s_nop 0
	s_nop 0
	v_cndmask_b32_e64 v104, 0, v104, s[42:43]
	s_waitcnt lgkmcnt(3)
	v_mul_f32_e32 v105, v6, v185
	v_fmac_f32_e32 v105, v4, v184
	s_waitcnt lgkmcnt(2)
	v_mul_f32_e32 v106, v7, v189
	v_fmac_f32_e32 v105, v8, v186
	v_fmac_f32_e32 v106, v5, v188
	v_fmac_f32_e32 v105, v10, v187
	v_fmac_f32_e32 v106, v9, v190
	v_add_f32_e32 v105, v26, v105
	v_fmac_f32_e32 v106, v11, v191
	v_add_f32_e32 v105, v105, v106
	s_waitcnt lgkmcnt(1)
	v_mul_f32_e32 v106, v14, v193
	v_fmac_f32_e32 v106, v12, v192
	v_fmac_f32_e32 v106, v16, v194
	v_fmac_f32_e32 v106, v18, v195
	v_add_f32_e32 v105, v105, v106
	s_waitcnt lgkmcnt(0)
	v_mul_f32_e32 v106, v15, v197
	v_fmac_f32_e32 v106, v13, v196
	v_fmac_f32_e32 v106, v17, v198
	v_fmac_f32_e32 v106, v19, v199
	v_add_f32_e32 v105, v105, v106
	v_max_f32_e64 v106, -v105, 0
	v_mul_f32_e64 v105, |v105|, s6
	v_exp_f32_e32 v105, v105
	v_add_f32_e32 v1, v1, v104
	v_add_f32_e32 v105, 1.0, v105
	v_cmp_gt_f32_e64 s[0:1], s7, v105
	s_nop 1
	v_cndmask_b32_e64 v107, 0, 32, s[0:1]
	v_ldexp_f32 v105, v105, v107
	v_log_f32_e32 v105, v105
	s_nop 0
	v_mul_f32_e32 v107, 0x3f317217, v105
	v_fma_f32 v107, v105, s8, -v107
	v_fmac_f32_e32 v107, 0x3377d1cf, v105
	v_fmac_f32_e32 v107, 0x3f317217, v105
	v_cmp_lt_f32_e64 s[4:5], |v105|, s9
	s_nop 1
	v_cndmask_b32_e64 v105, v105, v107, s[4:5]
	v_cndmask_b32_e64 v107, 0, v226, s[0:1]
	v_readlane_b32 s0, v254, 61
	v_sub_f32_e32 v105, v105, v107
	v_add_f32_e32 v105, v106, v105
	v_mov_b32_e32 v118, s0
	ds_read_b128 v[184:187], v118 offset:4096
	ds_read_b128 v[188:191], v118 offset:4112
	ds_read_b128 v[192:195], v118 offset:4128
	ds_read_b128 v[196:199], v118 offset:4144
	s_nop 0
	s_nop 0
	s_nop 0
	s_nop 0
	v_mul_f32_e32 v105, 0xbd800000, v105
	s_waitcnt lgkmcnt(3)
	v_mul_f32_e32 v107, v6, v185
	v_fmac_f32_e32 v107, v4, v184
	v_fmac_f32_e32 v107, v8, v186
	v_fmac_f32_e32 v107, v10, v187
	v_add_f32_e32 v106, v26, v107
	s_waitcnt lgkmcnt(2)
	v_mul_f32_e32 v107, v7, v189
	v_fmac_f32_e32 v107, v5, v188
	v_fmac_f32_e32 v107, v9, v190
	v_fmac_f32_e32 v107, v11, v191
	v_add_f32_e32 v106, v106, v107
	s_waitcnt lgkmcnt(1)
	v_mul_f32_e32 v107, v14, v193
	v_fmac_f32_e32 v107, v12, v192
	v_fmac_f32_e32 v107, v16, v194
	v_fmac_f32_e32 v107, v18, v195
	v_add_f32_e32 v106, v106, v107
	s_waitcnt lgkmcnt(0)
	v_mul_f32_e32 v107, v15, v197
	v_fmac_f32_e32 v107, v13, v196
	v_fmac_f32_e32 v107, v17, v198
	v_fmac_f32_e32 v107, v19, v199
	v_add_f32_e32 v106, v106, v107
	v_max_f32_e64 v107, -v106, 0
	v_mul_f32_e64 v106, |v106|, s6
	v_exp_f32_e32 v106, v106
	v_cndmask_b32_e64 v105, 0, v105, s[14:15]
	v_add_f32_e32 v1, v1, v105
	v_add_f32_e32 v106, 1.0, v106
	v_cmp_gt_f32_e64 s[0:1], s7, v106
	s_nop 1
	v_cndmask_b32_e64 v108, 0, 32, s[0:1]
	v_ldexp_f32 v106, v106, v108
	v_log_f32_e32 v106, v106
	s_nop 0
	v_mul_f32_e32 v108, 0x3f317217, v106
	v_fma_f32 v108, v106, s8, -v108
	v_fmac_f32_e32 v108, 0x3377d1cf, v106
	v_fmac_f32_e32 v108, 0x3f317217, v106
	v_cmp_lt_f32_e64 s[4:5], |v106|, s9
	s_nop 1
	v_cndmask_b32_e64 v106, v106, v108, s[4:5]
	v_cndmask_b32_e64 v108, 0, v226, s[0:1]
	v_sub_f32_e32 v106, v106, v108
	v_readlane_b32 s0, v253, 0
	v_add_f32_e32 v106, v107, v106
	v_mul_f32_e32 v106, 0xbd800000, v106
	v_mov_b32_e32 v107, s0
	ds_read_b128 v[184:187], v107 offset:4096
	ds_read_b128 v[188:191], v107 offset:4112
	ds_read_b128 v[192:195], v107 offset:4128
	ds_read_b128 v[196:199], v107 offset:4144
	s_nop 0
	s_nop 0
	s_nop 0
	s_nop 0
	v_cndmask_b32_e64 v106, 0, v106, s[40:41]
	s_waitcnt lgkmcnt(3)
	v_mul_f32_e32 v107, v6, v185
	v_fmac_f32_e32 v107, v4, v184
	s_waitcnt lgkmcnt(2)
	v_mul_f32_e32 v108, v7, v189
	v_fmac_f32_e32 v107, v8, v186
	v_fmac_f32_e32 v108, v5, v188
	v_fmac_f32_e32 v107, v10, v187
	v_fmac_f32_e32 v108, v9, v190
	v_add_f32_e32 v107, v26, v107
	v_fmac_f32_e32 v108, v11, v191
	v_add_f32_e32 v107, v107, v108
	s_waitcnt lgkmcnt(1)
	v_mul_f32_e32 v108, v14, v193
	v_fmac_f32_e32 v108, v12, v192
	v_fmac_f32_e32 v108, v16, v194
	v_fmac_f32_e32 v108, v18, v195
	v_add_f32_e32 v107, v107, v108
	s_waitcnt lgkmcnt(0)
	v_mul_f32_e32 v108, v15, v197
	v_fmac_f32_e32 v108, v13, v196
	v_fmac_f32_e32 v108, v17, v198
	v_fmac_f32_e32 v108, v19, v199
	v_add_f32_e32 v107, v107, v108
	v_max_f32_e64 v108, -v107, 0
	v_mul_f32_e64 v107, |v107|, s6
	v_exp_f32_e32 v107, v107
	v_add_f32_e32 v1, v1, v106
	v_add_f32_e32 v107, 1.0, v107
	v_cmp_gt_f32_e64 s[0:1], s7, v107
	s_nop 1
	v_cndmask_b32_e64 v109, 0, 32, s[0:1]
	v_ldexp_f32 v107, v107, v109
	v_log_f32_e32 v107, v107
	s_nop 0
	v_mul_f32_e32 v109, 0x3f317217, v107
	v_fma_f32 v109, v107, s8, -v109
	v_fmac_f32_e32 v109, 0x3377d1cf, v107
	v_fmac_f32_e32 v109, 0x3f317217, v107
	v_cmp_lt_f32_e64 s[4:5], |v107|, s9
	s_nop 1
	v_cndmask_b32_e64 v107, v107, v109, s[4:5]
	v_cndmask_b32_e64 v109, 0, v226, s[0:1]
	v_readlane_b32 s0, v253, 3
	v_sub_f32_e32 v107, v107, v109
	v_add_f32_e32 v107, v108, v107
	v_mov_b32_e32 v120, s0
	ds_read_b128 v[184:187], v120 offset:4096
	ds_read_b128 v[188:191], v120 offset:4112
	ds_read_b128 v[192:195], v120 offset:4128
	ds_read_b128 v[196:199], v120 offset:4144
	s_nop 0
	s_nop 0
	s_nop 0
	s_nop 0
	v_mul_f32_e32 v107, 0xbd800000, v107
	s_waitcnt lgkmcnt(3)
	v_mul_f32_e32 v109, v6, v185
	v_fmac_f32_e32 v109, v4, v184
	v_fmac_f32_e32 v109, v8, v186
	v_fmac_f32_e32 v109, v10, v187
	v_add_f32_e32 v108, v26, v109
	s_waitcnt lgkmcnt(2)
	v_mul_f32_e32 v109, v7, v189
	v_fmac_f32_e32 v109, v5, v188
	v_fmac_f32_e32 v109, v9, v190
	v_fmac_f32_e32 v109, v11, v191
	v_add_f32_e32 v108, v108, v109
	s_waitcnt lgkmcnt(1)
	v_mul_f32_e32 v109, v14, v193
	v_fmac_f32_e32 v109, v12, v192
	v_fmac_f32_e32 v109, v16, v194
	v_fmac_f32_e32 v109, v18, v195
	v_add_f32_e32 v108, v108, v109
	s_waitcnt lgkmcnt(0)
	v_mul_f32_e32 v109, v15, v197
	v_fmac_f32_e32 v109, v13, v196
	v_fmac_f32_e32 v109, v17, v198
	v_fmac_f32_e32 v109, v19, v199
	v_add_f32_e32 v108, v108, v109
	v_max_f32_e64 v109, -v108, 0
	v_mul_f32_e64 v108, |v108|, s6
	v_exp_f32_e32 v108, v108
	v_cndmask_b32_e64 v107, 0, v107, s[36:37]
	v_add_f32_e32 v1, v1, v107
	v_add_f32_e32 v108, 1.0, v108
	v_cmp_gt_f32_e64 s[0:1], s7, v108
	s_nop 1
	v_cndmask_b32_e64 v110, 0, 32, s[0:1]
	v_ldexp_f32 v108, v108, v110
	v_log_f32_e32 v108, v108
	s_nop 0
	v_mul_f32_e32 v110, 0x3f317217, v108
	v_fma_f32 v110, v108, s8, -v110
	v_fmac_f32_e32 v110, 0x3377d1cf, v108
	v_fmac_f32_e32 v110, 0x3f317217, v108
	v_cmp_lt_f32_e64 s[4:5], |v108|, s9
	s_nop 1
	v_cndmask_b32_e64 v108, v108, v110, s[4:5]
	v_cndmask_b32_e64 v110, 0, v226, s[0:1]
	v_sub_f32_e32 v108, v108, v110
	v_readlane_b32 s0, v253, 6
	v_add_f32_e32 v108, v109, v108
	v_mul_f32_e32 v108, 0xbd800000, v108
	v_mov_b32_e32 v109, s0
	ds_read_b128 v[184:187], v109 offset:4096
	ds_read_b128 v[188:191], v109 offset:4112
	ds_read_b128 v[192:195], v109 offset:4128
	ds_read_b128 v[196:199], v109 offset:4144
	s_nop 0
	s_nop 0
	s_nop 0
	s_nop 0
	v_cndmask_b32_e64 v108, 0, v108, s[34:35]
	s_waitcnt lgkmcnt(3)
	v_mul_f32_e32 v109, v6, v185
	v_fmac_f32_e32 v109, v4, v184
	s_waitcnt lgkmcnt(2)
	v_mul_f32_e32 v110, v7, v189
	v_fmac_f32_e32 v109, v8, v186
	v_fmac_f32_e32 v110, v5, v188
	v_fmac_f32_e32 v109, v10, v187
	v_fmac_f32_e32 v110, v9, v190
	v_add_f32_e32 v109, v26, v109
	v_fmac_f32_e32 v110, v11, v191
	v_add_f32_e32 v109, v109, v110
	s_waitcnt lgkmcnt(1)
	v_mul_f32_e32 v110, v14, v193
	v_fmac_f32_e32 v110, v12, v192
	v_fmac_f32_e32 v110, v16, v194
	v_fmac_f32_e32 v110, v18, v195
	v_add_f32_e32 v109, v109, v110
	s_waitcnt lgkmcnt(0)
	v_mul_f32_e32 v110, v15, v197
	v_fmac_f32_e32 v110, v13, v196
	v_fmac_f32_e32 v110, v17, v198
	v_fmac_f32_e32 v110, v19, v199
	v_add_f32_e32 v109, v109, v110
	v_max_f32_e64 v110, -v109, 0
	v_mul_f32_e64 v109, |v109|, s6
	v_exp_f32_e32 v109, v109
	v_mov_b32_e32 v122, s97
	ds_read_b128 v[184:187], v122 offset:4096
	ds_read_b128 v[188:191], v122 offset:4112
	ds_read_b128 v[192:195], v122 offset:4128
	ds_read_b128 v[196:199], v122 offset:4144
	v_add_f32_e32 v1, v1, v108
	v_add_f32_e32 v109, 1.0, v109
	v_cmp_gt_f32_e64 s[0:1], s7, v109
	s_nop 1
	v_cndmask_b32_e64 v111, 0, 32, s[0:1]
	v_ldexp_f32 v109, v109, v111
	v_log_f32_e32 v109, v109
	s_nop 0
	v_mul_f32_e32 v111, 0x3f317217, v109
	v_fma_f32 v111, v109, s8, -v111
	v_fmac_f32_e32 v111, 0x3377d1cf, v109
	v_fmac_f32_e32 v111, 0x3f317217, v109
	v_cmp_lt_f32_e64 s[4:5], |v109|, s9
	s_nop 1
	v_cndmask_b32_e64 v109, v109, v111, s[4:5]
	v_cndmask_b32_e64 v111, 0, v226, s[0:1]
	v_sub_f32_e32 v109, v109, v111
	v_add_f32_e32 v109, v110, v109
	s_nop 0
	s_nop 0
	s_nop 0
	s_nop 0
	v_mul_f32_e32 v109, 0xbd800000, v109
	s_waitcnt lgkmcnt(3)
	v_mul_f32_e32 v111, v6, v185
	v_fmac_f32_e32 v111, v4, v184
	v_fmac_f32_e32 v111, v8, v186
	v_fmac_f32_e32 v111, v10, v187
	v_add_f32_e32 v110, v26, v111
	s_waitcnt lgkmcnt(2)
	v_mul_f32_e32 v111, v7, v189
	v_fmac_f32_e32 v111, v5, v188
	v_fmac_f32_e32 v111, v9, v190
	v_fmac_f32_e32 v111, v11, v191
	v_add_f32_e32 v110, v110, v111
	s_waitcnt lgkmcnt(1)
	v_mul_f32_e32 v111, v14, v193
	v_fmac_f32_e32 v111, v12, v192
	v_fmac_f32_e32 v111, v16, v194
	v_fmac_f32_e32 v111, v18, v195
	v_add_f32_e32 v110, v110, v111
	s_waitcnt lgkmcnt(0)
	v_mul_f32_e32 v111, v15, v197
	v_fmac_f32_e32 v111, v13, v196
	v_fmac_f32_e32 v111, v17, v198
	v_fmac_f32_e32 v111, v19, v199
	v_add_f32_e32 v110, v110, v111
	v_max_f32_e64 v111, -v110, 0
	v_mul_f32_e64 v110, |v110|, s6
	v_exp_f32_e32 v110, v110
	v_cndmask_b32_e64 v109, 0, v109, s[30:31]
	v_add_f32_e32 v1, v1, v109
	v_add_f32_e32 v110, 1.0, v110
	v_cmp_gt_f32_e64 s[0:1], s7, v110
	s_nop 1
	v_cndmask_b32_e64 v112, 0, 32, s[0:1]
	v_ldexp_f32 v110, v110, v112
	v_log_f32_e32 v110, v110
	s_nop 0
	v_mul_f32_e32 v112, 0x3f317217, v110
	v_fma_f32 v112, v110, s8, -v112
	v_fmac_f32_e32 v112, 0x3377d1cf, v110
	v_fmac_f32_e32 v112, 0x3f317217, v110
	v_cmp_lt_f32_e64 s[4:5], |v110|, s9
	s_nop 1
	v_cndmask_b32_e64 v110, v110, v112, s[4:5]
	v_cndmask_b32_e64 v112, 0, v226, s[0:1]
	v_sub_f32_e32 v110, v110, v112
	v_add_f32_e32 v110, v111, v110
	v_mov_b32_e32 v111, s95
	ds_read_b128 v[184:187], v111 offset:4096
	ds_read_b128 v[188:191], v111 offset:4112
	ds_read_b128 v[192:195], v111 offset:4128
	ds_read_b128 v[196:199], v111 offset:4144
	s_nop 0
	s_nop 0
	s_nop 0
	s_nop 0
	v_mul_f32_e32 v110, 0xbd800000, v110
	s_waitcnt lgkmcnt(3)
	v_mul_f32_e32 v111, v6, v185
	v_fmac_f32_e32 v111, v4, v184
	s_waitcnt lgkmcnt(2)
	v_mul_f32_e32 v112, v7, v189
	v_fmac_f32_e32 v111, v8, v186
	v_fmac_f32_e32 v112, v5, v188
	v_fmac_f32_e32 v111, v10, v187
	v_fmac_f32_e32 v112, v9, v190
	v_add_f32_e32 v111, v26, v111
	v_fmac_f32_e32 v112, v11, v191
	v_add_f32_e32 v111, v111, v112
	s_waitcnt lgkmcnt(1)
	v_mul_f32_e32 v112, v14, v193
	v_fmac_f32_e32 v112, v12, v192
	v_fmac_f32_e32 v112, v16, v194
	v_fmac_f32_e32 v112, v18, v195
	v_add_f32_e32 v111, v111, v112
	s_waitcnt lgkmcnt(0)
	v_mul_f32_e32 v112, v15, v197
	v_fmac_f32_e32 v112, v13, v196
	v_fmac_f32_e32 v112, v17, v198
	v_fmac_f32_e32 v112, v19, v199
	v_add_f32_e32 v111, v111, v112
	v_max_f32_e64 v112, -v111, 0
	v_mul_f32_e64 v111, |v111|, s6
	v_exp_f32_e32 v111, v111
	v_mov_b32_e32 v124, s94
	ds_read_b128 v[184:187], v124 offset:4096
	ds_read_b128 v[188:191], v124 offset:4112
	ds_read_b128 v[192:195], v124 offset:4128
	ds_read_b128 v[196:199], v124 offset:4144
	v_cndmask_b32_e64 v110, 0, v110, s[24:25]
	v_add_f32_e32 v1, v1, v110
	v_add_f32_e32 v111, 1.0, v111
	v_cmp_gt_f32_e64 s[0:1], s7, v111
	s_nop 1
	v_cndmask_b32_e64 v113, 0, 32, s[0:1]
	v_ldexp_f32 v111, v111, v113
	v_log_f32_e32 v111, v111
	s_nop 0
	v_mul_f32_e32 v113, 0x3f317217, v111
	v_fma_f32 v113, v111, s8, -v113
	v_fmac_f32_e32 v113, 0x3377d1cf, v111
	v_fmac_f32_e32 v113, 0x3f317217, v111
	v_cmp_lt_f32_e64 s[4:5], |v111|, s9
	s_nop 1
	v_cndmask_b32_e64 v111, v111, v113, s[4:5]
	v_cndmask_b32_e64 v113, 0, v226, s[0:1]
	v_sub_f32_e32 v111, v111, v113
	v_add_f32_e32 v111, v112, v111
	s_nop 0
	s_nop 0
	s_nop 0
	s_nop 0
	v_mul_f32_e32 v111, 0xbd800000, v111
	s_waitcnt lgkmcnt(3)
	v_mul_f32_e32 v113, v6, v185
	v_fmac_f32_e32 v113, v4, v184
	v_fmac_f32_e32 v113, v8, v186
	v_fmac_f32_e32 v113, v10, v187
	v_add_f32_e32 v112, v26, v113
	s_waitcnt lgkmcnt(2)
	v_mul_f32_e32 v113, v7, v189
	v_fmac_f32_e32 v113, v5, v188
	v_fmac_f32_e32 v113, v9, v190
	v_fmac_f32_e32 v113, v11, v191
	v_add_f32_e32 v112, v112, v113
	s_waitcnt lgkmcnt(1)
	v_mul_f32_e32 v113, v14, v193
	v_fmac_f32_e32 v113, v12, v192
	v_fmac_f32_e32 v113, v16, v194
	v_fmac_f32_e32 v113, v18, v195
	v_add_f32_e32 v112, v112, v113
	s_waitcnt lgkmcnt(0)
	v_mul_f32_e32 v113, v15, v197
	v_fmac_f32_e32 v113, v13, v196
	v_fmac_f32_e32 v113, v17, v198
	v_fmac_f32_e32 v113, v19, v199
	v_add_f32_e32 v112, v112, v113
	v_max_f32_e64 v113, -v112, 0
	v_mul_f32_e64 v112, |v112|, s6
	v_exp_f32_e32 v112, v112
	v_cndmask_b32_e64 v111, 0, v111, s[44:45]
	v_add_f32_e32 v1, v1, v111
	v_add_f32_e32 v112, 1.0, v112
	v_cmp_gt_f32_e64 s[0:1], s7, v112
	s_nop 1
	v_cndmask_b32_e64 v114, 0, 32, s[0:1]
	v_ldexp_f32 v112, v112, v114
	v_log_f32_e32 v112, v112
	s_nop 0
	v_mul_f32_e32 v114, 0x3f317217, v112
	v_fma_f32 v114, v112, s8, -v114
	v_fmac_f32_e32 v114, 0x3377d1cf, v112
	v_fmac_f32_e32 v114, 0x3f317217, v112
	v_cmp_lt_f32_e64 s[4:5], |v112|, s9
	s_nop 1
	v_cndmask_b32_e64 v112, v112, v114, s[4:5]
	v_cndmask_b32_e64 v114, 0, v226, s[0:1]
	v_sub_f32_e32 v112, v112, v114
	v_add_f32_e32 v112, v113, v112
	v_mov_b32_e32 v113, s93
	ds_read_b128 v[184:187], v113 offset:4096
	ds_read_b128 v[188:191], v113 offset:4112
	ds_read_b128 v[192:195], v113 offset:4128
	ds_read_b128 v[196:199], v113 offset:4144
	s_nop 0
	s_nop 0
	s_nop 0
	s_nop 0
	v_mul_f32_e32 v112, 0xbd800000, v112
	s_waitcnt lgkmcnt(3)
	v_mul_f32_e32 v113, v6, v185
	v_fmac_f32_e32 v113, v4, v184
	s_waitcnt lgkmcnt(2)
	v_mul_f32_e32 v114, v7, v189
	v_fmac_f32_e32 v113, v8, v186
	v_fmac_f32_e32 v114, v5, v188
	v_fmac_f32_e32 v113, v10, v187
	v_fmac_f32_e32 v114, v9, v190
	v_add_f32_e32 v113, v26, v113
	v_fmac_f32_e32 v114, v11, v191
	v_add_f32_e32 v113, v113, v114
	s_waitcnt lgkmcnt(1)
	v_mul_f32_e32 v114, v14, v193
	v_fmac_f32_e32 v114, v12, v192
	v_fmac_f32_e32 v114, v16, v194
	v_fmac_f32_e32 v114, v18, v195
	v_add_f32_e32 v113, v113, v114
	s_waitcnt lgkmcnt(0)
	v_mul_f32_e32 v114, v15, v197
	v_fmac_f32_e32 v114, v13, v196
	v_fmac_f32_e32 v114, v17, v198
	v_fmac_f32_e32 v114, v19, v199
	v_add_f32_e32 v113, v113, v114
	v_max_f32_e64 v114, -v113, 0
	v_mul_f32_e64 v113, |v113|, s6
	v_exp_f32_e32 v113, v113
	v_mov_b32_e32 v126, s92
	ds_read_b128 v[184:187], v126 offset:4096
	ds_read_b128 v[188:191], v126 offset:4112
	ds_read_b128 v[192:195], v126 offset:4128
	v_cndmask_b32_e64 v112, 0, v112, s[26:27]
	v_add_f32_e32 v1, v1, v112
	v_add_f32_e32 v113, 1.0, v113
	v_cmp_gt_f32_e64 s[0:1], s7, v113
	s_nop 1
	v_cndmask_b32_e64 v115, 0, 32, s[0:1]
	v_ldexp_f32 v113, v113, v115
	v_log_f32_e32 v113, v113
	s_nop 0
	v_mul_f32_e32 v115, 0x3f317217, v113
	v_fma_f32 v115, v113, s8, -v115
	v_fmac_f32_e32 v115, 0x3377d1cf, v113
	v_fmac_f32_e32 v115, 0x3f317217, v113
	v_cmp_lt_f32_e64 s[4:5], |v113|, s9
	s_nop 1
	v_cndmask_b32_e64 v113, v113, v115, s[4:5]
	v_cndmask_b32_e64 v115, 0, v226, s[0:1]
	v_sub_f32_e32 v113, v113, v115
	v_add_f32_e32 v113, v114, v113
	s_nop 0
	s_nop 0
	s_nop 0
	ds_read_b128 v[126:129], v126 offset:4144
	v_mul_f32_e32 v113, 0xbd800000, v113
	s_waitcnt lgkmcnt(3)
	v_mul_f32_e32 v115, v6, v185
	v_fmac_f32_e32 v115, v4, v184
	v_fmac_f32_e32 v115, v8, v186
	v_fmac_f32_e32 v115, v10, v187
	v_add_f32_e32 v114, v26, v115
	s_waitcnt lgkmcnt(2)
	v_mul_f32_e32 v115, v7, v189
	v_fmac_f32_e32 v115, v5, v188
	v_fmac_f32_e32 v115, v9, v190
	v_fmac_f32_e32 v115, v11, v191
	v_add_f32_e32 v118, v114, v115
	s_waitcnt lgkmcnt(0)
	v_mov_b32_e32 v115, v126
	v_mov_b32_e32 v126, v193
	v_mov_b32_e32 v114, v192
	v_pk_mul_f32 v[116:117], v[14:15], v[126:127]
	v_cndmask_b32_e64 v113, 0, v113, s[28:29]
	v_pk_fma_f32 v[114:115], v[12:13], v[114:115], v[116:117]
	v_mov_b32_e32 v116, v194
	v_mov_b32_e32 v117, v128
	v_pk_fma_f32 v[114:115], v[16:17], v[116:117], v[114:115]
	v_mov_b32_e32 v128, v195
	v_pk_fma_f32 v[114:115], v[18:19], v[128:129], v[114:115]
	v_add_f32_e32 v1, v1, v113
	v_add_f32_e32 v114, v118, v114
	v_add_f32_e32 v114, v114, v115
	v_max_f32_e64 v115, -v114, 0
	v_mul_f32_e64 v114, |v114|, s6
	v_exp_f32_e32 v114, v114
	s_nop 0
	v_add_f32_e32 v114, 1.0, v114
	v_cmp_gt_f32_e64 s[0:1], s7, v114
	s_nop 1
	v_cndmask_b32_e64 v116, 0, 32, s[0:1]
	v_ldexp_f32 v114, v114, v116
	v_log_f32_e32 v114, v114
	s_nop 0
	v_mul_f32_e32 v116, 0x3f317217, v114
	v_fma_f32 v116, v114, s8, -v116
	v_fmac_f32_e32 v116, 0x3377d1cf, v114
	v_fmac_f32_e32 v116, 0x3f317217, v114
	v_cmp_lt_f32_e64 s[4:5], |v114|, s9
	s_nop 1
	v_cndmask_b32_e64 v114, v114, v116, s[4:5]
	v_cndmask_b32_e64 v116, 0, v226, s[0:1]
	v_sub_f32_e32 v114, v114, v116
	v_readlane_b32 s0, v254, 19
	v_add_f32_e32 v114, v115, v114
	v_mul_f32_e32 v114, 0xbd800000, v114
	v_mov_b32_e32 v115, s0
	ds_read_b128 v[184:187], v115 offset:4096
	ds_read_b128 v[188:191], v115 offset:4112
	ds_read_b128 v[192:195], v115 offset:4128
	s_nop 0
	s_nop 0
	s_nop 0
	ds_read_b128 v[128:131], v115 offset:4144
	v_cndmask_b32_e64 v114, 0, v114, s[22:23]
	s_waitcnt lgkmcnt(3)
	v_mul_f32_e32 v115, v6, v185
	v_fmac_f32_e32 v115, v4, v184
	s_waitcnt lgkmcnt(2)
	v_mul_f32_e32 v116, v7, v189
	v_fmac_f32_e32 v115, v8, v186
	v_fmac_f32_e32 v116, v5, v188
	v_fmac_f32_e32 v115, v10, v187
	v_fmac_f32_e32 v116, v9, v190
	v_add_f32_e32 v115, v26, v115
	v_fmac_f32_e32 v116, v11, v191
	s_waitcnt lgkmcnt(0)
	v_mov_b32_e32 v117, v128
	v_mov_b32_e32 v128, v193
	v_add_f32_e32 v115, v115, v116
	v_mov_b32_e32 v116, v192
	v_pk_mul_f32 v[118:119], v[14:15], v[128:129]
	v_mov_b32_e32 v128, s96
	ds_read_b128 v[184:187], v128 offset:4096
	v_pk_fma_f32 v[116:117], v[12:13], v[116:117], v[118:119]
	v_mov_b32_e32 v118, v194
	v_mov_b32_e32 v119, v130
	v_pk_fma_f32 v[116:117], v[16:17], v[118:119], v[116:117]
	v_mov_b32_e32 v130, v195
	v_pk_fma_f32 v[116:117], v[18:19], v[130:131], v[116:117]
	v_add_f32_e32 v1, v1, v114
	v_add_f32_e32 v115, v115, v116
	v_add_f32_e32 v115, v115, v117
	v_max_f32_e64 v116, -v115, 0
	v_mul_f32_e64 v115, |v115|, s6
	v_exp_f32_e32 v115, v115
	s_nop 0
	v_add_f32_e32 v115, 1.0, v115
	v_cmp_gt_f32_e64 s[0:1], s7, v115
	s_nop 1
	v_cndmask_b32_e64 v117, 0, 32, s[0:1]
	v_ldexp_f32 v115, v115, v117
	v_log_f32_e32 v115, v115
	s_nop 0
	v_mul_f32_e32 v117, 0x3f317217, v115
	v_fma_f32 v117, v115, s8, -v117
	v_fmac_f32_e32 v117, 0x3377d1cf, v115
	v_fmac_f32_e32 v117, 0x3f317217, v115
	v_cmp_lt_f32_e64 s[4:5], |v115|, s9
	s_nop 1
	v_cndmask_b32_e64 v115, v115, v117, s[4:5]
	v_cndmask_b32_e64 v117, 0, v226, s[0:1]
	v_sub_f32_e32 v115, v115, v117
	v_add_f32_e32 v115, v116, v115
	s_nop 0
	ds_read_b128 v[188:191], v128 offset:4128
	ds_read_b128 v[120:123], v128 offset:4112
	s_nop 0
	ds_read_b128 v[128:131], v128 offset:4144
	v_mul_f32_e32 v115, 0xbd800000, v115
	s_waitcnt lgkmcnt(3)
	v_mov_b32_e32 v132, v184
	s_waitcnt lgkmcnt(1)
	v_mov_b32_e32 v133, v120
	v_mov_b32_e32 v120, v185
	v_pk_mul_f32 v[116:117], v[6:7], v[120:121]
	v_mov_b32_e32 v120, v186
	v_pk_fma_f32 v[116:117], v[4:5], v[132:133], v[116:117]
	v_mov_b32_e32 v121, v122
	v_pk_fma_f32 v[116:117], v[8:9], v[120:121], v[116:117]
	v_mov_b32_e32 v122, v187
	v_pk_fma_f32 v[116:117], v[10:11], v[122:123], v[116:117]
	v_cndmask_b32_e64 v115, 0, v115, s[10:11]
	v_add_f32_e32 v116, v26, v116
	v_add_f32_e32 v120, v116, v117
	s_waitcnt lgkmcnt(0)
	v_mov_b32_e32 v117, v128
	v_mov_b32_e32 v128, v189
	v_mov_b32_e32 v116, v188
	v_pk_mul_f32 v[118:119], v[14:15], v[128:129]
	v_add_f32_e32 v1, v1, v115
	v_pk_fma_f32 v[116:117], v[12:13], v[116:117], v[118:119]
	v_mov_b32_e32 v118, v190
	v_mov_b32_e32 v119, v130
	v_pk_fma_f32 v[116:117], v[16:17], v[118:119], v[116:117]
	v_mov_b32_e32 v130, v191
	v_pk_fma_f32 v[116:117], v[18:19], v[130:131], v[116:117]
	s_nop 0
	v_add_f32_e32 v116, v120, v116
	v_add_f32_e32 v116, v116, v117
	v_max_f32_e64 v117, -v116, 0
	v_mul_f32_e64 v116, |v116|, s6
	v_exp_f32_e32 v116, v116
	s_nop 0
	v_add_f32_e32 v116, 1.0, v116
	v_cmp_gt_f32_e64 s[0:1], s7, v116
	s_nop 1
	v_cndmask_b32_e64 v118, 0, 32, s[0:1]
	v_ldexp_f32 v116, v116, v118
	v_log_f32_e32 v116, v116
	s_nop 0
	v_mul_f32_e32 v118, 0x3f317217, v116
	v_fma_f32 v118, v116, s8, -v118
	v_fmac_f32_e32 v118, 0x3377d1cf, v116
	v_fmac_f32_e32 v118, 0x3f317217, v116
	v_cmp_lt_f32_e64 s[4:5], |v116|, s9
	s_nop 1
	v_cndmask_b32_e64 v116, v116, v118, s[4:5]
	v_cndmask_b32_e64 v118, 0, v226, s[0:1]
	v_sub_f32_e32 v116, v116, v118
	v_add_f32_e32 v116, v117, v116
	v_mov_b32_e32 v117, s68
	ds_read_b128 v[184:187], v117 offset:4096
	s_nop 0
	ds_read_b128 v[188:191], v117 offset:4128
	ds_read_b128 v[122:125], v117 offset:4112
	s_nop 0
	ds_read_b128 v[130:133], v117 offset:4144
	v_mul_f32_e32 v116, 0xbd800000, v116
	s_waitcnt lgkmcnt(3)
	v_mov_b32_e32 v134, v184
	s_waitcnt lgkmcnt(1)
	v_mov_b32_e32 v135, v122
	v_mov_b32_e32 v122, v185
	v_pk_mul_f32 v[118:119], v[6:7], v[122:123]
	v_mov_b32_e32 v122, v186
	v_pk_fma_f32 v[118:119], v[4:5], v[134:135], v[118:119]
	v_mov_b32_e32 v123, v124
	v_pk_fma_f32 v[118:119], v[8:9], v[122:123], v[118:119]
	v_mov_b32_e32 v124, v187
	v_pk_fma_f32 v[118:119], v[10:11], v[124:125], v[118:119]
	v_cndmask_b32_e64 v116, 0, v116, s[18:19]
	v_add_f32_e32 v117, v26, v118
	v_add_f32_e32 v117, v117, v119
	s_waitcnt lgkmcnt(0)
	v_mov_b32_e32 v119, v130
	v_mov_b32_e32 v130, v189
	v_mov_b32_e32 v118, v188
	v_pk_mul_f32 v[120:121], v[14:15], v[130:131]
	v_mov_b32_e32 v130, s66
	ds_read_b128 v[184:187], v130 offset:4096
	v_pk_fma_f32 v[118:119], v[12:13], v[118:119], v[120:121]
	v_mov_b32_e32 v120, v190
	v_mov_b32_e32 v121, v132
	v_pk_fma_f32 v[118:119], v[16:17], v[120:121], v[118:119]
	v_mov_b32_e32 v132, v191
	v_pk_fma_f32 v[118:119], v[18:19], v[132:133], v[118:119]
	v_add_f32_e32 v1, v1, v116
	v_add_f32_e32 v117, v117, v118
	v_add_f32_e32 v117, v117, v119
	v_max_f32_e64 v118, -v117, 0
	v_mul_f32_e64 v117, |v117|, s6
	v_exp_f32_e32 v117, v117
	s_nop 0
	v_add_f32_e32 v117, 1.0, v117
	v_cmp_gt_f32_e64 s[0:1], s7, v117
	s_nop 1
	v_cndmask_b32_e64 v119, 0, 32, s[0:1]
	v_ldexp_f32 v117, v117, v119
	v_log_f32_e32 v117, v117
	s_nop 0
	v_mul_f32_e32 v119, 0x3f317217, v117
	v_fma_f32 v119, v117, s8, -v119
	v_fmac_f32_e32 v119, 0x3377d1cf, v117
	v_fmac_f32_e32 v119, 0x3f317217, v117
	v_cmp_lt_f32_e64 s[4:5], |v117|, s9
	s_nop 1
	v_cndmask_b32_e64 v117, v117, v119, s[4:5]
	v_cndmask_b32_e64 v119, 0, v226, s[0:1]
	v_sub_f32_e32 v117, v117, v119
	v_add_f32_e32 v117, v118, v117
	s_nop 0
	ds_read_b128 v[188:191], v130 offset:4128
	ds_read_b128 v[122:125], v130 offset:4112
	s_nop 0
	ds_read_b128 v[130:133], v130 offset:4144
	v_mul_f32_e32 v117, 0xbd800000, v117
	s_waitcnt lgkmcnt(3)
	v_mov_b32_e32 v134, v184
	s_waitcnt lgkmcnt(1)
	v_mov_b32_e32 v135, v122
	v_mov_b32_e32 v122, v185
	v_pk_mul_f32 v[118:119], v[6:7], v[122:123]
	v_mov_b32_e32 v122, v186
	v_pk_fma_f32 v[118:119], v[4:5], v[134:135], v[118:119]
	v_mov_b32_e32 v123, v124
	v_pk_fma_f32 v[118:119], v[8:9], v[122:123], v[118:119]
	v_mov_b32_e32 v124, v187
	v_pk_fma_f32 v[118:119], v[10:11], v[124:125], v[118:119]
	v_cndmask_b32_e64 v117, 0, v117, s[20:21]
	v_add_f32_e32 v118, v26, v118
	v_add_f32_e32 v122, v118, v119
	s_waitcnt lgkmcnt(0)
	v_mov_b32_e32 v119, v130
	v_mov_b32_e32 v130, v189
	v_mov_b32_e32 v118, v188
	v_pk_mul_f32 v[120:121], v[14:15], v[130:131]
	v_add_f32_e32 v1, v1, v117
	v_pk_fma_f32 v[118:119], v[12:13], v[118:119], v[120:121]
	v_mov_b32_e32 v120, v190
	v_mov_b32_e32 v121, v132
	v_pk_fma_f32 v[118:119], v[16:17], v[120:121], v[118:119]
	v_mov_b32_e32 v132, v191
	v_pk_fma_f32 v[118:119], v[18:19], v[132:133], v[118:119]
	s_nop 0
	v_add_f32_e32 v118, v122, v118
	v_add_f32_e32 v118, v118, v119
	v_max_f32_e64 v119, -v118, 0
	v_mul_f32_e64 v118, |v118|, s6
	v_exp_f32_e32 v118, v118
	s_nop 0
	v_add_f32_e32 v118, 1.0, v118
	v_cmp_gt_f32_e64 s[0:1], s7, v118
	s_nop 1
	v_cndmask_b32_e64 v120, 0, 32, s[0:1]
	v_ldexp_f32 v118, v118, v120
	v_log_f32_e32 v118, v118
	s_nop 0
	v_mul_f32_e32 v120, 0x3f317217, v118
	v_fma_f32 v120, v118, s8, -v120
	v_fmac_f32_e32 v120, 0x3377d1cf, v118
	v_fmac_f32_e32 v120, 0x3f317217, v118
	v_cmp_lt_f32_e64 s[4:5], |v118|, s9
	s_nop 1
	v_cndmask_b32_e64 v118, v118, v120, s[4:5]
	v_cndmask_b32_e64 v120, 0, v226, s[0:1]
	v_sub_f32_e32 v118, v118, v120
	v_add_f32_e32 v118, v119, v118
	v_mov_b32_e32 v119, s60
	ds_read_b128 v[120:123], v119 offset:4096
	ds_read_b128 v[124:127], v119 offset:4112
	ds_read_b128 v[128:131], v119 offset:4128
	ds_read_b128 v[132:135], v119 offset:4144
	v_mul_f32_e32 v118, 0xbd800000, v118
	s_waitcnt lgkmcnt(3)
	v_mov_b32_e32 v136, v120
	s_waitcnt lgkmcnt(2)
	v_mov_b32_e32 v137, v124
	v_mov_b32_e32 v124, v121
	v_pk_mul_f32 v[6:7], v[6:7], v[124:125]
	v_cndmask_b32_e64 v118, 0, v118, s[12:13]
	v_pk_fma_f32 v[4:5], v[4:5], v[136:137], v[6:7]
	v_mov_b32_e32 v6, v122
	v_mov_b32_e32 v7, v126
	v_pk_fma_f32 v[4:5], v[8:9], v[6:7], v[4:5]
	v_mov_b32_e32 v126, v123
	v_pk_fma_f32 v[4:5], v[10:11], v[126:127], v[4:5]
	v_add_f32_e32 v1, v1, v118
	v_add_f32_e32 v4, v26, v4
	v_add_f32_e32 v8, v4, v5
	s_waitcnt lgkmcnt(0)
	v_mov_b32_e32 v5, v132
	v_mov_b32_e32 v132, v129
	v_mov_b32_e32 v4, v128
	v_pk_mul_f32 v[6:7], v[14:15], v[132:133]
	s_nop 0
	v_pk_fma_f32 v[4:5], v[12:13], v[4:5], v[6:7]
	v_mov_b32_e32 v6, v130
	v_mov_b32_e32 v7, v134
	v_pk_fma_f32 v[4:5], v[16:17], v[6:7], v[4:5]
	v_mov_b32_e32 v134, v131
	v_pk_fma_f32 v[4:5], v[18:19], v[134:135], v[4:5]
	s_nop 0
	v_add_f32_e32 v4, v8, v4
	v_add_f32_e32 v4, v4, v5
	v_max_f32_e64 v5, -v4, 0
	v_mul_f32_e64 v4, |v4|, s6
	v_exp_f32_e32 v4, v4
	s_nop 0
	v_add_f32_e32 v4, 1.0, v4
	v_cmp_gt_f32_e64 s[0:1], s7, v4
	s_mov_b64 s[6:7], s[88:89]
	s_nop 0
	v_cndmask_b32_e64 v6, 0, 32, s[0:1]
	v_ldexp_f32 v4, v4, v6
	v_log_f32_e32 v4, v4
	s_nop 0
	v_mul_f32_e32 v6, 0x3f317217, v4
	v_fma_f32 v6, v4, s8, -v6
	v_fmac_f32_e32 v6, 0x3377d1cf, v4
	v_fmac_f32_e32 v6, 0x3f317217, v4
	v_cmp_lt_f32_e64 s[4:5], |v4|, s9
	s_nop 1
	v_cndmask_b32_e64 v4, v4, v6, s[4:5]
	v_cndmask_b32_e64 v6, 0, v226, s[0:1]
	v_sub_f32_e32 v4, v4, v6
	v_readlane_b32 s4, v253, 10
	v_add_f32_e32 v4, v5, v4
	v_readlane_b32 s5, v253, 11
	v_mul_f32_e32 v4, 0xbd800000, v4
	v_lshl_add_u64 v[6:7], s[84:85], 0, v[2:3]
	v_cndmask_b32_e64 v12, 0, v4, s[4:5]
	v_lshlrev_b32_sdwa v4, v228, v25 dst_sel:DWORD dst_unused:UNUSED_PAD src0_sel:DWORD src1_sel:BYTE_0
	v_add_f32_e32 v1, v1, v12
	v_add_u32_e32 v5, s50, v4
	ds_write_b32 v5, v1
	v_add_u32_e32 v1, 0, v4
	s_waitcnt lgkmcnt(0)
	s_barrier
	ds_read2st64_b32 v[4:5], v1 offset1:4
	v_lshl_add_u64 v[2:3], s[86:87], 0, v[2:3]
	s_waitcnt lgkmcnt(0)
	v_cndmask_b32_e64 v1, v4, 0, s[6:7]
	v_add_f32_e32 v9, v22, v1
	v_sub_f32_e32 v1, v4, v9
	v_mul_f32_e32 v1, 0x3fb8aa3b, v1
	v_exp_f32_e32 v1, v1
	s_nop 0
	v_mul_f32_e32 v8, v1, v89
	s_cbranch_scc1 .LBB0_531
	v_sub_f32_e32 v1, v9, v4
	v_mul_f32_e32 v1, 0x3fb8aa3b, v1
	v_exp_f32_e32 v1, v1
	v_lshlrev_b32_e32 v10, 16, v86
	v_mul_f32_e32 v1, v1, v10
	v_cvt_pk_bf16_f32 v1, v1, s0
	s_lshl_b64 s[0:1], s[38:39], 11
	v_lshl_add_u64 v[10:11], v[6:7], 0, s[0:1]
	global_store_short v[10:11], v1, off
	v_cvt_pk_bf16_f32 v1, v8, s0
	v_lshl_add_u64 v[10:11], v[2:3], 0, s[0:1]
	global_store_short v[10:11], v1, off

.LBB0_707:
	ds_read_b64_tr_b16 v[134:135], v211
	ds_read_b64_tr_b16 v[136:137], v211 offset:1088
	ds_read_b64_tr_b16 v[130:131], v211 offset:8704
	ds_read_b64_tr_b16 v[132:133], v211 offset:9792
	v_mov_b32_e32 v138, 0
	s_andn2_b64 vcc, exec, s[18:19]
	v_mov_b32_e32 v140, 0
	v_mov_b32_e32 v141, 0
	v_mov_b32_e32 v142, 0
	v_mov_b32_e32 v143, 0
	s_cbranch_vccnz .LBB0_709
	ds_read_b128 v[102:105], v221
	ds_read_b128 v[106:109], v232
	ds_read_b128 v[110:113], v221 offset:64
	ds_read_b128 v[114:117], v232 offset:64
	ds_read_b128 v[118:121], v221 offset:128
	ds_read_b128 v[122:125], v232 offset:128
	s_nop 0
	s_nop 0
	s_waitcnt lgkmcnt(6)
	s_waitcnt lgkmcnt(4)
	v_mfma_f32_16x16x32_bf16 v[140:143], v[102:105], v[106:109], 0
	ds_read_b128 v[102:105], v221 offset:192
	ds_read_b128 v[106:109], v232 offset:192
	s_nop 0
	s_nop 0
	s_waitcnt lgkmcnt(4)
	v_mfma_f32_16x16x32_bf16 v[140:143], v[110:113], v[114:117], v[140:143]
	ds_read_b128 v[110:113], v221 offset:256
	ds_read_b128 v[114:117], v232 offset:256
	s_nop 0
	s_nop 0
	s_waitcnt lgkmcnt(4)
	v_mfma_f32_16x16x32_bf16 v[140:143], v[118:121], v[122:125], v[140:143]
	ds_read_b128 v[118:121], v221 offset:320
	ds_read_b128 v[122:125], v232 offset:320
	s_nop 0
	s_nop 0
	s_waitcnt lgkmcnt(4)
	v_mfma_f32_16x16x32_bf16 v[140:143], v[102:105], v[106:109], v[140:143]
	ds_read_b128 v[102:105], v221 offset:384
	ds_read_b128 v[106:109], v232 offset:384
	s_nop 0
	s_nop 0
	s_waitcnt lgkmcnt(4)
	v_mfma_f32_16x16x32_bf16 v[140:143], v[110:113], v[114:117], v[140:143]
	s_nop 0
	s_nop 0
	s_waitcnt lgkmcnt(2)
	v_mfma_f32_16x16x32_bf16 v[140:143], v[118:121], v[122:125], v[140:143]
	s_nop 0
	s_nop 0
	s_waitcnt lgkmcnt(0)
	v_mfma_f32_16x16x32_bf16 v[140:143], v[102:105], v[106:109], v[140:143]
	ds_read_b128 v[144:147], v221 offset:448
	ds_read_b128 v[148:151], v232 offset:448
	s_waitcnt lgkmcnt(0)
	v_mfma_f32_16x16x32_bf16 v[140:143], v[144:147], v[148:151], v[140:143]
.LBB0_709:
	s_nop 7
	v_cndmask_b32_e64 v1, v140, 0, s[40:41]
	v_cndmask_b32_e64 v35, 0, v141, s[42:43]
	v_cndmask_b32_e64 v1, v1, v140, s[42:43]
	v_cndmask_b32_e64 v37, v142, 0, s[44:45]
	v_cndmask_b32_e64 v139, v143, 0, s[46:47]
	v_cvt_pk_bf16_f32 v36, v1, v35
	v_cvt_pk_bf16_f32 v37, v37, v139
	s_andn2_b64 vcc, exec, s[20:21]
	v_mov_b32_e32 v139, 0
	v_mov_b32_e32 v140, 0
	v_mov_b32_e32 v141, 0
	ds_write_b64 v212, v[36:37]
	s_cbranch_vccnz .LBB0_711
	ds_read_b128 v[102:105], v221 offset:8448
	ds_read_b128 v[106:109], v232
	ds_read_b128 v[110:113], v221 offset:8512
	ds_read_b128 v[114:117], v232 offset:64
	ds_read_b128 v[118:121], v221 offset:8576
	ds_read_b128 v[122:125], v232 offset:128
	s_nop 0
	s_nop 0
	s_waitcnt lgkmcnt(6)
	s_waitcnt lgkmcnt(4)
	v_mfma_f32_16x16x32_bf16 v[138:141], v[102:105], v[106:109], 0
	ds_read_b128 v[102:105], v221 offset:8640
	ds_read_b128 v[106:109], v232 offset:192
	s_nop 0
	s_nop 0
	s_waitcnt lgkmcnt(4)
	v_mfma_f32_16x16x32_bf16 v[138:141], v[110:113], v[114:117], v[138:141]
	ds_read_b128 v[110:113], v221 offset:8704
	ds_read_b128 v[114:117], v232 offset:256
	s_nop 0
	s_nop 0
	s_waitcnt lgkmcnt(4)
	v_mfma_f32_16x16x32_bf16 v[138:141], v[118:121], v[122:125], v[138:141]
	ds_read_b128 v[118:121], v221 offset:8768
	ds_read_b128 v[122:125], v232 offset:320
	s_nop 0
	s_nop 0
	s_waitcnt lgkmcnt(4)
	v_mfma_f32_16x16x32_bf16 v[138:141], v[102:105], v[106:109], v[138:141]
	ds_read_b128 v[102:105], v221 offset:8832
	ds_read_b128 v[106:109], v232 offset:384
	s_nop 0
	s_nop 0
	s_waitcnt lgkmcnt(4)
	v_mfma_f32_16x16x32_bf16 v[138:141], v[110:113], v[114:117], v[138:141]
	s_nop 0
	s_nop 0
	s_waitcnt lgkmcnt(2)
	v_mfma_f32_16x16x32_bf16 v[138:141], v[118:121], v[122:125], v[138:141]
	s_nop 0
	s_nop 0
	s_waitcnt lgkmcnt(0)
	v_mfma_f32_16x16x32_bf16 v[138:141], v[102:105], v[106:109], v[138:141]
	ds_read_b128 v[142:145], v221 offset:8896
	ds_read_b128 v[146:149], v232 offset:448
	s_waitcnt lgkmcnt(0)
	v_mfma_f32_16x16x32_bf16 v[138:141], v[142:145], v[146:149], v[138:141]
.LBB0_711:
	s_nop 7
	v_cndmask_b32_e64 v1, v138, 0, s[48:49]
	v_cndmask_b32_e64 v35, v139, 0, s[50:51]
	v_cndmask_b32_e64 v37, v140, 0, s[52:53]
	v_cndmask_b32_e64 v138, v141, 0, s[54:55]
	v_cvt_pk_bf16_f32 v36, v1, v35
	v_cvt_pk_bf16_f32 v37, v37, v138
	ds_write_b64 v213, v[36:37]
	ds_read_b128 v[102:105], v155
	ds_read_b128 v[106:109], v180
	ds_read_b64 v[110:111], v157
	ds_read_b64 v[112:113], v157 offset:32
	s_nop 0
	s_nop 0
	v_add_u32_e32 v1, 0x2000, v157
	ds_read_b64 v[114:115], v1 offset:256
	ds_read_b64 v[116:117], v1 offset:288
	v_add_u32_e32 v35, 0x4000, v157
	ds_read_b64 v[118:119], v35 offset:512
	ds_read_b64 v[120:121], v35 offset:544
	v_add_u32_e32 v246, 0x6000, v157
	ds_read_b64 v[122:123], v246 offset:768
	ds_read_b64 v[124:125], v246 offset:800
	s_waitcnt lgkmcnt(11)
	s_waitcnt lgkmcnt(9)
	v_pk_mul_f32 v[36:37], v[4:5], v[104:105]
	ds_read_b128 v[126:129], v181
	v_pk_mul_f32 v[138:139], v[2:3], v[102:103]
	s_waitcnt lgkmcnt(9)
	v_pk_mul_f32 v[140:141], v[10:11], v[106:107]
	ds_read_b128 v[102:105], v182
	v_cvt_pk_bf16_f32 v138, v138, v139
	v_cvt_pk_bf16_f32 v139, v36, v37
	v_pk_mul_f32 v[36:37], v[12:13], v[108:109]
	v_cvt_pk_bf16_f32 v140, v140, v141
	v_cvt_pk_bf16_f32 v141, v36, v37
	s_nop 0
	s_nop 0
	s_nop 0
	s_nop 0
	s_waitcnt lgkmcnt(8)
	v_mfma_f32_16x16x32_bf16 v[142:145], v[138:141], v[110:113], 0
	ds_read_b64 v[106:107], v157 offset:64
	ds_read_b64 v[108:109], v157 offset:96
	s_andn2_b64 vcc, exec, s[22:23]
	s_waitcnt lgkmcnt(8)
	v_mfma_f32_16x16x32_bf16 v[146:149], v[138:141], v[114:117], 0
	ds_read_b64 v[110:111], v1 offset:320
	ds_read_b64 v[112:113], v1 offset:352
	s_waitcnt lgkmcnt(8)
	v_mfma_f32_16x16x32_bf16 v[150:153], v[138:141], v[118:121], 0
	ds_read_b64 v[114:115], v35 offset:576
	ds_read_b64 v[116:117], v35 offset:608
	s_waitcnt lgkmcnt(8)
	v_mfma_f32_16x16x32_bf16 v[138:141], v[138:141], v[122:125], 0
	ds_read_b64 v[118:119], v246 offset:832
	ds_read_b64 v[120:121], v246 offset:864
	s_nop 0
	s_nop 0
	s_waitcnt lgkmcnt(9)
	v_pk_mul_f32 v[36:37], v[8:9], v[128:129]
	ds_read_b128 v[122:125], v183
	v_pk_mul_f32 v[234:235], v[6:7], v[126:127]
	s_waitcnt lgkmcnt(9)
	v_pk_mul_f32 v[236:237], v[14:15], v[102:103]
	ds_read_b128 v[126:129], v184
	v_cvt_pk_bf16_f32 v234, v234, v235
	v_cvt_pk_bf16_f32 v235, v36, v37
	v_pk_mul_f32 v[36:37], v[16:17], v[104:105]
	v_cvt_pk_bf16_f32 v236, v236, v237
	v_cvt_pk_bf16_f32 v237, v36, v37
	s_nop 0
	s_waitcnt lgkmcnt(8)
	v_mfma_f32_16x16x32_bf16 v[142:145], v[234:237], v[106:109], v[142:145]
	ds_read_b64 v[102:103], v157 offset:128
	ds_read_b64 v[104:105], v157 offset:160
	s_nop 0
	s_waitcnt lgkmcnt(8)
	v_mfma_f32_16x16x32_bf16 v[146:149], v[234:237], v[110:113], v[146:149]
	ds_read_b64 v[106:107], v1 offset:384
	ds_read_b64 v[108:109], v1 offset:416
	s_nop 0
	s_waitcnt lgkmcnt(8)
	v_mfma_f32_16x16x32_bf16 v[150:153], v[234:237], v[114:117], v[150:153]
	ds_read_b64 v[110:111], v35 offset:640
	ds_read_b64 v[112:113], v35 offset:672
	s_nop 0
	s_waitcnt lgkmcnt(8)
	v_mfma_f32_16x16x32_bf16 v[138:141], v[234:237], v[118:121], v[138:141]
	ds_read_b64 v[114:115], v246 offset:896
	ds_read_b64 v[116:117], v246 offset:928
	s_nop 0
	s_nop 0
	s_waitcnt lgkmcnt(9)
	v_pk_mul_f32 v[36:37], v[20:21], v[124:125]
	ds_read_b128 v[118:121], v185
	v_pk_mul_f32 v[234:235], v[18:19], v[122:123]
	s_waitcnt lgkmcnt(9)
	v_pk_mul_f32 v[236:237], v[22:23], v[126:127]
	ds_read_b128 v[122:125], v186
	v_cvt_pk_bf16_f32 v234, v234, v235
	v_cvt_pk_bf16_f32 v235, v36, v37
	v_pk_mul_f32 v[36:37], v[24:25], v[128:129]
	v_cvt_pk_bf16_f32 v236, v236, v237
	v_cvt_pk_bf16_f32 v237, v36, v37
	s_nop 0
	s_waitcnt lgkmcnt(8)
	v_mfma_f32_16x16x32_bf16 v[142:145], v[234:237], v[102:105], v[142:145]
	ds_read_b64 v[102:103], v157 offset:192
	ds_read_b64 v[104:105], v157 offset:224
	s_nop 0
	s_waitcnt lgkmcnt(8)
	v_mfma_f32_16x16x32_bf16 v[146:149], v[234:237], v[106:109], v[146:149]
	ds_read_b64 v[106:107], v1 offset:448
	ds_read_b64 v[108:109], v1 offset:480
	s_nop 0
	s_waitcnt lgkmcnt(8)
	v_mfma_f32_16x16x32_bf16 v[150:153], v[234:237], v[110:113], v[150:153]
	ds_read_b64 v[110:111], v35 offset:704
	ds_read_b64 v[112:113], v35 offset:736
	s_nop 0
	s_waitcnt lgkmcnt(8)
	v_mfma_f32_16x16x32_bf16 v[138:141], v[234:237], v[114:117], v[138:141]
	ds_read_b64 v[114:115], v246 offset:960
	ds_read_b64 v[116:117], v246 offset:992
	s_nop 0
	s_nop 0
	s_waitcnt lgkmcnt(9)
	v_pk_mul_f32 v[36:37], v[28:29], v[120:121]
	ds_read_b128 v[126:129], v187
	v_pk_mul_f32 v[234:235], v[26:27], v[118:119]
	s_waitcnt lgkmcnt(9)
	v_pk_mul_f32 v[236:237], v[30:31], v[122:123]
	ds_read_b128 v[118:121], v188
	v_cvt_pk_bf16_f32 v234, v234, v235
	v_cvt_pk_bf16_f32 v235, v36, v37
	v_pk_mul_f32 v[36:37], v[32:33], v[124:125]
	v_cvt_pk_bf16_f32 v236, v236, v237
	v_cvt_pk_bf16_f32 v237, v36, v37
	s_nop 0
	s_waitcnt lgkmcnt(8)
	v_mfma_f32_16x16x32_bf16 v[142:145], v[234:237], v[102:105], v[142:145]
	ds_read_b64 v[102:103], v157 offset:256
	ds_read_b64 v[104:105], v157 offset:288
	s_nop 0
	s_waitcnt lgkmcnt(8)
	v_mfma_f32_16x16x32_bf16 v[146:149], v[234:237], v[106:109], v[146:149]
	ds_read_b64 v[106:107], v1 offset:512
	ds_read_b64 v[108:109], v1 offset:544
	s_nop 0
	s_waitcnt lgkmcnt(8)
	v_mfma_f32_16x16x32_bf16 v[150:153], v[234:237], v[110:113], v[150:153]
	ds_read_b64 v[110:111], v35 offset:768
	ds_read_b64 v[112:113], v35 offset:800
	s_nop 0
	s_waitcnt lgkmcnt(8)
	v_mfma_f32_16x16x32_bf16 v[138:141], v[234:237], v[114:117], v[138:141]
	ds_read_b64 v[114:115], v246 offset:1024
	ds_read_b64 v[116:117], v246 offset:1056
	s_nop 0
	s_nop 0
	s_waitcnt lgkmcnt(9)
	v_pk_mul_f32 v[36:37], v[40:41], v[128:129]
	ds_read_b128 v[122:125], v189
	v_pk_mul_f32 v[234:235], v[38:39], v[126:127]
	s_waitcnt lgkmcnt(9)
	v_pk_mul_f32 v[236:237], v[42:43], v[118:119]
	ds_read_b128 v[126:129], v190
	v_cvt_pk_bf16_f32 v234, v234, v235
	v_cvt_pk_bf16_f32 v235, v36, v37
	v_pk_mul_f32 v[36:37], v[44:45], v[120:121]
	v_cvt_pk_bf16_f32 v236, v236, v237
	v_cvt_pk_bf16_f32 v237, v36, v37
	s_nop 0
	s_waitcnt lgkmcnt(8)
	v_mfma_f32_16x16x32_bf16 v[142:145], v[234:237], v[102:105], v[142:145]
	ds_read_b64 v[102:103], v157 offset:320
	ds_read_b64 v[104:105], v157 offset:352
	s_nop 0
	s_waitcnt lgkmcnt(8)
	v_mfma_f32_16x16x32_bf16 v[146:149], v[234:237], v[106:109], v[146:149]
	ds_read_b64 v[106:107], v1 offset:576
	ds_read_b64 v[108:109], v1 offset:608
	s_nop 0
	s_waitcnt lgkmcnt(8)
	v_mfma_f32_16x16x32_bf16 v[150:153], v[234:237], v[110:113], v[150:153]
	ds_read_b64 v[110:111], v35 offset:832
	ds_read_b64 v[112:113], v35 offset:864
	s_nop 0
	s_waitcnt lgkmcnt(8)
	v_mfma_f32_16x16x32_bf16 v[138:141], v[234:237], v[114:117], v[138:141]
	ds_read_b64 v[114:115], v246 offset:1088
	ds_read_b64 v[116:117], v246 offset:1120
	s_nop 0
	s_nop 0
	s_waitcnt lgkmcnt(9)
	v_pk_mul_f32 v[36:37], v[48:49], v[124:125]
	ds_read_b128 v[118:121], v191
	v_pk_mul_f32 v[234:235], v[46:47], v[122:123]
	s_waitcnt lgkmcnt(9)
	v_pk_mul_f32 v[236:237], v[50:51], v[126:127]
	ds_read_b128 v[122:125], v192
	v_cvt_pk_bf16_f32 v234, v234, v235
	v_cvt_pk_bf16_f32 v235, v36, v37
	v_pk_mul_f32 v[36:37], v[52:53], v[128:129]
	v_cvt_pk_bf16_f32 v236, v236, v237
	v_cvt_pk_bf16_f32 v237, v36, v37
	s_nop 0
	s_waitcnt lgkmcnt(8)
	v_mfma_f32_16x16x32_bf16 v[142:145], v[234:237], v[102:105], v[142:145]
	ds_read_b64 v[102:103], v157 offset:384
	ds_read_b64 v[104:105], v157 offset:416
	s_nop 0
	s_waitcnt lgkmcnt(8)
	v_mfma_f32_16x16x32_bf16 v[146:149], v[234:237], v[106:109], v[146:149]
	ds_read_b64 v[106:107], v1 offset:640
	ds_read_b64 v[108:109], v1 offset:672
	s_nop 0
	s_waitcnt lgkmcnt(8)
	v_mfma_f32_16x16x32_bf16 v[150:153], v[234:237], v[110:113], v[150:153]
	ds_read_b64 v[110:111], v35 offset:896
	ds_read_b64 v[112:113], v35 offset:928
	s_nop 0
	s_waitcnt lgkmcnt(8)
	v_mfma_f32_16x16x32_bf16 v[138:141], v[234:237], v[114:117], v[138:141]
	ds_read_b64 v[114:115], v246 offset:1152
	ds_read_b64 v[116:117], v246 offset:1184
	s_nop 0
	s_nop 0
	s_waitcnt lgkmcnt(9)
	v_pk_mul_f32 v[36:37], v[56:57], v[120:121]
	ds_read_b128 v[126:129], v193
	v_pk_mul_f32 v[234:235], v[54:55], v[118:119]
	s_waitcnt lgkmcnt(9)
	v_pk_mul_f32 v[236:237], v[58:59], v[122:123]
	ds_read_b128 v[118:121], v194
	v_cvt_pk_bf16_f32 v234, v234, v235
	v_cvt_pk_bf16_f32 v235, v36, v37
	v_pk_mul_f32 v[36:37], v[60:61], v[124:125]
	v_cvt_pk_bf16_f32 v236, v236, v237
	v_cvt_pk_bf16_f32 v237, v36, v37
	s_nop 0
	s_waitcnt lgkmcnt(8)
	v_mfma_f32_16x16x32_bf16 v[142:145], v[234:237], v[102:105], v[142:145]
	ds_read_b64 v[102:103], v157 offset:448
	ds_read_b64 v[104:105], v157 offset:480
	s_nop 0
	s_waitcnt lgkmcnt(8)
	v_mfma_f32_16x16x32_bf16 v[146:149], v[234:237], v[106:109], v[146:149]
	s_nop 0
	s_waitcnt lgkmcnt(6)
	v_mfma_f32_16x16x32_bf16 v[238:241], v[234:237], v[110:113], v[150:153]
	s_nop 2
	s_nop 0
	s_waitcnt lgkmcnt(4)
	v_mfma_f32_16x16x32_bf16 v[138:141], v[234:237], v[114:117], v[138:141]
	s_nop 0
	s_nop 0
	s_waitcnt lgkmcnt(3)
	v_pk_mul_f32 v[36:37], v[64:65], v[128:129]
	v_pk_mul_f32 v[150:151], v[62:63], v[126:127]
	v_cvt_pk_bf16_f32 v243, v36, v37
	v_cvt_pk_bf16_f32 v242, v150, v151
	s_waitcnt lgkmcnt(2)
	v_pk_mul_f32 v[36:37], v[68:69], v[120:121]
	v_pk_mul_f32 v[150:151], v[66:67], v[118:119]
	v_cvt_pk_bf16_f32 v245, v36, v37
	v_cvt_pk_bf16_f32 v244, v150, v151
	s_nop 0
	ds_read_b64 v[106:107], v1 offset:704
	ds_read_b64 v[108:109], v1 offset:736
	ds_read_b64 v[234:235], v246 offset:1216
	ds_read_b64 v[236:237], v246 offset:1248
	s_waitcnt lgkmcnt(4)
	v_mfma_f32_16x16x32_bf16 v[150:153], v[242:245], v[102:105], v[142:145]
	s_nop 2
	s_nop 0
	s_waitcnt lgkmcnt(2)
	v_mfma_f32_16x16x32_bf16 v[146:149], v[242:245], v[106:109], v[146:149]
	ds_read_b64 v[142:143], v35 offset:960
	ds_read_b64 v[144:145], v35 offset:992
	s_waitcnt lgkmcnt(0)
	s_barrier
	v_mfma_f32_16x16x32_bf16 v[142:145], v[242:245], v[142:145], v[238:241]
	v_mfma_f32_16x16x32_bf16 v[138:141], v[242:245], v[234:237], v[138:141]
	s_cbranch_vccnz .LBB0_719
	v_mov_b32_e32 v1, v158
	s_mov_b32 s22, s79
	v_ashrrev_i32_e32 v35, 5, v1
	v_lshlrev_b32_e32 v1, 4, v1
	v_and_b32_e32 v1, 0x1f0, v1
	v_mul_lo_u32 v35, v35, s84
	v_add3_u32 v1, 0, v1, v35
	s_waitcnt vmcnt(0)
	ds_write_b128 v1, v[70:73]
	ds_write_b128 v1, v[74:77] offset:33792
	ds_write_b128 v1, v[78:81] offset:8448
	ds_write_b128 v1, v[82:85] offset:42240
	ds_write_b128 v1, v[86:89] offset:16896
	ds_write_b128 v1, v[90:93] offset:50688
	ds_write_b128 v1, v[94:97] offset:25344
	ds_write_b128 v1, v[98:101] offset:59136
	v_mov_b32_e32 v1, v158
	s_lshl_b32 s26, s22, 6
	s_add_i32 s22, s22, s75
	s_ashr_i32 s23, s22, 31
	s_ashr_i32 s27, s26, 31
	s_sub_i32 s80, s7, s26
	s_lshl_b64 s[24:25], s[22:23], 17
	s_add_u32 s24, s73, s24
	v_lshlrev_b32_e32 v36, 3, v1
	s_addc_u32 s25, s74, s25
	v_mov_b32_e32 v37, v34
	v_lshl_add_u64 v[110:111], v[36:37], 1, s[24:25]
	s_movk_i32 s24, 0x2000
	v_add_co_u32_e32 v106, vcc, s24, v110
	s_movk_i32 s24, 0x4000
	s_nop 0
	v_addc_co_u32_e32 v107, vcc, 0, v111, vcc
	v_add_co_u32_e32 v112, vcc, s24, v110
	s_movk_i32 s24, 0x6000
	s_nop 0
	v_addc_co_u32_e32 v113, vcc, 0, v111, vcc
	v_add_co_u32_e32 v114, vcc, s24, v110
	global_load_dwordx4 v[102:105], v[110:111], off
	s_nop 0
	global_load_dwordx4 v[106:109], v[106:107], off
	v_addc_co_u32_e32 v115, vcc, 0, v111, vcc
	global_load_dwordx4 v[110:113], v[112:113], off
	s_nop 0
	global_load_dwordx4 v[114:117], v[114:115], off
	v_ashrrev_i32_e32 v35, 4, v1
	v_and_b32_e32 v1, 0x78, v36
	s_add_u32 s24, s26, s71
	v_mov_b32_e32 v126, 0
	v_mov_b32_e32 v127, v34
	v_lshl_or_b32 v36, v35, 11, v1
	s_addc_u32 s25, s27, s72
	s_min_i32 s80, s80, 64
	v_mov_b32_e32 v128, v34
	v_mov_b32_e32 v129, v34
	v_mov_b64_e32 v[118:119], v[126:127]
	v_lshl_add_u64 v[36:37], v[36:37], 1, s[14:15]
	v_cmp_gt_i32_e32 vcc, s80, v35
	v_mov_b64_e32 v[120:121], v[128:129]
	s_and_saveexec_b64 s[26:27], vcc
	s_cbranch_execz .LBB0_714
	s_lshl_b64 s[82:83], s[24:25], 12
	v_lshl_add_u64 v[118:119], v[36:37], 0, s[82:83]
	global_load_dwordx4 v[118:121], v[118:119], off

.LBB0_735:
	s_or_b64 exec, exec, s[24:25]
	ds_read_b128 v[70:73], v163
	ds_read_b128 v[74:77], v218
	ds_read_b128 v[78:81], v218 offset:64
	ds_read_b128 v[82:85], v195
	ds_read_b128 v[86:89], v218 offset:2304
	ds_read_b128 v[90:93], v218 offset:2368
	s_nop 0
	v_cmp_gt_i32_e32 vcc, s26, v158
	s_and_b64 s[26:27], s[56:57], vcc
	s_waitcnt lgkmcnt(6)
	s_waitcnt lgkmcnt(5)
	v_pk_mul_f32 v[4:5], v[4:5], v[72:73]
	ds_read_b128 v[94:97], v196
	v_pk_mul_f32 v[2:3], v[2:3], v[70:71]
	s_nop 0
	s_waitcnt lgkmcnt(5)
	v_mfma_f32_16x16x32_bf16 v[2:5], v[74:77], v[134:137], v[2:5]
	ds_read_b128 v[70:73], v218 offset:4608
	s_nop 0
	s_waitcnt lgkmcnt(5)
	v_mfma_f32_16x16x32_bf16 v[2:5], v[78:81], v[130:133], v[2:5]
	ds_read_b128 v[74:77], v218 offset:4672
	s_nop 0
	s_waitcnt lgkmcnt(5)
	v_pk_mul_f32 v[12:13], v[12:13], v[84:85]
	ds_read_b128 v[78:81], v197
	v_pk_mul_f32 v[10:11], v[10:11], v[82:83]
	s_nop 0
	s_waitcnt lgkmcnt(5)
	v_mfma_f32_16x16x32_bf16 v[10:13], v[86:89], v[134:137], v[10:13]
	ds_read_b128 v[82:85], v218 offset:6912
	s_nop 0
	s_waitcnt lgkmcnt(5)
	v_mfma_f32_16x16x32_bf16 v[10:13], v[90:93], v[130:133], v[10:13]
	ds_read_b128 v[86:89], v218 offset:6976
	s_nop 0
	s_waitcnt lgkmcnt(5)
	v_pk_mul_f32 v[8:9], v[8:9], v[96:97]
	ds_read_b128 v[90:93], v198
	v_pk_mul_f32 v[6:7], v[6:7], v[94:95]
	s_nop 0
	s_waitcnt lgkmcnt(5)
	v_mfma_f32_16x16x32_bf16 v[6:9], v[70:73], v[134:137], v[6:9]
	ds_read_b128 v[70:73], v218 offset:9216
	s_nop 0
	s_waitcnt lgkmcnt(5)
	v_mfma_f32_16x16x32_bf16 v[6:9], v[74:77], v[130:133], v[6:9]
	ds_read_b128 v[74:77], v218 offset:9280
	s_nop 0
	s_waitcnt lgkmcnt(5)
	v_pk_mul_f32 v[16:17], v[16:17], v[80:81]
	ds_read_b128 v[94:97], v199
	v_pk_mul_f32 v[14:15], v[14:15], v[78:79]
	s_nop 0
	s_waitcnt lgkmcnt(5)
	v_mfma_f32_16x16x32_bf16 v[14:17], v[82:85], v[134:137], v[14:17]
	ds_read_b128 v[78:81], v218 offset:11520
	s_nop 0
	s_waitcnt lgkmcnt(5)
	v_mfma_f32_16x16x32_bf16 v[14:17], v[86:89], v[130:133], v[14:17]
	ds_read_b128 v[82:85], v218 offset:11584
	s_nop 0
	s_waitcnt lgkmcnt(5)
	v_pk_mul_f32 v[20:21], v[20:21], v[92:93]
	ds_read_b128 v[86:89], v200
	v_pk_mul_f32 v[18:19], v[18:19], v[90:91]
	s_nop 0
	s_waitcnt lgkmcnt(5)
	v_mfma_f32_16x16x32_bf16 v[18:21], v[70:73], v[134:137], v[18:21]
	ds_read_b128 v[70:73], v218 offset:13824
	s_nop 0
	s_waitcnt lgkmcnt(5)
	v_mfma_f32_16x16x32_bf16 v[18:21], v[74:77], v[130:133], v[18:21]
	ds_read_b128 v[74:77], v218 offset:13888
	s_nop 0
	s_waitcnt lgkmcnt(5)
	v_pk_mul_f32 v[24:25], v[24:25], v[96:97]
	ds_read_b128 v[90:93], v201
	v_pk_mul_f32 v[22:23], v[22:23], v[94:95]
	s_nop 0
	s_waitcnt lgkmcnt(5)
	v_mfma_f32_16x16x32_bf16 v[22:25], v[78:81], v[134:137], v[22:25]
	ds_read_b128 v[78:81], v218 offset:16128
	s_nop 0
	s_waitcnt lgkmcnt(5)
	v_mfma_f32_16x16x32_bf16 v[22:25], v[82:85], v[130:133], v[22:25]
	ds_read_b128 v[82:85], v218 offset:16192
	s_nop 0
	s_waitcnt lgkmcnt(5)
	v_pk_mul_f32 v[28:29], v[28:29], v[88:89]
	ds_read_b128 v[94:97], v202
	v_pk_mul_f32 v[26:27], v[26:27], v[86:87]
	s_nop 0
	s_waitcnt lgkmcnt(5)
	v_mfma_f32_16x16x32_bf16 v[26:29], v[70:73], v[134:137], v[26:29]
	ds_read_b128 v[70:73], v218 offset:18432
	s_nop 0
	s_waitcnt lgkmcnt(5)
	v_mfma_f32_16x16x32_bf16 v[26:29], v[74:77], v[130:133], v[26:29]
	ds_read_b128 v[74:77], v218 offset:18496
	s_nop 0
	s_waitcnt lgkmcnt(5)
	v_pk_mul_f32 v[32:33], v[32:33], v[92:93]
	ds_read_b128 v[86:89], v203
	v_pk_mul_f32 v[30:31], v[30:31], v[90:91]
	s_nop 0
	s_waitcnt lgkmcnt(5)
	v_mfma_f32_16x16x32_bf16 v[30:33], v[78:81], v[134:137], v[30:33]
	ds_read_b128 v[78:81], v218 offset:20736
	s_nop 0
	s_waitcnt lgkmcnt(5)
	v_mfma_f32_16x16x32_bf16 v[30:33], v[82:85], v[130:133], v[30:33]
	ds_read_b128 v[82:85], v218 offset:20800
	s_nop 0
	s_waitcnt lgkmcnt(5)
	v_pk_mul_f32 v[40:41], v[40:41], v[96:97]
	ds_read_b128 v[90:93], v204
	v_pk_mul_f32 v[38:39], v[38:39], v[94:95]
	s_nop 0
	s_waitcnt lgkmcnt(5)
	v_mfma_f32_16x16x32_bf16 v[36:39], v[70:73], v[134:137], v[38:41]
	ds_read_b128 v[70:73], v218 offset:23040
	s_nop 0
	s_waitcnt lgkmcnt(5)
	v_mfma_f32_16x16x32_bf16 v[38:41], v[74:77], v[130:133], v[36:39]
	ds_read_b128 v[74:77], v218 offset:23104
	s_nop 0
	s_waitcnt lgkmcnt(5)
	v_pk_mul_f32 v[44:45], v[44:45], v[88:89]
	ds_read_b128 v[94:97], v205
	v_pk_mul_f32 v[42:43], v[42:43], v[86:87]
	s_nop 0
	s_waitcnt lgkmcnt(5)
	v_mfma_f32_16x16x32_bf16 v[42:45], v[78:81], v[134:137], v[42:45]
	ds_read_b128 v[78:81], v218 offset:25344
	s_nop 0
	s_waitcnt lgkmcnt(5)
	v_mfma_f32_16x16x32_bf16 v[42:45], v[82:85], v[130:133], v[42:45]
	ds_read_b128 v[82:85], v218 offset:25408
	s_nop 0
	s_waitcnt lgkmcnt(5)
	v_pk_mul_f32 v[48:49], v[48:49], v[92:93]
	ds_read_b128 v[86:89], v206
	v_pk_mul_f32 v[46:47], v[46:47], v[90:91]
	s_nop 0
	s_waitcnt lgkmcnt(5)
	v_mfma_f32_16x16x32_bf16 v[46:49], v[70:73], v[134:137], v[46:49]
	ds_read_b128 v[70:73], v218 offset:27648
	s_nop 0
	s_waitcnt lgkmcnt(5)
	v_mfma_f32_16x16x32_bf16 v[46:49], v[74:77], v[130:133], v[46:49]
	ds_read_b128 v[74:77], v218 offset:27712
	s_nop 0
	s_waitcnt lgkmcnt(5)
	v_pk_mul_f32 v[52:53], v[52:53], v[96:97]
	ds_read_b128 v[90:93], v207
	v_pk_mul_f32 v[50:51], v[50:51], v[94:95]
	s_nop 0
	s_waitcnt lgkmcnt(5)
	v_mfma_f32_16x16x32_bf16 v[50:53], v[78:81], v[134:137], v[50:53]
	ds_read_b128 v[78:81], v218 offset:29952
	s_nop 0
	s_waitcnt lgkmcnt(5)
	v_mfma_f32_16x16x32_bf16 v[50:53], v[82:85], v[130:133], v[50:53]
	ds_read_b128 v[82:85], v218 offset:30016
	s_nop 0
	s_waitcnt lgkmcnt(5)
	v_pk_mul_f32 v[56:57], v[56:57], v[88:89]
	ds_read_b128 v[94:97], v208
	v_pk_mul_f32 v[54:55], v[54:55], v[86:87]
	s_nop 0
	s_waitcnt lgkmcnt(5)
	v_mfma_f32_16x16x32_bf16 v[54:57], v[70:73], v[134:137], v[54:57]
	ds_read_b128 v[70:73], v218 offset:32256
	s_nop 0
	s_waitcnt lgkmcnt(5)
	v_mfma_f32_16x16x32_bf16 v[54:57], v[74:77], v[130:133], v[54:57]
	ds_read_b128 v[74:77], v218 offset:32320
	s_nop 0
	s_waitcnt lgkmcnt(5)
	v_pk_mul_f32 v[60:61], v[60:61], v[92:93]
	ds_read_b128 v[86:89], v209
	v_pk_mul_f32 v[58:59], v[58:59], v[90:91]
	s_nop 0
	s_waitcnt lgkmcnt(5)
	v_mfma_f32_16x16x32_bf16 v[58:61], v[78:81], v[134:137], v[58:61]
	s_nop 0
	s_waitcnt lgkmcnt(4)
	v_mfma_f32_16x16x32_bf16 v[58:61], v[82:85], v[130:133], v[58:61]
	s_nop 0
	s_waitcnt lgkmcnt(3)
	v_pk_mul_f32 v[64:65], v[64:65], v[96:97]
	v_pk_mul_f32 v[62:63], v[62:63], v[94:95]
	s_nop 0
	s_waitcnt lgkmcnt(2)
	v_mfma_f32_16x16x32_bf16 v[62:65], v[70:73], v[134:137], v[62:65]
	s_nop 0
	s_waitcnt lgkmcnt(1)
	v_mfma_f32_16x16x32_bf16 v[62:65], v[74:77], v[130:133], v[62:65]
	s_nop 0
	s_waitcnt lgkmcnt(0)
	v_pk_mul_f32 v[68:69], v[68:69], v[88:89]
	v_pk_mul_f32 v[66:67], v[66:67], v[86:87]
	ds_read_b128 v[138:141], v218 offset:34560
	s_waitcnt lgkmcnt(0)
	v_mfma_f32_16x16x32_bf16 v[66:69], v[138:141], v[134:137], v[66:69]
	ds_read_b128 v[134:137], v218 offset:34624
	s_waitcnt lgkmcnt(0)
	s_barrier
	v_mfma_f32_16x16x32_bf16 v[66:69], v[134:137], v[130:133], v[66:69]
	s_and_saveexec_b64 s[24:25], s[26:27]
	s_cbranch_execz .LBB0_694
	ds_read_b128 v[130:133], v220
	ds_read_b128 v[134:137], v220 offset:16
	s_waitcnt lgkmcnt(0)
	v_mov_b32_e32 v36, v130
	v_mov_b32_e32 v37, v134
	v_mov_b32_e32 v134, v131
	v_mov_b32_e32 v130, v132
	v_mov_b32_e32 v131, v136
	v_mov_b32_e32 v136, v133
	v_pk_add_f32 v[36:37], v[36:37], v[134:135]
	v_pk_add_f32 v[130:131], v[130:131], v[136:137]
	s_nop 0
	v_pk_add_f32 v[36:37], v[36:37], v[130:131]
	s_nop 0
	v_add_f32_e32 v1, v36, v37
	v_lshl_add_u64 v[36:37], s[22:23], 0, v[158:159]
	v_lshlrev_b64 v[36:37], 7, v[36:37]
	v_lshl_add_u64 v[36:37], s[16:17], 0, v[36:37]
	global_store_dword v[36:37], v1, off
	s_branch .LBB0_694

.LBB0_823:
	s_waitcnt vmcnt(0) lgkmcnt(0)
	v_add_f32_e32 v1, 0, v91
	v_add_f32_e32 v1, v120, v1
	v_add_f32_e32 v1, v121, v1
	v_add_f32_e32 v1, v122, v1
	v_add_f32_e32 v1, v123, v1
	v_add_f32_e32 v1, v124, v1
	v_add_f32_e32 v1, v125, v1
	v_add_f32_e32 v1, v126, v1
	v_add_f32_e32 v1, v128, v1
	v_add_f32_e32 v1, v131, v1
	v_add_f32_e32 v1, v134, v1
	v_add_f32_e32 v1, v144, v1
	v_add_f32_e32 v1, v147, v1
	v_add_f32_e32 v1, v155, v1
	v_add_f32_e32 v1, v175, v1
	v_add_f32_e32 v1, v176, v1
	v_add_u32_e32 v35, s93, v129
	ds_write_b128 v156, v[42:45]
	ds_write_b128 v156, v[46:49] offset:8704
	ds_write_b128 v157, v[50:53] offset:53248
	ds_write_b128 v157, v[54:57] offset:61952
	ds_write_b32 v35, v1
	v_add_u32_e32 v35, 0, v129
	v_add_u32_e32 v1, 0x13800, v35
	s_waitcnt lgkmcnt(0)
	s_barrier
	ds_read2st64_b32 v[36:37], v1 offset1:2
	ds_read2st64_b32 v[58:59], v1 offset0:4 offset1:6
	s_andn2_b64 vcc, exec, s[12:13]
	s_waitcnt lgkmcnt(1)
	v_add_f32_e32 v60, 0, v36
	v_cndmask_b32_e64 v61, 0, v37, s[40:41]
	v_cndmask_b32_e64 v36, 0, v60, s[38:39]
	s_waitcnt lgkmcnt(0)
	v_cndmask_b32_e64 v1, 0, v58, s[42:43]
	v_add_f32_e32 v36, v36, v61
	v_cndmask_b32_e64 v62, 0, v59, s[44:45]
	v_add_f32_e32 v1, v36, v1
	v_add_f32_e32 v61, v1, v62
	v_mov_b32_e32 v90, v37
	v_pk_add_f32 v[36:37], v[60:61], v[90:91]
	s_nop 0
	v_add_f32_e32 v1, v36, v58
	v_add_f32_e32 v59, v1, v59
	v_sub_f32_e32 v1, v59, v36
	v_mul_f32_e32 v1, 0x3fb8aa3b, v1
	v_exp_f32_e32 v58, v1
	v_add_u32_e32 v1, s96, v130
	ds_read_u16 v184, v1
	s_nop 0
	v_sub_f32_e32 v62, v37, v36
	v_mul_f32_e32 v62, 0x3fb8aa3b, v62
	v_exp_f32_e32 v63, v62
	v_sub_f32_e32 v62, v36, v37
	s_waitcnt lgkmcnt(1)
	s_waitcnt lgkmcnt(0)
	v_lshlrev_b32_e32 v61, 16, v184
	v_add_f32_e32 v64, v120, v37
	v_mul_f32_e32 v61, v63, v61
	v_cvt_pk_bf16_f32 v61, v61, s0
	s_mul_i32 s0, s76, 0x110
	v_add_u32_e32 v37, s0, v130
	ds_read_u16 v184, v37
	ds_read_u16 v188, v37 offset:272
	ds_read_u16 v192, v37 offset:544
	ds_read_u16 v196, v37 offset:816
	ds_read_u16 v200, v37 offset:1088
	ds_read_u16 v204, v37 offset:1360
	ds_write_b16 v1, v61
	s_nop 0
	v_sub_f32_e32 v63, v64, v36
	v_mul_f32_e32 v63, 0x3fb8aa3b, v63
	v_mul_f32_e32 v60, 0x3fb8aa3b, v91
	v_exp_f32_e32 v66, v63
	s_waitcnt lgkmcnt(6)
	v_lshlrev_b32_e32 v65, 16, v184
	ds_read_u16 v184, v37 offset:1632
	v_mul_f32_e32 v61, 0x3fb8aa3b, v120
	v_sub_f32_e32 v63, v36, v64
	v_exp_f32_e32 v60, v60
	v_mul_f32_e32 v62, 0x3fb8aa3b, v62
	v_exp_f32_e32 v61, v61
	v_mul_f32_e32 v63, 0x3fb8aa3b, v63
	v_exp_f32_e32 v62, v62
	v_exp_f32_e32 v63, v63
	v_pk_add_f32 v[60:61], v[60:61], 1.0 op_sel_hi:[1,0] neg_lo:[1,0] neg_hi:[1,0]
	v_mul_f32_e32 v65, v66, v65
	v_cvt_pk_bf16_f32 v65, v65, s0
	v_pk_mul_f32 v[62:63], v[60:61], v[62:63]
	ds_write_b16 v37, v65
	v_cvt_pk_bf16_f32 v60, v62, s0
	ds_write_b16 v1, v60 offset:17408
	v_cvt_pk_bf16_f32 v1, v63, s0
	ds_write_b16 v37, v1 offset:17408
	v_add_f32_e32 v1, v121, v64
	v_pk_mul_f32 v[60:61], v[58:59], v[62:63] op_sel_hi:[0,1]
	s_nop 0
	v_sub_f32_e32 v64, v1, v36
	v_mul_f32_e32 v64, 0x3fb8aa3b, v64
	v_exp_f32_e32 v65, v64
	v_sub_f32_e32 v64, v36, v1
	s_waitcnt lgkmcnt(9)
	v_lshlrev_b32_e32 v63, 16, v188
	ds_read_u16 v188, v37 offset:1904
	v_add_f32_e32 v1, v122, v1
	v_mul_f32_e32 v63, v65, v63
	v_cvt_pk_bf16_f32 v63, v63, s0
	ds_write_b16 v37, v63 offset:272
	s_nop 0
	v_sub_f32_e32 v65, v1, v36
	v_mul_f32_e32 v65, 0x3fb8aa3b, v65
	v_mul_f32_e32 v62, 0x3fb8aa3b, v121
	v_exp_f32_e32 v67, v65
	s_waitcnt lgkmcnt(10)
	v_lshlrev_b32_e32 v66, 16, v192
	ds_read_u16 v192, v37 offset:2176
	v_mul_f32_e32 v63, 0x3fb8aa3b, v122
	v_sub_f32_e32 v65, v36, v1
	v_exp_f32_e32 v62, v62
	v_mul_f32_e32 v64, 0x3fb8aa3b, v64
	v_exp_f32_e32 v63, v63
	v_mul_f32_e32 v65, 0x3fb8aa3b, v65
	v_exp_f32_e32 v64, v64
	v_exp_f32_e32 v65, v65
	v_pk_add_f32 v[62:63], v[62:63], 1.0 op_sel_hi:[1,0] neg_lo:[1,0] neg_hi:[1,0]
	v_mul_f32_e32 v66, v67, v66
	v_cvt_pk_bf16_f32 v66, v66, s0
	v_pk_mul_f32 v[64:65], v[62:63], v[64:65]
	v_add_f32_e32 v1, v123, v1
	v_cvt_pk_bf16_f32 v62, v64, s0
	ds_write_b16 v37, v62 offset:17680
	v_pk_mul_f32 v[62:63], v[58:59], v[64:65] op_sel_hi:[0,1]
	v_cvt_pk_bf16_f32 v64, v65, s0
	ds_write_b16 v37, v66 offset:544
	ds_write_b16 v37, v64 offset:17952
	s_nop 0
	v_sub_f32_e32 v66, v1, v36
	v_mul_f32_e32 v66, 0x3fb8aa3b, v66
	v_exp_f32_e32 v67, v66
	v_sub_f32_e32 v66, v36, v1
	s_waitcnt lgkmcnt(13)
	v_lshlrev_b32_e32 v65, 16, v196
	ds_read_u16 v196, v37 offset:2448
	v_add_f32_e32 v1, v124, v1
	v_mul_f32_e32 v65, v67, v65
	v_cvt_pk_bf16_f32 v65, v65, s0
	ds_write_b16 v37, v65 offset:816
	s_nop 0
	v_sub_f32_e32 v67, v1, v36
	v_mul_f32_e32 v67, 0x3fb8aa3b, v67
	v_mul_f32_e32 v64, 0x3fb8aa3b, v123
	v_exp_f32_e32 v69, v67
	s_waitcnt lgkmcnt(14)
	v_lshlrev_b32_e32 v68, 16, v200
	ds_read_u16 v200, v37 offset:2720
	v_mul_f32_e32 v65, 0x3fb8aa3b, v124
	v_sub_f32_e32 v67, v36, v1
	v_exp_f32_e32 v64, v64
	v_mul_f32_e32 v66, 0x3fb8aa3b, v66
	v_exp_f32_e32 v65, v65
	v_mul_f32_e32 v67, 0x3fb8aa3b, v67
	v_exp_f32_e32 v66, v66
	v_exp_f32_e32 v67, v67
	v_pk_add_f32 v[64:65], v[64:65], 1.0 op_sel_hi:[1,0] neg_lo:[1,0] neg_hi:[1,0]
	v_mul_f32_e32 v68, v69, v68
	v_cvt_pk_bf16_f32 v68, v68, s0
	v_pk_mul_f32 v[66:67], v[64:65], v[66:67]
	v_add_f32_e32 v1, v125, v1
	v_cvt_pk_bf16_f32 v64, v66, s0
	ds_write_b16 v37, v64 offset:18224
	v_pk_mul_f32 v[64:65], v[58:59], v[66:67] op_sel_hi:[0,1]
	v_cvt_pk_bf16_f32 v66, v67, s0
	ds_write_b16 v37, v68 offset:1088
	ds_write_b16 v37, v66 offset:18496
	s_nop 0
	v_sub_f32_e32 v68, v1, v36
	v_mul_f32_e32 v68, 0x3fb8aa3b, v68
	v_exp_f32_e32 v69, v68
	v_sub_f32_e32 v68, v36, v1
	s_waitcnt lgkmcnt(15)
	v_lshlrev_b32_e32 v67, 16, v204
	ds_read_u16 v204, v37 offset:2992
	v_add_f32_e32 v1, v126, v1
	v_mul_f32_e32 v67, v69, v67
	v_cvt_pk_bf16_f32 v67, v67, s0
	ds_write_b16 v37, v67 offset:1360
	s_nop 0
	v_sub_f32_e32 v69, v1, v36
	v_mul_f32_e32 v69, 0x3fb8aa3b, v69
	v_mul_f32_e32 v66, 0x3fb8aa3b, v125
	v_exp_f32_e32 v71, v69
	s_waitcnt lgkmcnt(15)
	v_lshlrev_b32_e32 v70, 16, v184
	ds_read_u16 v184, v37 offset:3264
	v_mul_f32_e32 v67, 0x3fb8aa3b, v126
	v_sub_f32_e32 v69, v36, v1
	v_exp_f32_e32 v66, v66
	v_mul_f32_e32 v68, 0x3fb8aa3b, v68
	v_exp_f32_e32 v67, v67
	v_mul_f32_e32 v69, 0x3fb8aa3b, v69
	v_exp_f32_e32 v68, v68
	v_exp_f32_e32 v69, v69
	v_pk_add_f32 v[66:67], v[66:67], 1.0 op_sel_hi:[1,0] neg_lo:[1,0] neg_hi:[1,0]
	v_mul_f32_e32 v70, v71, v70
	v_cvt_pk_bf16_f32 v70, v70, s0
	v_pk_mul_f32 v[66:67], v[66:67], v[68:69]
	v_cvt_pk_bf16_f32 v60, v60, v61
	v_cvt_pk_bf16_f32 v68, v66, s0
	ds_write_b16 v37, v68 offset:18768
	v_pk_mul_f32 v[68:69], v[58:59], v[66:67] op_sel_hi:[0,1]
	v_cvt_pk_bf16_f32 v66, v67, s0
	v_cvt_pk_bf16_f32 v61, v62, v63
	v_cvt_pk_bf16_f32 v62, v64, v65
	v_cvt_pk_bf16_f32 v63, v68, v69
	ds_write_b16 v37, v70 offset:1632
	ds_write_b16 v37, v66 offset:19040
	ds_write_b128 v158, v[60:63] offset:34816
	v_add_f32_e32 v1, v128, v1
	s_nop 0
	v_sub_f32_e32 v62, v1, v36
	v_mul_f32_e32 v62, 0x3fb8aa3b, v62
	v_exp_f32_e32 v63, v62
	v_sub_f32_e32 v62, v36, v1
	s_waitcnt lgkmcnt(15)
	v_lshlrev_b32_e32 v61, 16, v188
	ds_read_u16 v188, v37 offset:3536
	v_add_f32_e32 v1, v131, v1
	v_mul_f32_e32 v61, v63, v61
	v_cvt_pk_bf16_f32 v61, v61, s0
	ds_write_b16 v37, v61 offset:1904
	s_nop 0
	v_sub_f32_e32 v63, v1, v36
	v_mul_f32_e32 v63, 0x3fb8aa3b, v63
	v_mul_f32_e32 v60, 0x3fb8aa3b, v128
	v_exp_f32_e32 v65, v63
	s_waitcnt lgkmcnt(15)
	v_lshlrev_b32_e32 v64, 16, v192
	ds_read_u16 v192, v37 offset:3808
	v_mul_f32_e32 v61, 0x3fb8aa3b, v131
	v_sub_f32_e32 v63, v36, v1
	v_exp_f32_e32 v60, v60
	v_mul_f32_e32 v62, 0x3fb8aa3b, v62
	v_exp_f32_e32 v61, v61
	v_mul_f32_e32 v63, 0x3fb8aa3b, v63
	v_exp_f32_e32 v62, v62
	v_exp_f32_e32 v63, v63
	v_pk_add_f32 v[60:61], v[60:61], 1.0 op_sel_hi:[1,0] neg_lo:[1,0] neg_hi:[1,0]
	v_mul_f32_e32 v64, v65, v64
	v_cvt_pk_bf16_f32 v64, v64, s0
	v_pk_mul_f32 v[62:63], v[60:61], v[62:63]
	v_add_f32_e32 v1, v134, v1
	v_cvt_pk_bf16_f32 v60, v62, s0
	ds_write_b16 v37, v60 offset:19312
	v_pk_mul_f32 v[60:61], v[58:59], v[62:63] op_sel_hi:[0,1]
	v_cvt_pk_bf16_f32 v62, v63, s0
	ds_write_b16 v37, v64 offset:2176
	ds_write_b16 v37, v62 offset:19584
	s_nop 0
	v_sub_f32_e32 v64, v1, v36
	v_mul_f32_e32 v64, 0x3fb8aa3b, v64
	v_exp_f32_e32 v65, v64
	v_sub_f32_e32 v64, v36, v1
	s_waitcnt lgkmcnt(15)
	v_lshlrev_b32_e32 v63, 16, v196
	v_add_f32_e32 v1, v144, v1
	v_mul_f32_e32 v63, v65, v63
	v_cvt_pk_bf16_f32 v63, v63, s0
	ds_write_b16 v37, v63 offset:2448
	s_nop 0
	v_sub_f32_e32 v65, v1, v36
	v_mul_f32_e32 v65, 0x3fb8aa3b, v65
	v_mul_f32_e32 v62, 0x3fb8aa3b, v134
	v_exp_f32_e32 v67, v65
	s_waitcnt lgkmcnt(15)
	v_lshlrev_b32_e32 v66, 16, v200
	v_mul_f32_e32 v63, 0x3fb8aa3b, v144
	v_sub_f32_e32 v65, v36, v1
	v_exp_f32_e32 v62, v62
	v_mul_f32_e32 v64, 0x3fb8aa3b, v64
	v_exp_f32_e32 v63, v63
	v_mul_f32_e32 v65, 0x3fb8aa3b, v65
	v_exp_f32_e32 v64, v64
	v_exp_f32_e32 v65, v65
	v_pk_add_f32 v[62:63], v[62:63], 1.0 op_sel_hi:[1,0] neg_lo:[1,0] neg_hi:[1,0]
	v_mul_f32_e32 v66, v67, v66
	v_cvt_pk_bf16_f32 v66, v66, s0
	v_pk_mul_f32 v[64:65], v[62:63], v[64:65]
	v_add_f32_e32 v1, v147, v1
	v_cvt_pk_bf16_f32 v62, v64, s0
	ds_write_b16 v37, v62 offset:19856
	v_pk_mul_f32 v[62:63], v[58:59], v[64:65] op_sel_hi:[0,1]
	v_cvt_pk_bf16_f32 v64, v65, s0
	ds_write_b16 v37, v66 offset:2720
	ds_write_b16 v37, v64 offset:20128
	s_nop 0
	v_sub_f32_e32 v66, v1, v36
	v_mul_f32_e32 v66, 0x3fb8aa3b, v66
	v_exp_f32_e32 v67, v66
	v_sub_f32_e32 v66, v36, v1
	s_waitcnt lgkmcnt(15)
	v_lshlrev_b32_e32 v65, 16, v204
	v_add_f32_e32 v1, v155, v1
	v_mul_f32_e32 v65, v67, v65
	v_cvt_pk_bf16_f32 v65, v65, s0
	ds_write_b16 v37, v65 offset:2992
	s_nop 0
	v_sub_f32_e32 v67, v1, v36
	v_mul_f32_e32 v67, 0x3fb8aa3b, v67
	v_mul_f32_e32 v64, 0x3fb8aa3b, v147
	v_exp_f32_e32 v69, v67
	s_waitcnt lgkmcnt(15)
	v_lshlrev_b32_e32 v68, 16, v184
	v_mul_f32_e32 v65, 0x3fb8aa3b, v155
	v_sub_f32_e32 v67, v36, v1
	v_exp_f32_e32 v64, v64
	v_mul_f32_e32 v66, 0x3fb8aa3b, v66
	v_exp_f32_e32 v65, v65
	v_mul_f32_e32 v67, 0x3fb8aa3b, v67
	v_exp_f32_e32 v66, v66
	v_exp_f32_e32 v67, v67
	v_pk_add_f32 v[64:65], v[64:65], 1.0 op_sel_hi:[1,0] neg_lo:[1,0] neg_hi:[1,0]
	v_mul_f32_e32 v68, v69, v68
	v_cvt_pk_bf16_f32 v68, v68, s0
	v_pk_mul_f32 v[66:67], v[64:65], v[66:67]
	v_add_f32_e32 v1, v175, v1
	v_cvt_pk_bf16_f32 v64, v66, s0
	ds_write_b16 v37, v64 offset:20400
	v_pk_mul_f32 v[64:65], v[58:59], v[66:67] op_sel_hi:[0,1]
	v_cvt_pk_bf16_f32 v66, v67, s0
	ds_write_b16 v37, v68 offset:3264
	ds_write_b16 v37, v66 offset:20672
	s_nop 0
	v_sub_f32_e32 v68, v1, v36
	v_mul_f32_e32 v68, 0x3fb8aa3b, v68
	v_exp_f32_e32 v69, v68
	v_sub_f32_e32 v68, v36, v1
	s_waitcnt lgkmcnt(13)
	v_lshlrev_b32_e32 v67, 16, v188
	v_add_f32_e32 v1, v176, v1
	v_mul_f32_e32 v67, v69, v67
	v_cvt_pk_bf16_f32 v67, v67, s0
	ds_write_b16 v37, v67 offset:3536
	s_nop 0
	v_sub_f32_e32 v69, v1, v36
	v_mul_f32_e32 v66, 0x3fb8aa3b, v175
	v_mul_f32_e32 v69, 0x3fb8aa3b, v69
	v_sub_f32_e32 v1, v36, v1
	s_waitcnt lgkmcnt(12)
	v_lshlrev_b32_e32 v70, 16, v192
	v_mul_f32_e32 v67, 0x3fb8aa3b, v176
	v_exp_f32_e32 v66, v66
	v_mul_f32_e32 v68, 0x3fb8aa3b, v68
	v_exp_f32_e32 v67, v67
	v_exp_f32_e32 v71, v69
	v_mul_f32_e32 v1, 0x3fb8aa3b, v1
	v_exp_f32_e32 v68, v68
	v_exp_f32_e32 v69, v1
	v_mul_f32_e32 v1, v71, v70
	v_pk_add_f32 v[66:67], v[66:67], 1.0 op_sel_hi:[1,0] neg_lo:[1,0] neg_hi:[1,0]
	v_cvt_pk_bf16_f32 v1, v1, s0
	v_pk_mul_f32 v[66:67], v[66:67], v[68:69]
	ds_write_b16 v37, v1 offset:3808
	v_cvt_pk_bf16_f32 v1, v66, s0
	v_pk_mul_f32 v[68:69], v[58:59], v[66:67] op_sel_hi:[0,1]
	ds_write_b16 v37, v1 offset:20944
	v_cvt_pk_bf16_f32 v1, v67, s0
	v_cvt_pk_bf16_f32 v60, v60, v61
	v_cvt_pk_bf16_f32 v61, v62, v63
	v_cvt_pk_bf16_f32 v62, v64, v65
	v_cvt_pk_bf16_f32 v63, v68, v69
	ds_write_b16 v37, v1 offset:21216
	ds_write_b128 v158, v[60:63] offset:34832
	s_cbranch_vccnz .LBB0_825
	v_mul_f32_e32 v1, 0x3fb8aa3b, v36
	v_exp_f32_e32 v1, v1
	v_mul_f32_e32 v36, 0x3fb8aa3b, v59
	v_exp_f32_e32 v36, v36
	v_add_u32_e32 v37, 0x14000, v35
	ds_write_b32 v37, v1
	v_add_u32_e32 v1, 0x14200, v35
	ds_write_b32 v1, v36

.Lhg_gdone:
	ds_read_b64_tr_b16 v[62:63], v159 offset:53248
	ds_read_b64_tr_b16 v[64:65], v159 offset:54336
	ds_read_b64_tr_b16 v[58:59], v159 offset:61952
	ds_read_b64_tr_b16 v[60:61], v159 offset:63040
	v_mov_b32_e32 v66, 0
	s_andn2_b64 vcc, exec, s[14:15]
	v_mov_b32_e32 v68, 0
	v_mov_b32_e32 v69, 0
	v_mov_b32_e32 v70, 0
	v_mov_b32_e32 v71, 0
	s_cbranch_vccnz .LBB0_837
	ds_read_b128 v[184:187], v172
	ds_read_b128 v[188:191], v173
	ds_read_b128 v[192:195], v172 offset:64
	ds_read_b128 v[196:199], v173 offset:64
	ds_read_b128 v[200:203], v172 offset:128
	ds_read_b128 v[204:207], v173 offset:128
	s_nop 0
	s_nop 0
	s_waitcnt lgkmcnt(6)
	s_waitcnt lgkmcnt(4)
	v_mfma_f32_16x16x32_bf16 v[68:71], v[184:187], v[188:191], 0
	s_nop 0
	s_nop 0
	s_waitcnt lgkmcnt(2)
	v_mfma_f32_16x16x32_bf16 v[68:71], v[192:195], v[196:199], v[68:71]
	s_nop 0
	s_nop 0
	s_waitcnt lgkmcnt(0)
	v_mfma_f32_16x16x32_bf16 v[68:71], v[200:203], v[204:207], v[68:71]
	ds_read_b128 v[72:75], v172 offset:192
	ds_read_b128 v[76:79], v173 offset:192
	s_waitcnt lgkmcnt(0)
	v_mfma_f32_16x16x32_bf16 v[68:71], v[72:75], v[76:79], v[68:71]
.LBB0_837:
	s_nop 7
	v_cndmask_b32_e64 v1, v68, 0, s[46:47]
	v_cndmask_b32_e64 v35, 0, v69, s[48:49]
	v_cndmask_b32_e64 v1, v1, v68, s[48:49]
	v_cndmask_b32_e64 v37, v70, 0, s[50:51]
	v_cndmask_b32_e64 v67, v71, 0, s[52:53]
	v_cvt_pk_bf16_f32 v36, v1, v35
	v_cvt_pk_bf16_f32 v37, v37, v67
	s_andn2_b64 vcc, exec, s[16:17]
	v_mov_b32_e32 v67, 0
	v_mov_b32_e32 v68, 0
	v_mov_b32_e32 v69, 0
	ds_write_b64 v160, v[36:37]
	s_cbranch_vccnz .LBB0_839
	ds_read_b128 v[184:187], v172 offset:4352
	ds_read_b128 v[188:191], v173
	ds_read_b128 v[192:195], v172 offset:4416
	ds_read_b128 v[196:199], v173 offset:64
	ds_read_b128 v[200:203], v172 offset:4480
	ds_read_b128 v[204:207], v173 offset:128
	s_nop 0
	s_nop 0
	s_waitcnt lgkmcnt(6)
	s_waitcnt lgkmcnt(4)
	v_mfma_f32_16x16x32_bf16 v[66:69], v[184:187], v[188:191], 0
	s_nop 0
	s_nop 0
	s_waitcnt lgkmcnt(2)
	v_mfma_f32_16x16x32_bf16 v[66:69], v[192:195], v[196:199], v[66:69]
	s_nop 0
	s_nop 0
	s_waitcnt lgkmcnt(0)
	v_mfma_f32_16x16x32_bf16 v[66:69], v[200:203], v[204:207], v[66:69]
	ds_read_b128 v[70:73], v172 offset:4544
	ds_read_b128 v[74:77], v173 offset:192
	s_waitcnt lgkmcnt(0)
	v_mfma_f32_16x16x32_bf16 v[66:69], v[70:73], v[74:77], v[66:69]
.LBB0_839:
	s_nop 7
	v_cndmask_b32_e64 v1, v66, 0, s[54:55]
	v_cndmask_b32_e64 v35, v67, 0, s[56:57]
	v_cndmask_b32_e64 v37, v68, 0, s[58:59]
	v_cndmask_b32_e64 v67, v69, 0, s[60:61]
	v_cvt_pk_bf16_f32 v66, v1, v35
	v_cvt_pk_bf16_f32 v67, v37, v67
	ds_write_b64 v161, v[66:67]
	ds_read_b128 v[184:187], v132
	ds_read_b128 v[188:191], v135
	s_nop 0
	s_nop 0
	v_add_u32_e32 v1, 0x1000, v162
	ds_read_b64 v[192:193], v1 offset:256
	ds_read_b64 v[194:195], v1 offset:288
	ds_read_b64 v[196:197], v162
	ds_read_b64 v[198:199], v162 offset:32
	v_add_u32_e32 v35, 0x2000, v162
	ds_read_b64 v[200:201], v35 offset:512
	ds_read_b64 v[202:203], v35 offset:544
	v_add_u32_e32 v37, 0x3000, v162
	ds_read_b64 v[204:205], v37 offset:768
	ds_read_b64 v[206:207], v37 offset:800
	s_waitcnt lgkmcnt(11)
	s_waitcnt lgkmcnt(9)
	v_pk_mul_f32 v[68:69], v[4:5], v[186:187]
	ds_read_b128 v[208:211], v136
	v_pk_mul_f32 v[66:67], v[2:3], v[184:185]
	s_waitcnt lgkmcnt(9)
	v_pk_mul_f32 v[72:73], v[12:13], v[190:191]
	ds_read_b128 v[184:187], v137
	v_cvt_pk_bf16_f32 v66, v66, v67
	v_cvt_pk_bf16_f32 v67, v68, v69
	v_pk_mul_f32 v[68:69], v[10:11], v[188:189]
	s_nop 0
	v_cvt_pk_bf16_f32 v68, v68, v69
	v_cvt_pk_bf16_f32 v69, v72, v73
	s_nop 0
	s_nop 0
	s_nop 0
	s_waitcnt lgkmcnt(6)
	v_mfma_f32_16x16x32_bf16 v[70:73], v[66:69], v[196:199], 0
	s_sub_i32 s5, s8, 64
	s_add_u32 s18, s5, s72
	s_addc_u32 s19, 0, s74
	v_mfma_f32_16x16x32_bf16 v[74:77], v[66:69], v[192:195], 0
	ds_read_b64 v[188:189], v162 offset:64
	ds_read_b64 v[190:191], v162 offset:96
	ds_read_b64 v[192:193], v1 offset:320
	ds_read_b64 v[194:195], v1 offset:352
	v_mov_b32_e32 v36, 0
	v_cmp_gt_i32_e64 s[68:69], s9, v95
	v_or_b32_e32 v116, s18, v95
	s_waitcnt lgkmcnt(8)
	v_mfma_f32_16x16x32_bf16 v[78:81], v[66:69], v[200:203], 0
	ds_read_b64 v[196:197], v35 offset:576
	ds_read_b64 v[198:199], v35 offset:608
	s_waitcnt lgkmcnt(8)
	v_mfma_f32_16x16x32_bf16 v[66:69], v[66:69], v[204:207], 0
	ds_read_b64 v[200:201], v37 offset:832
	ds_read_b64 v[202:203], v37 offset:864
	s_nop 0
	s_nop 0
	s_waitcnt lgkmcnt(9)
	v_pk_mul_f32 v[106:107], v[8:9], v[210:211]
	ds_read_b128 v[204:207], v138
	v_pk_mul_f32 v[104:105], v[6:7], v[208:209]
	s_waitcnt lgkmcnt(9)
	v_pk_mul_f32 v[110:111], v[16:17], v[186:187]
	ds_read_b128 v[208:211], v139
	v_cvt_pk_bf16_f32 v104, v104, v105
	v_cvt_pk_bf16_f32 v105, v106, v107
	v_pk_mul_f32 v[106:107], v[14:15], v[184:185]
	s_nop 0
	v_cvt_pk_bf16_f32 v106, v106, v107
	v_cvt_pk_bf16_f32 v107, v110, v111
	s_nop 0
	s_waitcnt lgkmcnt(8)
	v_mfma_f32_16x16x32_bf16 v[70:73], v[104:107], v[188:191], v[70:73]
	ds_read_b64 v[184:185], v162 offset:128
	ds_read_b64 v[186:187], v162 offset:160
	s_nop 0
	s_waitcnt lgkmcnt(8)
	v_mfma_f32_16x16x32_bf16 v[74:77], v[104:107], v[192:195], v[74:77]
	ds_read_b64 v[188:189], v1 offset:384
	ds_read_b64 v[190:191], v1 offset:416
	s_nop 0
	s_waitcnt lgkmcnt(8)
	v_mfma_f32_16x16x32_bf16 v[78:81], v[104:107], v[196:199], v[78:81]
	ds_read_b64 v[192:193], v35 offset:640
	ds_read_b64 v[194:195], v35 offset:672
	s_nop 0
	s_waitcnt lgkmcnt(8)
	v_mfma_f32_16x16x32_bf16 v[66:69], v[104:107], v[200:203], v[66:69]
	ds_read_b64 v[196:197], v37 offset:896
	ds_read_b64 v[198:199], v37 offset:928
	s_nop 0
	s_nop 0
	s_waitcnt lgkmcnt(9)
	v_pk_mul_f32 v[106:107], v[20:21], v[206:207]
	ds_read_b128 v[200:203], v140
	v_pk_mul_f32 v[104:105], v[18:19], v[204:205]
	s_waitcnt lgkmcnt(9)
	v_pk_mul_f32 v[110:111], v[24:25], v[210:211]
	ds_read_b128 v[204:207], v141
	v_cvt_pk_bf16_f32 v104, v104, v105
	v_cvt_pk_bf16_f32 v105, v106, v107
	v_pk_mul_f32 v[106:107], v[22:23], v[208:209]
	s_nop 0
	v_cvt_pk_bf16_f32 v106, v106, v107
	v_cvt_pk_bf16_f32 v107, v110, v111
	s_nop 0
	s_waitcnt lgkmcnt(8)
	v_mfma_f32_16x16x32_bf16 v[70:73], v[104:107], v[184:187], v[70:73]
	ds_read_b64 v[184:185], v162 offset:192
	ds_read_b64 v[186:187], v162 offset:224
	s_nop 0
	s_waitcnt lgkmcnt(8)
	v_mfma_f32_16x16x32_bf16 v[74:77], v[104:107], v[188:191], v[74:77]
	ds_read_b64 v[188:189], v1 offset:448
	ds_read_b64 v[190:191], v1 offset:480
	s_nop 0
	s_waitcnt lgkmcnt(8)
	v_mfma_f32_16x16x32_bf16 v[78:81], v[104:107], v[192:195], v[78:81]
	ds_read_b64 v[192:193], v35 offset:704
	ds_read_b64 v[194:195], v35 offset:736
	s_nop 0
	s_waitcnt lgkmcnt(8)
	v_mfma_f32_16x16x32_bf16 v[66:69], v[104:107], v[196:199], v[66:69]
	s_nop 0
	s_nop 0
	s_waitcnt lgkmcnt(7)
	v_pk_mul_f32 v[106:107], v[28:29], v[202:203]
	v_pk_mul_f32 v[104:105], v[26:27], v[200:201]
	s_waitcnt lgkmcnt(6)
	v_pk_mul_f32 v[110:111], v[32:33], v[206:207]
	v_cvt_pk_bf16_f32 v104, v104, v105
	v_cvt_pk_bf16_f32 v105, v106, v107
	v_pk_mul_f32 v[106:107], v[30:31], v[204:205]
	s_nop 0
	v_cvt_pk_bf16_f32 v106, v106, v107
	v_cvt_pk_bf16_f32 v107, v110, v111
	s_nop 0
	s_waitcnt lgkmcnt(4)
	v_mfma_f32_16x16x32_bf16 v[108:111], v[104:107], v[184:187], v[70:73]
	s_nop 2
	s_nop 0
	s_waitcnt lgkmcnt(2)
	v_mfma_f32_16x16x32_bf16 v[74:77], v[104:107], v[188:191], v[74:77]
	s_nop 0
	s_waitcnt lgkmcnt(0)
	v_mfma_f32_16x16x32_bf16 v[70:73], v[104:107], v[192:195], v[78:81]
	s_nop 2
	ds_read_b64 v[78:79], v37 offset:960
	ds_read_b64 v[80:81], v37 offset:992
	s_waitcnt lgkmcnt(0)
	v_mfma_f32_16x16x32_bf16 v[66:69], v[104:107], v[78:81], v[66:69]
	s_barrier
	ds_read_b128 v[78:81], v174
	ds_read_b128 v[104:107], v174 offset:64
	s_waitcnt lgkmcnt(0)
	v_mfma_f32_16x16x32_bf16 v[78:81], v[62:65], v[78:81], v[108:111]
	v_mov_b32_e32 v37, 0
	v_mfma_f32_16x16x32_bf16 v[78:81], v[58:61], v[104:107], v[78:81]
	s_and_saveexec_b64 s[20:21], s[68:69]
	s_cbranch_execz .LBB0_841
	v_mov_b32_e32 v117, s19
	v_lshlrev_b64 v[36:37], 12, v[116:117]
	v_lshl_add_u64 v[36:37], v[102:103], 0, v[36:37]
	global_load_dwordx2 v[36:37], v[36:37], off

.LBB0_873:
	ds_read_b128 v[184:187], v133
	ds_read_b128 v[188:191], v163
	ds_read_b128 v[192:195], v163 offset:64
	ds_read_b128 v[196:199], v148
	ds_read_b128 v[200:203], v163 offset:2304
	ds_read_b128 v[204:207], v163 offset:2368
	s_nop 0
	s_waitcnt lgkmcnt(6)
	s_waitcnt lgkmcnt(5)
	v_pk_mul_f32 v[4:5], v[4:5], v[186:187]
	ds_read_b128 v[208:211], v149
	v_pk_mul_f32 v[2:3], v[2:3], v[184:185]
	s_nop 0
	s_waitcnt lgkmcnt(5)
	v_mfma_f32_16x16x32_bf16 v[2:5], v[188:191], v[62:65], v[2:5]
	ds_read_b128 v[184:187], v163 offset:4608
	s_nop 0
	s_waitcnt lgkmcnt(5)
	v_mfma_f32_16x16x32_bf16 v[2:5], v[192:195], v[58:61], v[2:5]
	ds_read_b128 v[188:191], v163 offset:4672
	s_nop 0
	s_waitcnt lgkmcnt(5)
	v_pk_mul_f32 v[12:13], v[12:13], v[198:199]
	ds_read_b128 v[192:195], v150
	v_pk_mul_f32 v[10:11], v[10:11], v[196:197]
	s_nop 0
	s_waitcnt lgkmcnt(5)
	v_mfma_f32_16x16x32_bf16 v[10:13], v[200:203], v[62:65], v[10:13]
	ds_read_b128 v[196:199], v163 offset:6912
	s_nop 0
	s_waitcnt lgkmcnt(5)
	v_mfma_f32_16x16x32_bf16 v[10:13], v[204:207], v[58:61], v[10:13]
	ds_read_b128 v[200:203], v163 offset:6976
	s_nop 0
	s_waitcnt lgkmcnt(5)
	v_pk_mul_f32 v[8:9], v[8:9], v[210:211]
	ds_read_b128 v[204:207], v151
	v_pk_mul_f32 v[6:7], v[6:7], v[208:209]
	s_nop 0
	s_waitcnt lgkmcnt(5)
	v_mfma_f32_16x16x32_bf16 v[6:9], v[184:187], v[62:65], v[6:9]
	ds_read_b128 v[184:187], v163 offset:9216
	s_nop 0
	s_waitcnt lgkmcnt(5)
	v_mfma_f32_16x16x32_bf16 v[6:9], v[188:191], v[58:61], v[6:9]
	ds_read_b128 v[188:191], v163 offset:9280
	s_nop 0
	s_waitcnt lgkmcnt(5)
	v_pk_mul_f32 v[16:17], v[16:17], v[194:195]
	ds_read_b128 v[208:211], v152
	v_pk_mul_f32 v[14:15], v[14:15], v[192:193]
	s_nop 0
	s_waitcnt lgkmcnt(5)
	v_mfma_f32_16x16x32_bf16 v[14:17], v[196:199], v[62:65], v[14:17]
	ds_read_b128 v[192:195], v163 offset:11520
	s_nop 0
	s_waitcnt lgkmcnt(5)
	v_mfma_f32_16x16x32_bf16 v[14:17], v[200:203], v[58:61], v[14:17]
	ds_read_b128 v[196:199], v163 offset:11584
	s_nop 0
	s_waitcnt lgkmcnt(5)
	v_pk_mul_f32 v[20:21], v[20:21], v[206:207]
	ds_read_b128 v[200:203], v153
	v_pk_mul_f32 v[18:19], v[18:19], v[204:205]
	s_nop 0
	s_waitcnt lgkmcnt(5)
	v_mfma_f32_16x16x32_bf16 v[18:21], v[184:187], v[62:65], v[18:21]
	ds_read_b128 v[184:187], v163 offset:13824
	s_nop 0
	s_waitcnt lgkmcnt(5)
	v_mfma_f32_16x16x32_bf16 v[18:21], v[188:191], v[58:61], v[18:21]
	ds_read_b128 v[188:191], v163 offset:13888
	s_nop 0
	s_waitcnt lgkmcnt(5)
	v_pk_mul_f32 v[24:25], v[24:25], v[210:211]
	ds_read_b128 v[204:207], v154
	v_pk_mul_f32 v[22:23], v[22:23], v[208:209]
	s_nop 0
	s_waitcnt lgkmcnt(5)
	v_mfma_f32_16x16x32_bf16 v[22:25], v[192:195], v[62:65], v[22:25]
	s_nop 0
	s_waitcnt lgkmcnt(4)
	v_mfma_f32_16x16x32_bf16 v[22:25], v[196:199], v[58:61], v[22:25]
	s_nop 0
	s_waitcnt lgkmcnt(3)
	v_pk_mul_f32 v[28:29], v[28:29], v[202:203]
	v_pk_mul_f32 v[26:27], v[26:27], v[200:201]
	s_nop 0
	s_waitcnt lgkmcnt(2)
	v_mfma_f32_16x16x32_bf16 v[26:29], v[184:187], v[62:65], v[26:29]
	s_nop 0
	s_waitcnt lgkmcnt(1)
	v_mfma_f32_16x16x32_bf16 v[26:29], v[188:191], v[58:61], v[26:29]
	s_nop 0
	s_waitcnt lgkmcnt(0)
	v_pk_mul_f32 v[32:33], v[32:33], v[206:207]
	v_pk_mul_f32 v[30:31], v[30:31], v[204:205]
	ds_read_b128 v[178:181], v163 offset:16128
	s_waitcnt lgkmcnt(0)
	v_mfma_f32_16x16x32_bf16 v[30:33], v[178:181], v[62:65], v[30:33]
	ds_read_b128 v[62:65], v163 offset:16192
	s_waitcnt lgkmcnt(0)
	s_barrier
	v_mfma_f32_16x16x32_bf16 v[30:33], v[62:65], v[58:61], v[30:33]
	s_and_saveexec_b64 s[20:21], s[68:69]
	s_cbranch_execz .LBB0_875
	v_add_u32_e32 v1, 0, v142
	v_add_u32_e32 v1, 0x14400, v1
	ds_read_b128 v[58:61], v1
	ds_read_b128 v[62:65], v1 offset:16
	s_mov_b32 s0, 0xf800000
	s_waitcnt lgkmcnt(0)
	v_mov_b32_e32 v178, v58
	v_mov_b32_e32 v179, v62
	v_mov_b32_e32 v62, v59
	v_pk_add_f32 v[58:59], v[178:179], v[62:63]
	v_mov_b32_e32 v62, v60
	v_mov_b32_e32 v63, v64
	v_mov_b32_e32 v64, v61
	v_pk_add_f32 v[60:61], v[62:63], v[64:65]
	s_waitcnt vmcnt(0)
	v_lshlrev_b32_e32 v62, 16, v37
	v_pk_add_f32 v[58:59], v[58:59], v[60:61]
	v_and_b32_e32 v63, 0xffff0000, v37
	v_add_f32_e32 v1, v58, v59
	v_fmamk_f32 v1, v1, 0x3c000000, v222
	v_cmp_gt_f32_e32 vcc, s0, v1
	v_mul_f32_e32 v35, 0x4f800000, v1
	s_nop 0
	v_cndmask_b32_e32 v1, v1, v35, vcc
	v_sqrt_f32_e32 v35, v1
	s_nop 0
	v_add_u32_e32 v58, -1, v35
	v_fma_f32 v59, -v58, v35, v1
	v_cmp_ge_f32_e64 s[0:1], 0, v59
	v_add_u32_e32 v59, 1, v35
	s_nop 0
	v_cndmask_b32_e64 v58, v35, v58, s[0:1]
	v_fma_f32 v35, -v59, v35, v1
	v_cmp_lt_f32_e64 s[0:1], 0, v35
	s_nop 1
	v_cndmask_b32_e64 v35, v58, v59, s[0:1]
	v_mul_f32_e32 v58, 0x37800000, v35
	v_cndmask_b32_e32 v35, v35, v58, vcc
	v_cmp_class_f32_e32 vcc, v1, v223
	s_nop 1
	v_cndmask_b32_e32 v1, v35, v1, vcc
	v_div_scale_f32 v35, s[0:1], v1, v1, 1.0
	v_rcp_f32_e32 v58, v35
	s_movk_i32 s0, 0x3000
	v_fma_f32 v59, -v35, v58, 1.0
	v_fmac_f32_e32 v58, v59, v58
	v_div_scale_f32 v59, vcc, 1.0, v1, 1.0
	v_mul_f32_e32 v60, v59, v58
	v_fma_f32 v61, -v35, v60, v59
	v_fmac_f32_e32 v60, v61, v58
	v_fma_f32 v35, -v35, v60, v59
	v_div_fmas_f32 v35, v35, v58, v60
	v_div_fixup_f32 v58, v35, v1, 1.0
	v_pk_mul_f32 v[60:61], v[80:81], v[58:59] op_sel_hi:[1,0]
	v_pk_mul_f32 v[58:59], v[78:79], v[58:59] op_sel_hi:[1,0]
	v_pk_mul_f32 v[60:61], v[40:41], v[60:61]
	v_pk_mul_f32 v[58:59], v[38:39], v[58:59]
	v_pk_mul_f32 v[60:61], v[60:61], v[62:63]
	s_nop 0
	v_cvt_pk_bf16_f32 v37, v60, v61
	v_lshlrev_b32_e32 v60, 16, v36
	v_and_b32_e32 v61, 0xffff0000, v36
	v_pk_mul_f32 v[58:59], v[58:59], v[60:61]
	s_nop 0
	v_cvt_pk_bf16_f32 v36, v58, v59
	v_mad_u64_u32 v[58:59], s[0:1], v116, s0, v[100:101]
	v_mad_i32_i24 v59, s19, v230, v59
	global_store_dwordx2 v[58:59], v[36:37], off

.LBB0_1286:
	ds_read_b128 v[184:187], v144
	ds_read_b128 v[188:191], v144 offset:64
	ds_read_b128 v[192:195], v144 offset:128
	ds_read_b128 v[196:199], v144 offset:192
	ds_read_b32 v200, v128 offset:17408
	ds_read_b32 v204, v129 offset:17408
	ds_read_b32 v208, v130 offset:17408
	ds_read_b32 v212, v131 offset:17408
	s_nop 0
	s_nop 0
	s_lshl_b32 s59, s59, 6
	s_sub_i32 s6, s15, s59
	s_min_i32 s70, s6, 64
	s_waitcnt lgkmcnt(8)
	s_waitcnt lgkmcnt(7)
	v_mfma_f32_16x16x32_bf16 v[40:43], v[184:187], v[2:5], 0
	v_mfma_f32_16x16x32_bf16 v[36:39], v[184:187], v[6:9], 0
	ds_read_b128 v[184:187], v144 offset:4352
	s_waitcnt lgkmcnt(7)
	v_mfma_f32_16x16x32_bf16 v[40:43], v[188:191], v[10:13], v[40:43]
	v_mfma_f32_16x16x32_bf16 v[36:39], v[188:191], v[14:17], v[36:39]
	ds_read_b128 v[188:191], v144 offset:4416
	s_nop 0
	s_waitcnt lgkmcnt(7)
	v_mfma_f32_16x16x32_bf16 v[40:43], v[192:195], v[18:21], v[40:43]
	v_mfma_f32_16x16x32_bf16 v[36:39], v[192:195], v[22:25], v[36:39]
	ds_read_b128 v[192:195], v144 offset:4480
	s_nop 0
	s_waitcnt lgkmcnt(7)
	v_mfma_f32_16x16x32_bf16 v[40:43], v[196:199], v[26:29], v[40:43]
	s_nop 7
	v_add_f32_e32 v1, v52, v40
	v_mul_f32_e32 v1, 0xbfb8aa3b, v1
	v_exp_f32_e32 v1, v1
	v_mfma_f32_16x16x32_bf16 v[36:39], v[196:199], v[30:33], v[36:39]
	ds_read_b128 v[196:199], v144 offset:4544
	v_add_f32_e32 v1, 1.0, v1
	v_rcp_f32_e32 v1, v1
	s_nop 0
	v_mul_f32_e32 v1, v89, v1
	v_mul_f32_e32 v40, 0x3fb8aa3b, v1
	v_exp_f32_e32 v40, v40
	v_add_f32_e32 v174, v1, v1
	v_cmp_nlt_f32_e32 vcc, s33, v174
	s_and_saveexec_b64 s[6:7], vcc
	s_xor_b64 s[6:7], exec, s[6:7]
	v_fma_f32 v173, -v40, v40, 1.0
	s_andn2_saveexec_b64 s[6:7], s[6:7]
	v_fmamk_f32 v1, v174, 0x3d2aaaab, v225
	v_fma_f32 v1, v174, v1, 0.5
	v_fma_f32 v1, v174, v1, 1.0
	v_mul_f32_e64 v173, v1, -v174
	s_or_b64 exec, exec, s[6:7]
	v_add_f32_e32 v1, v53, v36
	v_mul_f32_e32 v1, 0xbfb8aa3b, v1
	v_exp_f32_e32 v1, v1
	v_max_f32_e32 v36, v173, v173
	v_max_f32_e32 v36, 0, v36
	v_sqrt_f32_e32 v36, v36
	v_add_f32_e32 v1, 1.0, v1
	v_rcp_f32_e32 v1, v1
	v_cmp_gt_i32_e32 vcc, s70, v92
	v_mul_f32_e32 v1, v1, v36
	s_nop 0
	s_waitcnt lgkmcnt(7)
	v_mul_f32_e32 v1, v200, v1
	ds_read_b32 v200, v132 offset:17408
	v_cndmask_b32_e32 v36, 1.0, v40, vcc
	v_cndmask_b32_e32 v1, 0, v1, vcc
	ds_write_b32 v128, v36 offset:50176
	v_add_u32_e32 v36, 0x14400, v128
	ds_write_b32 v36, v1
	v_add_f32_e32 v1, v52, v41
	v_mul_f32_e32 v1, 0xbfb8aa3b, v1
	v_exp_f32_e32 v1, v1
	s_nop 0
	v_add_f32_e32 v1, 1.0, v1
	v_rcp_f32_e32 v1, v1
	s_nop 0
	v_mul_f32_e32 v1, v89, v1
	v_mul_f32_e32 v36, 0x3fb8aa3b, v1
	v_exp_f32_e32 v36, v36
	v_add_f32_e32 v41, v1, v1
	v_cmp_nlt_f32_e32 vcc, s33, v41
	s_and_saveexec_b64 s[6:7], vcc
	s_xor_b64 s[6:7], exec, s[6:7]
	v_fma_f32 v40, -v36, v36, 1.0
	s_andn2_saveexec_b64 s[6:7], s[6:7]
	v_fmamk_f32 v1, v41, 0x3d2aaaab, v225
	v_fma_f32 v1, v41, v1, 0.5
	v_fma_f32 v1, v41, v1, 1.0
	v_mul_f32_e64 v40, v1, -v41
	s_or_b64 exec, exec, s[6:7]
	v_add_f32_e32 v1, v53, v37
	v_mul_f32_e32 v1, 0xbfb8aa3b, v1
	v_exp_f32_e32 v1, v1
	v_max_f32_e32 v37, v40, v40
	v_max_f32_e32 v37, 0, v37
	v_sqrt_f32_e32 v37, v37
	v_add_f32_e32 v1, 1.0, v1
	v_rcp_f32_e32 v1, v1
	v_cmp_gt_i32_e32 vcc, s70, v94
	v_mul_f32_e32 v1, v1, v37
	s_nop 0
	v_cndmask_b32_e32 v36, 1.0, v36, vcc
	ds_write_b32 v129, v36 offset:50176
	v_add_u32_e32 v36, 0x14400, v129
	s_waitcnt lgkmcnt(10)
	v_mul_f32_e32 v1, v204, v1
	ds_read_b32 v204, v133 offset:17408
	v_cndmask_b32_e32 v1, 0, v1, vcc
	ds_write_b32 v36, v1
	v_add_f32_e32 v1, v52, v42
	v_mul_f32_e32 v1, 0xbfb8aa3b, v1
	v_exp_f32_e32 v1, v1
	s_nop 0
	v_add_f32_e32 v1, 1.0, v1
	v_rcp_f32_e32 v1, v1
	s_nop 0
	v_mul_f32_e32 v1, v89, v1
	v_mul_f32_e32 v36, 0x3fb8aa3b, v1
	v_exp_f32_e32 v36, v36
	v_add_f32_e32 v40, v1, v1
	v_cmp_nlt_f32_e32 vcc, s33, v40
	s_and_saveexec_b64 s[6:7], vcc
	s_xor_b64 s[6:7], exec, s[6:7]
	v_fma_f32 v37, -v36, v36, 1.0
	s_andn2_saveexec_b64 s[6:7], s[6:7]
	v_fmamk_f32 v1, v40, 0x3d2aaaab, v225
	v_fma_f32 v1, v40, v1, 0.5
	v_fma_f32 v1, v40, v1, 1.0
	v_mul_f32_e64 v37, v1, -v40
	s_or_b64 exec, exec, s[6:7]
	v_add_f32_e32 v1, v53, v38
	v_mul_f32_e32 v1, 0xbfb8aa3b, v1
	v_exp_f32_e32 v1, v1
	v_max_f32_e32 v37, v37, v37
	v_max_f32_e32 v37, 0, v37
	v_sqrt_f32_e32 v37, v37
	v_add_f32_e32 v1, 1.0, v1
	v_rcp_f32_e32 v1, v1
	v_cmp_gt_i32_e32 vcc, s70, v95
	v_mul_f32_e32 v1, v1, v37
	s_nop 0
	v_cndmask_b32_e32 v36, 1.0, v36, vcc
	ds_write_b32 v130, v36 offset:50176
	v_add_u32_e32 v36, 0x14400, v130
	s_waitcnt lgkmcnt(12)
	v_mul_f32_e32 v1, v208, v1
	ds_read_b32 v208, v134 offset:17408
	v_cndmask_b32_e32 v1, 0, v1, vcc
	ds_write_b32 v36, v1
	v_add_f32_e32 v1, v52, v43
	v_mul_f32_e32 v1, 0xbfb8aa3b, v1
	v_exp_f32_e32 v1, v1
	s_nop 0
	v_add_f32_e32 v1, 1.0, v1
	v_rcp_f32_e32 v1, v1
	s_nop 0
	v_mul_f32_e32 v1, v89, v1
	v_mul_f32_e32 v36, 0x3fb8aa3b, v1
	v_exp_f32_e32 v36, v36
	v_add_f32_e32 v38, v1, v1
	v_cmp_nlt_f32_e32 vcc, s33, v38
	s_and_saveexec_b64 s[6:7], vcc
	s_xor_b64 s[6:7], exec, s[6:7]
	v_fma_f32 v37, -v36, v36, 1.0
	s_andn2_saveexec_b64 s[6:7], s[6:7]
	v_fmamk_f32 v1, v38, 0x3d2aaaab, v225
	v_fma_f32 v1, v38, v1, 0.5
	v_fma_f32 v1, v38, v1, 1.0
	v_mul_f32_e64 v37, v1, -v38
	s_or_b64 exec, exec, s[6:7]
	v_add_f32_e32 v1, v53, v39
	v_mul_f32_e32 v1, 0xbfb8aa3b, v1
	v_exp_f32_e32 v1, v1
	v_max_f32_e32 v37, v37, v37
	v_max_f32_e32 v37, 0, v37
	v_sqrt_f32_e32 v37, v37
	v_add_f32_e32 v1, 1.0, v1
	v_rcp_f32_e32 v1, v1
	v_cmp_gt_i32_e32 vcc, s70, v96
	v_mul_f32_e32 v1, v1, v37
	s_nop 0
	v_cndmask_b32_e32 v36, 1.0, v36, vcc
	ds_write_b32 v131, v36 offset:50176
	v_add_u32_e32 v36, 0x14400, v131
	s_waitcnt lgkmcnt(14)
	v_mul_f32_e32 v1, v212, v1
	ds_read_b32 v212, v135 offset:17408
	v_cndmask_b32_e32 v1, 0, v1, vcc
	ds_write_b32 v36, v1
	s_nop 0
	s_nop 0
	s_waitcnt lgkmcnt(15)
	v_mfma_f32_16x16x32_bf16 v[40:43], v[184:187], v[2:5], 0
	v_mfma_f32_16x16x32_bf16 v[36:39], v[184:187], v[6:9], 0
	ds_read_b128 v[184:187], v144 offset:8704
	s_waitcnt lgkmcnt(15)
	v_mfma_f32_16x16x32_bf16 v[40:43], v[188:191], v[10:13], v[40:43]
	v_mfma_f32_16x16x32_bf16 v[36:39], v[188:191], v[14:17], v[36:39]
	ds_read_b128 v[188:191], v144 offset:8768
	s_nop 0
	s_waitcnt lgkmcnt(15)
	v_mfma_f32_16x16x32_bf16 v[40:43], v[192:195], v[18:21], v[40:43]
	v_mfma_f32_16x16x32_bf16 v[36:39], v[192:195], v[22:25], v[36:39]
	ds_read_b128 v[192:195], v144 offset:8832
	s_nop 0
	s_waitcnt lgkmcnt(15)
	v_mfma_f32_16x16x32_bf16 v[40:43], v[196:199], v[26:29], v[40:43]
	s_nop 7
	v_add_f32_e32 v1, v52, v40
	v_mul_f32_e32 v1, 0xbfb8aa3b, v1
	v_exp_f32_e32 v1, v1
	v_mfma_f32_16x16x32_bf16 v[36:39], v[196:199], v[30:33], v[36:39]
	ds_read_b128 v[196:199], v144 offset:8896
	v_add_f32_e32 v1, 1.0, v1
	v_rcp_f32_e32 v1, v1
	s_nop 0
	v_mul_f32_e32 v1, v89, v1
	v_mul_f32_e32 v40, 0x3fb8aa3b, v1
	v_exp_f32_e32 v40, v40
	v_add_f32_e32 v174, v1, v1
	v_cmp_nlt_f32_e32 vcc, s33, v174
	s_and_saveexec_b64 s[6:7], vcc
	s_xor_b64 s[6:7], exec, s[6:7]
	v_fma_f32 v173, -v40, v40, 1.0
	s_andn2_saveexec_b64 s[6:7], s[6:7]
	v_fmamk_f32 v1, v174, 0x3d2aaaab, v225
	v_fma_f32 v1, v174, v1, 0.5
	v_fma_f32 v1, v174, v1, 1.0
	v_mul_f32_e64 v173, v1, -v174
	s_or_b64 exec, exec, s[6:7]
	v_add_f32_e32 v1, v53, v36
	v_mul_f32_e32 v1, 0xbfb8aa3b, v1
	v_exp_f32_e32 v1, v1
	v_max_f32_e32 v36, v173, v173
	v_max_f32_e32 v36, 0, v36
	v_sqrt_f32_e32 v36, v36
	v_add_f32_e32 v1, 1.0, v1
	v_rcp_f32_e32 v1, v1
	v_cmp_gt_i32_e32 vcc, s70, v97
	v_mul_f32_e32 v1, v1, v36
	s_nop 0
	s_waitcnt lgkmcnt(15)
	v_mul_f32_e32 v1, v200, v1
	ds_read_b32 v200, v136 offset:17408
	v_cndmask_b32_e32 v36, 1.0, v40, vcc
	v_cndmask_b32_e32 v1, 0, v1, vcc
	ds_write_b32 v132, v36 offset:50176
	v_add_u32_e32 v36, 0x14400, v132
	ds_write_b32 v36, v1
	v_add_f32_e32 v1, v52, v41
	v_mul_f32_e32 v1, 0xbfb8aa3b, v1
	v_exp_f32_e32 v1, v1
	s_nop 0
	v_add_f32_e32 v1, 1.0, v1
	v_rcp_f32_e32 v1, v1
	s_nop 0
	v_mul_f32_e32 v1, v89, v1
	v_mul_f32_e32 v36, 0x3fb8aa3b, v1
	v_exp_f32_e32 v36, v36
	v_add_f32_e32 v41, v1, v1
	v_cmp_nlt_f32_e32 vcc, s33, v41
	s_and_saveexec_b64 s[6:7], vcc
	s_xor_b64 s[6:7], exec, s[6:7]
	v_fma_f32 v40, -v36, v36, 1.0
	s_andn2_saveexec_b64 s[6:7], s[6:7]
	v_fmamk_f32 v1, v41, 0x3d2aaaab, v225
	v_fma_f32 v1, v41, v1, 0.5
	v_fma_f32 v1, v41, v1, 1.0
	v_mul_f32_e64 v40, v1, -v41
	s_or_b64 exec, exec, s[6:7]
	v_add_f32_e32 v1, v53, v37
	v_mul_f32_e32 v1, 0xbfb8aa3b, v1
	v_exp_f32_e32 v1, v1
	v_max_f32_e32 v37, v40, v40
	v_max_f32_e32 v37, 0, v37
	v_sqrt_f32_e32 v37, v37
	v_add_f32_e32 v1, 1.0, v1
	v_rcp_f32_e32 v1, v1
	v_cmp_gt_i32_e32 vcc, s70, v99
	v_mul_f32_e32 v1, v1, v37
	s_nop 0
	v_cndmask_b32_e32 v36, 1.0, v36, vcc
	ds_write_b32 v133, v36 offset:50176
	v_add_u32_e32 v36, 0x14400, v133
	s_waitcnt lgkmcnt(15)
	v_mul_f32_e32 v1, v204, v1
	ds_read_b32 v204, v137 offset:17408
	v_cndmask_b32_e32 v1, 0, v1, vcc
	ds_write_b32 v36, v1
	v_add_f32_e32 v1, v52, v42
	v_mul_f32_e32 v1, 0xbfb8aa3b, v1
	v_exp_f32_e32 v1, v1
	s_nop 0
	v_add_f32_e32 v1, 1.0, v1
	v_rcp_f32_e32 v1, v1
	s_nop 0
	v_mul_f32_e32 v1, v89, v1
	v_mul_f32_e32 v36, 0x3fb8aa3b, v1
	v_exp_f32_e32 v36, v36
	v_add_f32_e32 v40, v1, v1
	v_cmp_nlt_f32_e32 vcc, s33, v40
	s_and_saveexec_b64 s[6:7], vcc
	s_xor_b64 s[6:7], exec, s[6:7]
	v_fma_f32 v37, -v36, v36, 1.0
	s_andn2_saveexec_b64 s[6:7], s[6:7]
	v_fmamk_f32 v1, v40, 0x3d2aaaab, v225
	v_fma_f32 v1, v40, v1, 0.5
	v_fma_f32 v1, v40, v1, 1.0
	v_mul_f32_e64 v37, v1, -v40
	s_or_b64 exec, exec, s[6:7]
	v_add_f32_e32 v1, v53, v38
	v_mul_f32_e32 v1, 0xbfb8aa3b, v1
	v_exp_f32_e32 v1, v1
	v_max_f32_e32 v37, v37, v37
	v_max_f32_e32 v37, 0, v37
	v_sqrt_f32_e32 v37, v37
	v_add_f32_e32 v1, 1.0, v1
	v_rcp_f32_e32 v1, v1
	v_cmp_gt_i32_e32 vcc, s70, v100
	v_mul_f32_e32 v1, v1, v37
	s_nop 0
	v_cndmask_b32_e32 v36, 1.0, v36, vcc
	ds_write_b32 v134, v36 offset:50176
	v_add_u32_e32 v36, 0x14400, v134
	s_waitcnt lgkmcnt(15)
	v_mul_f32_e32 v1, v208, v1
	ds_read_b32 v208, v138 offset:17408
	v_cndmask_b32_e32 v1, 0, v1, vcc
	ds_write_b32 v36, v1
	v_add_f32_e32 v1, v52, v43
	v_mul_f32_e32 v1, 0xbfb8aa3b, v1
	v_exp_f32_e32 v1, v1
	s_nop 0
	v_add_f32_e32 v1, 1.0, v1
	v_rcp_f32_e32 v1, v1
	s_nop 0
	v_mul_f32_e32 v1, v89, v1
	v_mul_f32_e32 v36, 0x3fb8aa3b, v1
	v_exp_f32_e32 v36, v36
	v_add_f32_e32 v38, v1, v1
	v_cmp_nlt_f32_e32 vcc, s33, v38
	s_and_saveexec_b64 s[6:7], vcc
	s_xor_b64 s[6:7], exec, s[6:7]
	v_fma_f32 v37, -v36, v36, 1.0
	s_andn2_saveexec_b64 s[6:7], s[6:7]
	v_fmamk_f32 v1, v38, 0x3d2aaaab, v225
	v_fma_f32 v1, v38, v1, 0.5
	v_fma_f32 v1, v38, v1, 1.0
	v_mul_f32_e64 v37, v1, -v38
	s_or_b64 exec, exec, s[6:7]
	v_add_f32_e32 v1, v53, v39
	v_mul_f32_e32 v1, 0xbfb8aa3b, v1
	v_exp_f32_e32 v1, v1
	v_max_f32_e32 v37, v37, v37
	v_max_f32_e32 v37, 0, v37
	v_sqrt_f32_e32 v37, v37
	v_add_f32_e32 v1, 1.0, v1
	v_rcp_f32_e32 v1, v1
	v_cmp_gt_i32_e32 vcc, s70, v101
	v_mul_f32_e32 v1, v1, v37
	s_nop 0
	v_cndmask_b32_e32 v36, 1.0, v36, vcc
	ds_write_b32 v135, v36 offset:50176
	v_add_u32_e32 v36, 0x14400, v135
	s_waitcnt lgkmcnt(15)
	v_mul_f32_e32 v1, v212, v1
	ds_read_b32 v212, v139 offset:17408
	v_cndmask_b32_e32 v1, 0, v1, vcc
	ds_write_b32 v36, v1
	s_nop 0
	s_nop 0
	s_waitcnt lgkmcnt(15)
	v_mfma_f32_16x16x32_bf16 v[40:43], v[184:187], v[2:5], 0
	v_mfma_f32_16x16x32_bf16 v[36:39], v[184:187], v[6:9], 0
	ds_read_b128 v[184:187], v144 offset:13056
	s_waitcnt lgkmcnt(15)
	v_mfma_f32_16x16x32_bf16 v[40:43], v[188:191], v[10:13], v[40:43]
	v_mfma_f32_16x16x32_bf16 v[36:39], v[188:191], v[14:17], v[36:39]
	ds_read_b128 v[188:191], v144 offset:13120
	s_nop 0
	s_waitcnt lgkmcnt(15)
	v_mfma_f32_16x16x32_bf16 v[40:43], v[192:195], v[18:21], v[40:43]
	v_mfma_f32_16x16x32_bf16 v[36:39], v[192:195], v[22:25], v[36:39]
	ds_read_b128 v[192:195], v144 offset:13184
	s_nop 0
	s_waitcnt lgkmcnt(15)
	v_mfma_f32_16x16x32_bf16 v[40:43], v[196:199], v[26:29], v[40:43]
	s_nop 7
	v_add_f32_e32 v1, v52, v40
	v_mul_f32_e32 v1, 0xbfb8aa3b, v1
	v_exp_f32_e32 v1, v1
	v_mfma_f32_16x16x32_bf16 v[36:39], v[196:199], v[30:33], v[36:39]
	v_add_f32_e32 v1, 1.0, v1
	v_rcp_f32_e32 v1, v1
	s_nop 0
	v_mul_f32_e32 v1, v89, v1
	v_mul_f32_e32 v40, 0x3fb8aa3b, v1
	v_exp_f32_e32 v40, v40
	v_add_f32_e32 v174, v1, v1
	v_cmp_nlt_f32_e32 vcc, s33, v174
	s_and_saveexec_b64 s[6:7], vcc
	s_xor_b64 s[6:7], exec, s[6:7]
	v_fma_f32 v173, -v40, v40, 1.0
	s_andn2_saveexec_b64 s[6:7], s[6:7]
	v_fmamk_f32 v1, v174, 0x3d2aaaab, v225
	v_fma_f32 v1, v174, v1, 0.5
	v_fma_f32 v1, v174, v1, 1.0
	v_mul_f32_e64 v173, v1, -v174
	s_or_b64 exec, exec, s[6:7]
	v_add_f32_e32 v1, v53, v36
	v_mul_f32_e32 v1, 0xbfb8aa3b, v1
	v_exp_f32_e32 v1, v1
	v_max_f32_e32 v36, v173, v173
	v_max_f32_e32 v36, 0, v36
	v_sqrt_f32_e32 v36, v36
	v_add_f32_e32 v1, 1.0, v1
	v_rcp_f32_e32 v1, v1
	v_cmp_gt_i32_e32 vcc, s70, v102
	v_mul_f32_e32 v1, v1, v36
	s_nop 0
	s_waitcnt lgkmcnt(14)
	v_mul_f32_e32 v1, v200, v1
	v_cndmask_b32_e32 v36, 1.0, v40, vcc
	v_cndmask_b32_e32 v1, 0, v1, vcc
	ds_write_b32 v136, v36 offset:50176
	v_add_u32_e32 v36, 0x14400, v136
	ds_write_b32 v36, v1
	v_add_f32_e32 v1, v52, v41
	v_mul_f32_e32 v1, 0xbfb8aa3b, v1
	v_exp_f32_e32 v1, v1
	s_nop 0
	v_add_f32_e32 v1, 1.0, v1
	v_rcp_f32_e32 v1, v1
	s_nop 0
	v_mul_f32_e32 v1, v89, v1
	v_mul_f32_e32 v36, 0x3fb8aa3b, v1
	v_exp_f32_e32 v36, v36
	v_add_f32_e32 v41, v1, v1
	v_cmp_nlt_f32_e32 vcc, s33, v41
	s_and_saveexec_b64 s[6:7], vcc
	s_xor_b64 s[6:7], exec, s[6:7]
	v_fma_f32 v40, -v36, v36, 1.0
	s_andn2_saveexec_b64 s[6:7], s[6:7]
	v_fmamk_f32 v1, v41, 0x3d2aaaab, v225
	v_fma_f32 v1, v41, v1, 0.5
	v_fma_f32 v1, v41, v1, 1.0
	v_mul_f32_e64 v40, v1, -v41
	s_or_b64 exec, exec, s[6:7]
	v_add_f32_e32 v1, v53, v37
	v_mul_f32_e32 v1, 0xbfb8aa3b, v1
	v_exp_f32_e32 v1, v1
	v_max_f32_e32 v37, v40, v40
	v_max_f32_e32 v37, 0, v37
	v_sqrt_f32_e32 v37, v37
	v_add_f32_e32 v1, 1.0, v1
	v_rcp_f32_e32 v1, v1
	v_cmp_gt_i32_e32 vcc, s70, v103
	v_mul_f32_e32 v1, v1, v37
	s_nop 0
	v_cndmask_b32_e32 v36, 1.0, v36, vcc
	ds_write_b32 v137, v36 offset:50176
	v_add_u32_e32 v36, 0x14400, v137
	s_waitcnt lgkmcnt(13)
	v_mul_f32_e32 v1, v204, v1
	v_cndmask_b32_e32 v1, 0, v1, vcc
	ds_write_b32 v36, v1
	v_add_f32_e32 v1, v52, v42
	v_mul_f32_e32 v1, 0xbfb8aa3b, v1
	v_exp_f32_e32 v1, v1
	s_nop 0
	v_add_f32_e32 v1, 1.0, v1
	v_rcp_f32_e32 v1, v1
	s_nop 0
	v_mul_f32_e32 v1, v89, v1
	v_mul_f32_e32 v36, 0x3fb8aa3b, v1
	v_exp_f32_e32 v36, v36
	v_add_f32_e32 v40, v1, v1
	v_cmp_nlt_f32_e32 vcc, s33, v40
	s_and_saveexec_b64 s[6:7], vcc
	s_xor_b64 s[6:7], exec, s[6:7]
	v_fma_f32 v37, -v36, v36, 1.0
	s_andn2_saveexec_b64 s[6:7], s[6:7]
	v_fmamk_f32 v1, v40, 0x3d2aaaab, v225
	v_fma_f32 v1, v40, v1, 0.5
	v_fma_f32 v1, v40, v1, 1.0
	v_mul_f32_e64 v37, v1, -v40
	s_or_b64 exec, exec, s[6:7]
	v_add_f32_e32 v1, v53, v38
	v_mul_f32_e32 v1, 0xbfb8aa3b, v1
	v_exp_f32_e32 v1, v1
	v_max_f32_e32 v37, v37, v37
	v_max_f32_e32 v37, 0, v37
	v_sqrt_f32_e32 v37, v37
	v_add_f32_e32 v1, 1.0, v1
	v_rcp_f32_e32 v1, v1
	v_cmp_gt_i32_e32 vcc, s70, v104
	v_mul_f32_e32 v1, v1, v37
	s_nop 0
	v_cndmask_b32_e32 v36, 1.0, v36, vcc
	ds_write_b32 v138, v36 offset:50176
	v_add_u32_e32 v36, 0x14400, v138
	s_waitcnt lgkmcnt(12)
	v_mul_f32_e32 v1, v208, v1
	v_cndmask_b32_e32 v1, 0, v1, vcc
	ds_write_b32 v36, v1
	v_add_f32_e32 v1, v52, v43
	v_mul_f32_e32 v1, 0xbfb8aa3b, v1
	v_exp_f32_e32 v1, v1
	s_nop 0
	v_add_f32_e32 v1, 1.0, v1
	v_rcp_f32_e32 v1, v1
	s_nop 0
	v_mul_f32_e32 v1, v89, v1
	v_mul_f32_e32 v36, 0x3fb8aa3b, v1
	v_exp_f32_e32 v36, v36
	v_add_f32_e32 v38, v1, v1
	v_cmp_nlt_f32_e32 vcc, s33, v38
	s_and_saveexec_b64 s[6:7], vcc
	s_xor_b64 s[6:7], exec, s[6:7]
	v_fma_f32 v37, -v36, v36, 1.0
	s_andn2_saveexec_b64 s[6:7], s[6:7]
	v_fmamk_f32 v1, v38, 0x3d2aaaab, v225
	v_fma_f32 v1, v38, v1, 0.5
	v_fma_f32 v1, v38, v1, 1.0
	v_mul_f32_e64 v37, v1, -v38
	s_or_b64 exec, exec, s[6:7]
	v_add_f32_e32 v1, v53, v39
	v_mul_f32_e32 v1, 0xbfb8aa3b, v1
	v_exp_f32_e32 v1, v1
	v_max_f32_e32 v37, v37, v37
	v_max_f32_e32 v37, 0, v37
	v_sqrt_f32_e32 v37, v37
	v_add_f32_e32 v1, 1.0, v1
	v_rcp_f32_e32 v1, v1
	v_cmp_gt_i32_e32 vcc, s70, v105
	v_mul_f32_e32 v1, v1, v37
	s_nop 0
	v_cndmask_b32_e32 v36, 1.0, v36, vcc
	ds_write_b32 v139, v36 offset:50176
	v_add_u32_e32 v36, 0x14400, v139
	s_waitcnt lgkmcnt(11)
	v_mul_f32_e32 v1, v212, v1
	v_cndmask_b32_e32 v1, 0, v1, vcc
	ds_write_b32 v36, v1
	s_nop 0
	s_nop 0
	s_waitcnt lgkmcnt(10)
	v_mfma_f32_16x16x32_bf16 v[40:43], v[184:187], v[2:5], 0
	v_mfma_f32_16x16x32_bf16 v[36:39], v[184:187], v[6:9], 0
	s_waitcnt lgkmcnt(9)
	v_mfma_f32_16x16x32_bf16 v[40:43], v[188:191], v[10:13], v[40:43]
	v_mfma_f32_16x16x32_bf16 v[36:39], v[188:191], v[14:17], v[36:39]
	s_nop 0
	s_waitcnt lgkmcnt(8)
	v_mfma_f32_16x16x32_bf16 v[40:43], v[192:195], v[18:21], v[40:43]
	v_mfma_f32_16x16x32_bf16 v[36:39], v[192:195], v[22:25], v[36:39]
	ds_read_b32 v184, v140 offset:17408
	ds_read_b32 v188, v141 offset:17408
	ds_read_b32 v192, v142 offset:17408
	ds_read_b128 v[174:177], v144 offset:13248
	s_waitcnt lgkmcnt(0)
	v_mfma_f32_16x16x32_bf16 v[40:43], v[174:177], v[26:29], v[40:43]
	s_nop 7
	v_add_f32_e32 v1, v52, v40
	v_mul_f32_e32 v1, 0xbfb8aa3b, v1
	v_exp_f32_e32 v1, v1
	v_mfma_f32_16x16x32_bf16 v[36:39], v[174:177], v[30:33], v[36:39]
	v_add_f32_e32 v1, 1.0, v1
	v_rcp_f32_e32 v1, v1
	s_nop 0
	v_mul_f32_e32 v1, v89, v1
	v_mul_f32_e32 v40, 0x3fb8aa3b, v1
	v_exp_f32_e32 v40, v40
	v_add_f32_e32 v174, v1, v1
	v_cmp_nlt_f32_e32 vcc, s33, v174
	s_and_saveexec_b64 s[6:7], vcc
	s_xor_b64 s[6:7], exec, s[6:7]
	v_fma_f32 v173, -v40, v40, 1.0
	s_andn2_saveexec_b64 s[6:7], s[6:7]
	v_fmamk_f32 v1, v174, 0x3d2aaaab, v225
	v_fma_f32 v1, v174, v1, 0.5
	v_fma_f32 v1, v174, v1, 1.0
	v_mul_f32_e64 v173, v1, -v174
	s_or_b64 exec, exec, s[6:7]
	v_add_f32_e32 v1, v53, v36
	v_mul_f32_e32 v1, 0xbfb8aa3b, v1
	v_exp_f32_e32 v1, v1
	v_max_f32_e32 v36, v173, v173
	v_max_f32_e32 v36, 0, v36
	v_sqrt_f32_e32 v36, v36
	v_add_f32_e32 v1, 1.0, v1
	v_rcp_f32_e32 v1, v1
	v_cmp_gt_i32_e32 vcc, s70, v106
	v_mul_f32_e32 v1, v1, v36
	s_nop 0
	s_nop 0
	v_mul_f32_e32 v1, v184, v1
	v_cndmask_b32_e32 v36, 1.0, v40, vcc
	v_cndmask_b32_e32 v1, 0, v1, vcc
	ds_write_b32 v140, v36 offset:50176
	v_add_u32_e32 v36, 0x14400, v140
	ds_write_b32 v36, v1
	v_add_f32_e32 v1, v52, v41
	v_mul_f32_e32 v1, 0xbfb8aa3b, v1
	v_exp_f32_e32 v1, v1
	s_nop 0
	v_add_f32_e32 v1, 1.0, v1
	v_rcp_f32_e32 v1, v1
	s_nop 0
	v_mul_f32_e32 v1, v89, v1
	v_mul_f32_e32 v36, 0x3fb8aa3b, v1
	v_exp_f32_e32 v36, v36
	v_add_f32_e32 v41, v1, v1
	v_cmp_nlt_f32_e32 vcc, s33, v41
	s_and_saveexec_b64 s[6:7], vcc
	s_xor_b64 s[6:7], exec, s[6:7]
	v_fma_f32 v40, -v36, v36, 1.0
	s_andn2_saveexec_b64 s[6:7], s[6:7]
	v_fmamk_f32 v1, v41, 0x3d2aaaab, v225
	v_fma_f32 v1, v41, v1, 0.5
	v_fma_f32 v1, v41, v1, 1.0
	v_mul_f32_e64 v40, v1, -v41
	s_or_b64 exec, exec, s[6:7]
	v_add_f32_e32 v1, v53, v37
	v_mul_f32_e32 v1, 0xbfb8aa3b, v1
	v_exp_f32_e32 v1, v1
	v_max_f32_e32 v37, v40, v40
	v_max_f32_e32 v37, 0, v37
	v_sqrt_f32_e32 v37, v37
	v_add_f32_e32 v1, 1.0, v1
	v_rcp_f32_e32 v1, v1
	v_cmp_gt_i32_e32 vcc, s70, v107
	v_mul_f32_e32 v1, v1, v37
	s_nop 0
	v_cndmask_b32_e32 v36, 1.0, v36, vcc
	ds_write_b32 v141, v36 offset:50176
	v_add_u32_e32 v36, 0x14400, v141
	s_nop 0
	v_mul_f32_e32 v1, v188, v1
	v_cndmask_b32_e32 v1, 0, v1, vcc
	ds_write_b32 v36, v1
	v_add_f32_e32 v1, v52, v42
	v_mul_f32_e32 v1, 0xbfb8aa3b, v1
	v_exp_f32_e32 v1, v1
	s_nop 0
	v_add_f32_e32 v1, 1.0, v1
	v_rcp_f32_e32 v1, v1
	s_nop 0
	v_mul_f32_e32 v1, v89, v1
	v_mul_f32_e32 v36, 0x3fb8aa3b, v1
	v_exp_f32_e32 v36, v36
	v_add_f32_e32 v40, v1, v1
	v_cmp_nlt_f32_e32 vcc, s33, v40
	s_and_saveexec_b64 s[6:7], vcc
	s_xor_b64 s[6:7], exec, s[6:7]
	v_fma_f32 v37, -v36, v36, 1.0
	s_andn2_saveexec_b64 s[6:7], s[6:7]
	v_fmamk_f32 v1, v40, 0x3d2aaaab, v225
	v_fma_f32 v1, v40, v1, 0.5
	v_fma_f32 v1, v40, v1, 1.0
	v_mul_f32_e64 v37, v1, -v40
	s_or_b64 exec, exec, s[6:7]
	v_add_f32_e32 v1, v53, v38
	v_mul_f32_e32 v1, 0xbfb8aa3b, v1
	v_exp_f32_e32 v1, v1
	v_max_f32_e32 v37, v37, v37
	v_max_f32_e32 v37, 0, v37
	v_sqrt_f32_e32 v37, v37
	v_add_f32_e32 v1, 1.0, v1
	v_rcp_f32_e32 v1, v1
	v_cmp_gt_i32_e32 vcc, s70, v108
	v_mul_f32_e32 v1, v1, v37
	s_nop 0
	v_cndmask_b32_e32 v36, 1.0, v36, vcc
	ds_write_b32 v142, v36 offset:50176
	v_add_u32_e32 v36, 0x14400, v142
	s_nop 0
	v_mul_f32_e32 v1, v192, v1
	v_cndmask_b32_e32 v1, 0, v1, vcc
	ds_write_b32 v36, v1
	v_add_f32_e32 v1, v52, v43
	v_mul_f32_e32 v1, 0xbfb8aa3b, v1
	v_exp_f32_e32 v1, v1
	s_nop 0
	v_add_f32_e32 v1, 1.0, v1
	v_rcp_f32_e32 v1, v1
	s_nop 0
	v_mul_f32_e32 v1, v89, v1
	v_mul_f32_e32 v36, 0x3fb8aa3b, v1
	v_exp_f32_e32 v36, v36
	v_add_f32_e32 v38, v1, v1
	v_cmp_nlt_f32_e32 vcc, s33, v38
	s_and_saveexec_b64 s[6:7], vcc
	s_xor_b64 s[6:7], exec, s[6:7]
	v_fma_f32 v37, -v36, v36, 1.0
	s_andn2_saveexec_b64 s[6:7], s[6:7]
	v_fmamk_f32 v1, v38, 0x3d2aaaab, v225
	v_fma_f32 v1, v38, v1, 0.5
	v_fma_f32 v1, v38, v1, 1.0
	v_mul_f32_e64 v37, v1, -v38
	s_or_b64 exec, exec, s[6:7]
	v_add_f32_e32 v1, v53, v39
	v_mul_f32_e32 v1, 0xbfb8aa3b, v1
	v_exp_f32_e32 v1, v1
	v_max_f32_e32 v37, v37, v37
	v_max_f32_e32 v37, 0, v37
	v_sqrt_f32_e32 v37, v37
	v_add_f32_e32 v1, 1.0, v1
	v_rcp_f32_e32 v1, v1
	v_cmp_gt_i32_e32 vcc, s70, v109
	v_mul_f32_e32 v1, v1, v37
	ds_read_b32 v37, v143 offset:17408
	v_cndmask_b32_e32 v36, 1.0, v36, vcc
	ds_write_b32 v143, v36 offset:50176
	v_add_u32_e32 v36, 0x14400, v143
	s_waitcnt lgkmcnt(1)
	v_mul_f32_e32 v1, v37, v1
	v_cndmask_b32_e32 v1, 0, v1, vcc
	ds_write_b32 v36, v1
	s_waitcnt lgkmcnt(0)
	s_barrier
	s_and_saveexec_b64 s[6:7], s[36:37]
	s_cbranch_execz .LBB0_1353
	s_mov_b32 s43, 0
